# combination: direct-release grid barrier + packed f32 ops of P4/P5 split + 7168 late table rows
# speedup vs baseline: 1.0036x; 1.0014x over previous
; __device__ __forceinline__ void out_unit(const bf16* __restrict__ Qc, const bf16* __restrict__ Kc, const bf16* __restrict__ Vc, const float* __restrict__ ST, int c, ...
;     ...
;         for (int g3 = 0; g3 < 9; g3 += 3) {
;             f32x4 sv[3][2][2]; float wf[3], wb[3];
; #pragma unroll
;             for (int u = 0; u < 3; ++u) { const int cp = g3 + u; const bool fwd = cp < c;
;                 const float wgt = cp == c ? 0.f : (fwd ? __builtin_amdgcn_exp2f((float)(256 * (c - 1 - cp)) * lgf2) : __builtin_amdgcn_exp2f((float)(256 * (cp - c - 1)) * lgb2));
;                 wf[u] = fwd ? wgt : 0.f; wb[u] = fwd ? 0.f : wgt;
;                 const float* S = ST + ((size_t)cp * 2 + (fwd ? 0 : 1)) * 8192;
; #pragma unroll
;                 for (int q = 0; q < 2; ++q) { sv[u][q][0] = *(const f32x4*)(S + (sr + 32 * q) * 128 + sc); sv[u][q][1] = *(const f32x4*)(S + (sr + 32 * q) * 128 + sc + 4); } }
; #pragma unroll
;             for (int u = 0; u < 3; ++u)
; #pragma unroll
;                 for (int q = 0; q < 2; ++q)
; #pragma unroll
;                     for (int j = 0; j < 8; ++j) { const float v = sv[u][q][j >> 2][j & 3]; rf[q][j] += wf[u] * v; rb[q][j] += wb[u] * v; }
;         }
.LBB0_631:
	v_cndmask_b32_e64 v132, 0, v130, s[12:13]
	v_cndmask_b32_e64 v130, v130, 0, s[12:13]
	s_add_i32 s12, s86, 0xfffffe00
	v_cvt_f32_u32_e32 v141, s12
	s_add_i32 s12, s86, 0xffffff00
	v_cvt_f32_u32_e32 v142, s12
	s_waitcnt vmcnt(26)
	v_mov_b32_e32 v151, v30
	v_mul_f32_e32 v141, v129, v141
	v_exp_f32_e32 v141, v141
	v_mul_f32_e32 v142, v129, v142
	v_exp_f32_e32 v142, v142
	v_mov_b32_e32 v30, v29
	v_cndmask_b32_e64 v144, v141, 0, s[64:65]
	v_mov_b32_e32 v150, v28
	s_waitcnt vmcnt(22)
	v_mov_b32_e32 v155, v34
	v_fma_f32 v28, v30, v142, 0
	v_fma_f32 v29, v31, v142, 0
	v_mov_b32_e32 v34, v33
	v_fma_f32 v30, v30, 0, 0
	v_fma_f32 v31, v31, 0, 0
	v_mov_b32_e32 v33, v22
	v_mov_b32_e32 v22, v21
	v_cndmask_b32_e64 v146, 0, v119, s[6:7]
	v_cndmask_b32_e64 v148, v119, 0, s[6:7]
	v_mov_b32_e32 v154, v32
	s_waitcnt vmcnt(18)
	v_mov_b32_e32 v157, v110
	v_fma_f32 v28, v34, v144, v28
	v_fma_f32 v29, v35, v144, v29
	v_mov_b32_e32 v110, v109
	v_fma_f32 v30, v34, 0, v30
	v_fma_f32 v31, v35, 0, v31
	v_mov_b32_e32 v32, v20
	v_mov_b32_e32 v109, v26
	v_fma_f32 v20, v22, v142, 0
	v_fma_f32 v21, v23, v142, 0
	v_mov_b32_e32 v26, v25
	v_fma_f32 v28, v146, v110, v28
	v_fma_f32 v29, v146, v111, v29
	v_fma_f32 v30, v148, v110, v30
	v_fma_f32 v31, v148, v111, v31
	v_mov_b32_e32 v111, v102
	v_fma_f32 v20, v26, v144, v20
	v_fma_f32 v21, v27, v144, v21
	v_mov_b32_e32 v102, v101
	v_mov_b32_e32 v110, v100
	v_fma_f32 v100, v146, v102, v20
	v_fma_f32 v101, v146, v103, v21
	v_fma_f32 v20, v22, 0, 0
	v_fma_f32 v21, v23, 0, 0
	v_mov_b32_e32 v23, v14
	v_mov_b32_e32 v14, v13
	v_fma_f32 v20, v26, 0, v20
	v_fma_f32 v21, v27, 0, v21
	v_mov_b32_e32 v22, v12
	v_mov_b32_e32 v27, v18
	v_fma_f32 v12, v14, v142, 0
	v_fma_f32 v13, v15, v142, 0
	v_mov_b32_e32 v18, v17
	v_fma_f32 v20, v148, v102, v20
	v_fma_f32 v21, v148, v103, v21
	s_waitcnt vmcnt(16)
	v_mov_b32_e32 v103, v98
	v_fma_f32 v12, v18, v144, v12
	v_fma_f32 v13, v19, v144, v13
	v_mov_b32_e32 v98, v97
	v_mov_b32_e32 v156, v108
	v_mov_b32_e32 v108, v24
	v_fma_f32 v24, v22, v142, 0
	v_fma_f32 v25, v23, v142, 0
	v_mov_b32_e32 v26, v16
	v_mov_b32_e32 v102, v96
	v_fma_f32 v96, v146, v98, v12
	v_fma_f32 v97, v146, v99, v13
	v_fma_f32 v12, v14, 0, 0
	v_fma_f32 v13, v15, 0, 0
	v_mov_b32_e32 v15, v6
	v_mov_b32_e32 v6, v5
	v_fma_f32 v34, v32, v142, 0
	v_fma_f32 v35, v33, v142, 0
	v_fma_f32 v32, v32, 0, 0
	v_fma_f32 v33, v33, 0, 0
	v_fma_f32 v24, v26, v144, v24
	v_fma_f32 v25, v27, v144, v25
	v_fma_f32 v12, v18, 0, v12
	v_fma_f32 v13, v19, 0, v13
	v_mov_b32_e32 v14, v4
	v_mov_b32_e32 v19, v10
	v_fma_f32 v4, v6, v142, 0
	v_fma_f32 v5, v7, v142, 0
	v_mov_b32_e32 v10, v9
	v_fma_f32 v34, v108, v144, v34
	v_fma_f32 v35, v109, v144, v35
	v_fma_f32 v32, v108, 0, v32
	v_fma_f32 v33, v109, 0, v33
	v_fma_f32 v108, v146, v102, v24
	v_fma_f32 v109, v146, v103, v25
	v_mov_b32_e32 v25, v86
	v_fma_f32 v4, v10, v144, v4
	v_fma_f32 v5, v11, v144, v5
	v_mov_b32_e32 v86, v85
	s_lshl_b64 s[6:7], s[52:53], 18
	v_mov_b32_e32 v18, v8
	v_fma_f32 v8, v146, v86, v4
	v_fma_f32 v9, v146, v87, v5
	v_fma_f32 v4, v6, 0, 0
	v_fma_f32 v5, v7, 0, 0
	s_add_u32 s6, s3, s6
	v_mov_b32_e32 v24, v84
	v_fma_f32 v4, v10, 0, v4
	v_fma_f32 v5, v11, 0, v5
	v_cndmask_b32_e64 v10, 0, v139, s[8:9]
	v_cndmask_b32_e64 v84, v139, 0, s[8:9]
	s_addc_u32 s7, s19, s7
	s_lshl_b32 s8, s84, 15
	v_fma_f32 v152, v150, v142, 0
	v_fma_f32 v153, v151, v142, 0
	v_fma_f32 v150, v150, 0, 0
	v_fma_f32 v151, v151, 0, 0
	s_add_u32 s6, s6, s8
	v_fma_f32 v152, v154, v144, v152
	v_fma_f32 v153, v155, v144, v153
	v_fma_f32 v150, v154, 0, v150
	v_fma_f32 v151, v155, 0, v151
	v_fma_f32 v16, v14, v142, 0
	v_fma_f32 v17, v15, v142, 0
	v_fma_f32 v14, v14, 0, 0
	v_fma_f32 v15, v15, 0, 0
	s_addc_u32 s7, s7, 0
	v_cndmask_b32_e64 v134, 0, v140, s[10:11]
	v_cndmask_b32_e64 v140, v140, 0, s[10:11]
	v_fma_f32 v152, v146, v156, v152
	v_fma_f32 v153, v146, v157, v153
	v_fma_f32 v150, v148, v156, v150
	v_fma_f32 v151, v148, v157, v151
	v_fma_f32 v22, v22, 0, 0
	v_fma_f32 v23, v23, 0, 0
	v_fma_f32 v16, v18, v144, v16
	v_fma_f32 v17, v19, v144, v17
	v_fma_f32 v14, v18, 0, v14
	v_fma_f32 v15, v19, 0, v15
	v_fma_f32 v4, v148, v86, v4
	v_fma_f32 v5, v148, v87, v5
	s_waitcnt vmcnt(14)
	v_mov_b32_e32 v6, v92
	v_mov_b32_e32 v7, v94
	v_mov_b32_e32 v94, v93
	s_waitcnt vmcnt(13)
	v_mov_b32_e32 v93, v46
	v_mov_b32_e32 v46, v45
	s_and_b64 s[8:9], s[4:5], exec
	v_fma_f32 v22, v26, 0, v22
	v_fma_f32 v23, v27, 0, v23
	v_fma_f32 v12, v148, v98, v12
	v_fma_f32 v13, v148, v99, v13
	v_fma_f32 v98, v146, v24, v16
	v_fma_f32 v99, v146, v25, v17
	v_fma_f32 v14, v148, v24, v14
	v_fma_f32 v15, v148, v25, v15
	v_fma_f32 v16, v140, v6, v150
	v_fma_f32 v17, v140, v7, v151
	v_mov_b32_e32 v25, v54
	v_mov_b32_e32 v54, v53
	s_waitcnt vmcnt(12)
	v_mov_b32_e32 v53, v50
	v_mov_b32_e32 v50, v49
	v_mov_b32_e32 v92, v44
	v_fma_f32 v44, v140, v46, v4
	v_fma_f32 v45, v140, v47, v5
	s_waitcnt vmcnt(10)
	v_mov_b32_e32 v4, v104
	v_mov_b32_e32 v5, v106
	v_fma_f32 v6, v134, v6, v152
	v_fma_f32 v7, v134, v7, v153
	s_mov_b32 s8, 0x70000
	s_mov_b32 s59, 0
	v_fma_f32 v22, v148, v102, v22
	v_fma_f32 v23, v148, v103, v23
	v_fma_f32 v18, v140, v94, v30
	v_fma_f32 v19, v140, v95, v31
	v_mov_b32_e32 v24, v52
	v_mov_b32_e32 v52, v48
	v_fma_f32 v48, v140, v50, v12
	v_fma_f32 v49, v140, v51, v13
	v_fma_f32 v102, v140, v92, v14
	v_fma_f32 v103, v140, v93, v15
	v_mov_b32_e32 v106, v105
	v_fma_f32 v12, v134, v94, v28
	v_fma_f32 v13, v134, v95, v29
	v_fma_f32 v6, v132, v4, v6
	v_fma_f32 v7, v132, v5, v7
	s_waitcnt vmcnt(6)
; __device__ __forceinline__ void out_unit(const bf16* __restrict__ Qc, const bf16* __restrict__ Kc, const bf16* __restrict__ Vc, const float* __restrict__ ST, int c, ...
;     ...
;         for (int g3 = 0; g3 < 9; g3 += 3) {
;             f32x4 sv[3][2][2]; float wf[3], wb[3];
; #pragma unroll
;             for (int u = 0; u < 3; ++u) { const int cp = g3 + u; const bool fwd = cp < c;
;                 const float wgt = cp == c ? 0.f : (fwd ? __builtin_amdgcn_exp2f((float)(256 * (c - 1 - cp)) * lgf2) : __builtin_amdgcn_exp2f((float)(256 * (cp - c - 1)) * lgb2));
;                 wf[u] = fwd ? wgt : 0.f; wb[u] = fwd ? 0.f : wgt;
;                 const float* S = ST + ((size_t)cp * 2 + (fwd ? 0 : 1)) * 8192;
; #pragma unroll
;                 for (int q = 0; q < 2; ++q) { sv[u][q][0] = *(const f32x4*)(S + (sr + 32 * q) * 128 + sc); sv[u][q][1] = *(const f32x4*)(S + (sr + 32 * q) * 128 + sc + 4); } }
; #pragma unroll
;             for (int u = 0; u < 3; ++u)
; #pragma unroll
;                 for (int q = 0; q < 2; ++q)
; #pragma unroll
;                     for (int j = 0; j < 8; ++j) { const float v = sv[u][q][j >> 2][j & 3]; rf[q][j] += wf[u] * v; rb[q][j] += wb[u] * v; }
;         }
	v_mov_b32_e32 v14, v112
	v_mov_b32_e32 v15, v114
	s_cselect_b32 s58, s8, 0x78000
	v_mov_b32_e32 v104, v72
	v_mov_b32_e32 v105, v74
	v_mov_b32_e32 v74, v73
	v_mov_b32_e32 v72, v68
	v_mov_b32_e32 v73, v70
	v_mov_b32_e32 v70, v69
	v_mov_b32_e32 v68, v64
	v_mov_b32_e32 v69, v66
	v_mov_b32_e32 v66, v65
	v_fma_f32 v12, v132, v106, v12
	v_fma_f32 v13, v132, v107, v13
	v_mov_b32_e32 v114, v113
	v_fma_f32 v94, v10, v14, v6
	v_fma_f32 v95, v10, v15, v7
	v_fma_f32 v4, v130, v4, v16
	v_fma_f32 v5, v130, v5, v17
	v_fma_f32 v6, v130, v106, v18
	v_fma_f32 v7, v130, v107, v19
	v_lshl_add_u64 v[64:65], v[124:125], 0, s[58:59]
	s_mov_b64 s[8:9], 0x88000
	v_fma_f32 v34, v146, v110, v34
	v_fma_f32 v35, v146, v111, v35
	v_fma_f32 v32, v148, v110, v32
	v_fma_f32 v33, v148, v111, v33
	v_fma_f32 v110, v10, v114, v12
	v_fma_f32 v111, v10, v115, v13
	v_fma_f32 v106, v84, v14, v4
	v_fma_f32 v107, v84, v15, v5
	v_fma_f32 v112, v84, v114, v6
	v_fma_f32 v113, v84, v115, v7
	v_lshl_add_u64 v[4:5], v[64:65], 0, v[122:123]
	v_lshl_add_u64 v[114:115], v[124:125], 0, s[8:9]
	global_load_dwordx4 v[12:15], v[4:5], off offset:16
	global_load_dwordx4 v[16:19], v[4:5], off
	v_fma_f32 v4, v134, v24, v34
	v_fma_f32 v5, v134, v25, v35
	v_lshl_add_u64 v[6:7], v[114:115], 0, v[122:123]
	v_fma_f32 v30, v140, v24, v32
	v_fma_f32 v31, v140, v25, v33
	v_fma_f32 v32, v140, v54, v20
	v_fma_f32 v33, v140, v55, v21
	v_fma_f32 v86, v140, v52, v22
	v_fma_f32 v87, v140, v53, v23
	global_load_dwordx4 v[20:23], v[6:7], off offset:16
	global_load_dwordx4 v[24:27], v[6:7], off
	v_fma_f32 v4, v132, v104, v4
	v_fma_f32 v5, v132, v105, v5
	v_mov_b32_e32 v28, v88
	v_mov_b32_e32 v29, v90
	v_fma_f32 v6, v134, v54, v100
	v_fma_f32 v7, v134, v55, v101
	v_mov_b32_e32 v90, v89
	v_fma_f32 v88, v10, v28, v4
	v_fma_f32 v89, v10, v29, v5
	v_fma_f32 v4, v130, v104, v30
	v_fma_f32 v5, v130, v105, v31
	v_fma_f32 v6, v132, v74, v6
	v_fma_f32 v7, v132, v75, v7
	v_fma_f32 v104, v84, v28, v4
	v_fma_f32 v105, v84, v29, v5
	v_fma_f32 v4, v134, v52, v108
	v_fma_f32 v5, v134, v53, v109
	v_fma_f32 v100, v10, v90, v6
	v_fma_f32 v101, v10, v91, v7
	v_fma_f32 v6, v130, v74, v32
	v_fma_f32 v7, v130, v75, v33
	v_fma_f32 v4, v132, v72, v4
	v_fma_f32 v5, v132, v73, v5
	s_waitcnt vmcnt(8)
	v_mov_b32_e32 v28, v80
	v_mov_b32_e32 v29, v82
	v_fma_f32 v90, v84, v90, v6
	v_fma_f32 v91, v84, v91, v7
	v_fma_f32 v6, v134, v50, v96
	v_fma_f32 v7, v134, v51, v97
	v_mov_b32_e32 v82, v81
	v_fma_f32 v80, v10, v28, v4
	v_fma_f32 v81, v10, v29, v5
	v_fma_f32 v4, v130, v72, v86
	v_fma_f32 v5, v130, v73, v87
	v_fma_f32 v6, v132, v70, v6
	v_fma_f32 v7, v132, v71, v7
	v_fma_f32 v4, v84, v28, v4
	v_fma_f32 v5, v84, v29, v5
	v_fma_f32 v28, v134, v92, v98
	v_fma_f32 v29, v134, v93, v99
	v_fma_f32 v96, v10, v82, v6
	v_fma_f32 v97, v10, v83, v7
	v_fma_f32 v6, v130, v70, v48
	v_fma_f32 v7, v130, v71, v49
	v_fma_f32 v8, v134, v46, v8
	v_fma_f32 v9, v134, v47, v9
	v_fma_f32 v28, v132, v68, v28
	v_fma_f32 v29, v132, v69, v29
	v_mov_b32_e32 v30, v76
	v_mov_b32_e32 v31, v78
	v_mov_b32_e32 v119, v117
	v_fma_f32 v6, v84, v82, v6
	v_fma_f32 v7, v84, v83, v7
	v_fma_f32 v8, v132, v66, v8
	v_fma_f32 v9, v132, v67, v9
	v_mov_b32_e32 v78, v77
	v_fma_f32 v82, v10, v30, v28
	v_fma_f32 v83, v10, v31, v29
	v_lshl_add_u64 v[28:29], s[50:51], 0, v[118:119]
	v_fma_f32 v86, v10, v78, v8
	v_fma_f32 v87, v10, v79, v9
	v_fma_f32 v8, v130, v68, v102
	v_fma_f32 v9, v130, v69, v103
	v_lshl_add_u64 v[68:69], v[28:29], 0, s[40:41]
	v_lshl_add_u64 v[32:33], v[68:69], 0, v[122:123]
	v_fma_f32 v8, v84, v30, v8
	v_fma_f32 v9, v84, v31, v9
	global_load_dwordx4 v[28:31], v[32:33], off offset:16
	s_nop 0
	global_load_dwordx4 v[32:35], v[32:33], off
	s_sub_i32 s8, 0x700, s86
	v_fma_f32 v10, v130, v66, v44
	v_fma_f32 v11, v130, v67, v45
	v_cvt_f32_u32_e32 v44, s8
	v_lshl_add_u64 v[48:49], v[64:65], 0, v[120:121]
	v_fma_f32 v10, v84, v78, v10
	v_fma_f32 v11, v84, v79, v11
	v_cndmask_b32_e64 v84, 0, v3, s[4:5]
	v_cndmask_b32_e64 v92, v3, 0, s[4:5]
	v_mul_f32_e32 v3, v131, v44
	global_load_dwordx4 v[44:47], v[48:49], off offset:16
	s_nop 0
	global_load_dwordx4 v[48:51], v[48:49], off
	v_lshl_add_u64 v[64:65], v[114:115], 0, v[120:121]
	global_load_dwordx4 v[52:55], v[64:65], off offset:16
	s_nop 0
	global_load_dwordx4 v[64:67], v[64:65], off
	v_lshl_add_u64 v[72:73], v[68:69], 0, v[120:121]
	global_load_dwordx4 v[68:71], v[72:73], off offset:16
	s_nop 0
	global_load_dwordx4 v[72:75], v[72:73], off
	v_exp_f32_e32 v3, v3
	s_cmp_lg_u32 s85, 8
	v_cndmask_b32_e64 v128, 0, v126, s[14:15]
	s_cselect_b64 vcc, -1, 0
	s_sub_i32 s4, 0x800, s86
	s_waitcnt vmcnt(14)
	v_mov_b32_e32 v108, v60
	v_mov_b32_e32 v109, v62
	v_mov_b32_e32 v62, v61
	v_cndmask_b32_e32 v98, 0, v3, vcc
	v_cvt_f32_u32_e32 v3, s4
	v_fma_f32 v76, v128, v108, v94
	v_fma_f32 v77, v128, v109, v95
	v_fma_f32 v60, v128, v62, v110
	v_fma_f32 v61, v128, v63, v111
	v_cndmask_b32_e64 v126, v126, 0, s[14:15]
	v_mul_f32_e32 v3, v131, v3
	v_exp_f32_e32 v102, v3
	s_add_i32 s4, 0, 0x18000
	s_add_i32 s5, 0, 0x1c000
	v_ashrrev_i32_e32 v130, 6, v135
	v_and_b32_e32 v125, 31, v135
	s_waitcnt vmcnt(10)
	v_mov_b32_e32 v95, v18
	v_mov_b32_e32 v18, v17
	v_mov_b32_e32 v94, v16
	v_fma_f32 v16, v84, v18, v60
	v_fma_f32 v17, v84, v19, v61
	v_fma_f32 v76, v84, v94, v76
	v_fma_f32 v77, v84, v95, v77
	v_lshlrev_b32_e32 v119, 5, v130
	s_waitcnt vmcnt(8)
; __device__ __forceinline__ unsigned pk2(float lo, float hi) { return f2bf(lo) | (f2bf(hi) << 16); }
; __device__ __forceinline__ void out_unit(const bf16* __restrict__ Qc, const bf16* __restrict__ Kc, const bf16* __restrict__ Vc, const float* __restrict__ ST, int c, ...
;     ...
;         for (int g3 = 0; g3 < 9; g3 += 3) {
;             f32x4 sv[3][2][2]; float wf[3], wb[3];
; #pragma unroll
;             for (int u = 0; u < 3; ++u) { const int cp = g3 + u; const bool fwd = cp < c;
;                 const float wgt = cp == c ? 0.f : (fwd ? __builtin_amdgcn_exp2f((float)(256 * (c - 1 - cp)) * lgf2) : __builtin_amdgcn_exp2f((float)(256 * (cp - c - 1)) * lgb2));
;                 wf[u] = fwd ? wgt : 0.f; wb[u] = fwd ? 0.f : wgt;
;                 const float* S = ST + ((size_t)cp * 2 + (fwd ? 0 : 1)) * 8192;
; #pragma unroll
;                 for (int q = 0; q < 2; ++q) { sv[u][q][0] = *(const f32x4*)(S + (sr + 32 * q) * 128 + sc); sv[u][q][1] = *(const f32x4*)(S + (sr + 32 * q) * 128 + sc + 4); } }
; #pragma unroll
;             for (int u = 0; u < 3; ++u)
; #pragma unroll
;                 for (int q = 0; q < 2; ++q)
; #pragma unroll
;                     for (int j = 0; j < 8; ++j) { const float v = sv[u][q][j >> 2][j & 3]; rf[q][j] += wf[u] * v; rb[q][j] += wb[u] * v; }
;         }
;         {
;             const float wgt = __builtin_amdgcn_exp2f((float)(256 * (8 - c)) * lgb2);
;             const float* S = ST + 8192;
; #pragma unroll
;             for (int q = 0; q < 2; ++q) { const f32x4 s0 = *(const f32x4*)(S + (sr + 32 * q) * 128 + sc), s1 = *(const f32x4*)(S + (sr + 32 * q) * 128 + sc + 4);
;                 rb[q][0] += wgt * s0.x; rb[q][1] += wgt * s0.y; rb[q][2] += wgt * s0.z; rb[q][3] += wgt * s0.w; rb[q][4] += wgt * s1.x; rb[q][5] += wgt * s1.y; rb[q][6] += wgt * s1.z; rb[q][7] += wgt * s1.w; }
;         }
; #pragma unroll
;         for (int q = 0; q < 2; ++q) {
;             v4u of, ob;
;             of.x = pk2(rf[q][0], rf[q][1]); of.y = pk2(rf[q][2], rf[q][3]); of.z = pk2(rf[q][4], rf[q][5]); of.w = pk2(rf[q][6], rf[q][7]);
;             ob.x = pk2(rb[q][0], rb[q][1]); ob.y = pk2(rb[q][2], rb[q][3]); ob.z = pk2(rb[q][4], rb[q][5]); ob.w = pk2(rb[q][6], rb[q][7]);
;             *(v4u*)(lds + 98304 + (q ? vst1 : vst0)) = of; *(v4u*)(lds + 114688 + (q ? vst1 : vst0)) = ob;
	v_mov_b32_e32 v60, v24
	v_mov_b32_e32 v61, v26
	v_mov_b32_e32 v26, v25
	v_mov_b32_e32 v24, v56
	v_mov_b32_e32 v25, v58
	v_mov_b32_e32 v58, v57
	v_fma_f32 v78, v128, v24, v88
	v_fma_f32 v79, v128, v25, v89
	v_fma_f32 v56, v128, v58, v100
	v_fma_f32 v57, v128, v59, v101
	v_mov_b32_e32 v89, v14
	v_mov_b32_e32 v14, v13
	v_mov_b32_e32 v88, v12
	v_fma_f32 v12, v84, v14, v56
	v_fma_f32 v13, v84, v15, v57
	v_mov_b32_e32 v57, v22
	v_mov_b32_e32 v22, v21
	v_fma_f32 v16, v26, 0, v16
	v_fma_f32 v17, v27, 0, v17
	v_fma_f32 v78, v84, v88, v78
	v_fma_f32 v79, v84, v89, v79
	v_mov_b32_e32 v56, v20
	v_fma_f32 v12, v22, 0, v12
	v_fma_f32 v13, v23, 0, v13
	v_fma_f32 v76, v60, 0, v76
	v_fma_f32 v77, v61, 0, v77
	v_fma_f32 v78, v56, 0, v78
	v_fma_f32 v79, v57, 0, v79
	v_bfe_u32 v3, v13, 16, 1
	v_bfe_u32 v21, v17, 16, 1
	v_bfe_u32 v85, v16, 16, 1
	v_bfe_u32 v20, v12, 16, 1
	v_add3_u32 v16, v16, v85, s81
	v_add3_u32 v17, v17, v21, s81
	v_add3_u32 v3, v13, v3, s81
	v_bfe_u32 v13, v76, 16, 1
	v_bfe_u32 v21, v78, 16, 1
	v_bfe_u32 v85, v79, 16, 1
	v_add3_u32 v12, v12, v20, s81
	v_bfe_u32 v20, v77, 16, 1
	v_add3_u32 v79, v79, v85, s81
	v_add3_u32 v21, v78, v21, s81
	v_add3_u32 v13, v76, v13, s81
	v_add3_u32 v20, v77, v20, s81
	v_lshrrev_b32_e32 v13, 16, v13
	v_lshrrev_b32_e32 v21, 16, v21
	v_lshrrev_b32_e32 v76, 16, v79
	v_lshrrev_b32_e32 v20, 16, v20
	v_and_or_b32 v79, v3, s82, v76
	v_and_or_b32 v78, v12, s82, v21
	v_and_or_b32 v76, v16, s82, v13
	v_fma_f32 v12, v126, v108, v106
	v_fma_f32 v13, v126, v109, v107
	v_and_or_b32 v77, v17, s82, v20
	v_fma_f32 v16, v126, v62, v112
	v_fma_f32 v17, v126, v63, v113
	v_fma_f32 v12, v92, v94, v12
	v_fma_f32 v13, v92, v95, v13
	v_fma_f32 v16, v92, v18, v16
	v_fma_f32 v17, v92, v19, v17
	v_fma_f32 v12, v98, v60, v12
	v_fma_f32 v13, v98, v61, v13
	s_waitcnt vmcnt(6)
	v_mov_b32_e32 v18, v32
	v_mov_b32_e32 v19, v34
	v_fma_f32 v12, v102, v18, v12
	v_fma_f32 v13, v102, v19, v13
	v_fma_f32 v18, v126, v24, v104
	v_fma_f32 v19, v126, v25, v105
	v_fma_f32 v20, v126, v58, v90
	v_fma_f32 v21, v126, v59, v91
	v_fma_f32 v16, v98, v26, v16
	v_fma_f32 v17, v98, v27, v17
	v_mov_b32_e32 v34, v33
	v_fma_f32 v18, v92, v88, v18
	v_fma_f32 v19, v92, v89, v19
	v_fma_f32 v14, v92, v14, v20
	v_fma_f32 v15, v92, v15, v21
	v_fma_f32 v16, v102, v34, v16
	v_fma_f32 v17, v102, v35, v17
	v_fma_f32 v18, v98, v56, v18
	v_fma_f32 v19, v98, v57, v19
	v_fma_f32 v14, v98, v22, v14
	v_fma_f32 v15, v98, v23, v15
	v_mov_b32_e32 v20, v28
	v_mov_b32_e32 v21, v30
	v_mov_b32_e32 v30, v29
	v_fma_f32 v18, v102, v20, v18
	v_fma_f32 v19, v102, v21, v19
	v_fma_f32 v14, v102, v30, v14
	v_fma_f32 v15, v102, v31, v15
	v_bfe_u32 v22, v16, 16, 1
	v_bfe_u32 v3, v15, 16, 1
	v_bfe_u32 v20, v14, 16, 1
	v_bfe_u32 v21, v17, 16, 1
	v_add3_u32 v16, v16, v22, s81
	v_bfe_u32 v22, v19, 16, 1
	v_add3_u32 v17, v17, v21, s81
	v_add3_u32 v14, v14, v20, s81
	v_add3_u32 v3, v15, v3, s81
	v_bfe_u32 v15, v12, 16, 1
	v_bfe_u32 v20, v13, 16, 1
	v_bfe_u32 v21, v18, 16, 1
	v_add3_u32 v19, v19, v22, s81
	v_add3_u32 v18, v18, v21, s81
	v_add3_u32 v13, v13, v20, s81
	v_add3_u32 v12, v12, v15, s81
	v_lshrrev_b32_e32 v15, 16, v19
	v_lshrrev_b32_e32 v12, 16, v12
	v_lshrrev_b32_e32 v13, 16, v13
	v_lshrrev_b32_e32 v18, 16, v18
	v_and_or_b32 v15, v3, s82, v15
	v_add_u32_e32 v3, s4, v138
	v_and_or_b32 v14, v14, s82, v18
	v_and_or_b32 v13, v17, s82, v13
	v_and_or_b32 v12, v16, s82, v12
	ds_write_b128 v3, v[76:79]
	v_add_u32_e32 v3, s5, v138
	v_mov_b32_e32 v17, v42
	v_mov_b32_e32 v42, v41
	v_mov_b32_e32 v23, v38
	v_mov_b32_e32 v38, v37
	ds_write_b128 v3, v[12:15]
	v_mov_b32_e32 v16, v40
	v_fma_f32 v14, v128, v42, v96
	v_fma_f32 v15, v128, v43, v97
	s_waitcnt vmcnt(4)
	v_mov_b32_e32 v19, v50
	v_mov_b32_e32 v50, v49
	v_mov_b32_e32 v22, v36
	v_fma_f32 v26, v128, v38, v86
	v_fma_f32 v27, v128, v39, v87
	v_mov_b32_e32 v29, v46
	v_mov_b32_e32 v46, v45
	v_mov_b32_e32 v18, v48
	v_fma_f32 v14, v84, v50, v14
	v_fma_f32 v15, v84, v51, v15
	s_waitcnt vmcnt(2)
	v_mov_b32_e32 v21, v66
	v_mov_b32_e32 v66, v65
	v_fma_f32 v24, v128, v22, v82
	v_fma_f32 v25, v128, v23, v83
	v_mov_b32_e32 v28, v44
	v_fma_f32 v26, v84, v46, v26
	v_fma_f32 v27, v84, v47, v27
	v_mov_b32_e32 v31, v54
	v_mov_b32_e32 v54, v53
	v_fma_f32 v4, v126, v16, v4
	v_fma_f32 v5, v126, v17, v5
	v_fma_f32 v12, v128, v16, v80
	v_fma_f32 v13, v128, v17, v81
	v_mov_b32_e32 v20, v64
	v_fma_f32 v14, v66, 0, v14
	v_fma_f32 v15, v67, 0, v15
	v_fma_f32 v24, v84, v28, v24
	v_fma_f32 v25, v84, v29, v25
	v_mov_b32_e32 v30, v52
	v_fma_f32 v26, v54, 0, v26
	v_fma_f32 v27, v55, 0, v27
	v_fma_f32 v6, v126, v42, v6
	v_fma_f32 v7, v126, v43, v7
	v_fma_f32 v4, v92, v18, v4
	v_fma_f32 v5, v92, v19, v5
	v_fma_f32 v10, v126, v38, v10
	v_fma_f32 v11, v126, v39, v11
	v_fma_f32 v12, v84, v18, v12
	v_fma_f32 v13, v84, v19, v13
	v_fma_f32 v24, v30, 0, v24
	v_fma_f32 v25, v31, 0, v25
	v_bfe_u32 v32, v26, 16, 1
	v_bfe_u32 v34, v14, 16, 1
	v_fma_f32 v6, v92, v50, v6
	v_fma_f32 v7, v92, v51, v7
	v_fma_f32 v4, v98, v20, v4
	v_fma_f32 v5, v98, v21, v5
	s_waitcnt vmcnt(0)
; __device__ __forceinline__ unsigned pk2(float lo, float hi) { return f2bf(lo) | (f2bf(hi) << 16); }
; __device__ __forceinline__ int v_rd_base(int lane) { return ((lane & 3) << 3) | (((lane >> 2) & 3) << 6) | (((lane >> 4) & 1) << 5) | (((lane >> 5) & 1) << 8); }
; __device__ __forceinline__ void out_unit(const bf16* __restrict__ Qc, const bf16* __restrict__ Kc, const bf16* __restrict__ Vc, const float* __restrict__ ST, int c, ...
;     ...
; #pragma unroll
;         for (int q = 0; q < 2; ++q) {
;             v4u of, ob;
;             of.x = pk2(rf[q][0], rf[q][1]); of.y = pk2(rf[q][2], rf[q][3]); of.z = pk2(rf[q][4], rf[q][5]); of.w = pk2(rf[q][6], rf[q][7]);
;             ob.x = pk2(rb[q][0], rb[q][1]); ob.y = pk2(rb[q][2], rb[q][3]); ob.z = pk2(rb[q][4], rb[q][5]); ob.w = pk2(rb[q][6], rb[q][7]);
;             *(v4u*)(lds + 98304 + (q ? vst1 : vst0)) = of; *(v4u*)(lds + 114688 + (q ? vst1 : vst0)) = ob;
;         }
;     }
;     bf16x8 qr[4];
;     const bf16* Qw = Qc + (long)(wid * 32 + r32) * 64 + hi * 8;
; #pragma unroll
;     for (int d0 = 0; d0 < 4; ++d0) qr[d0] = *reinterpret_cast<const bf16x8*>(Qw + d0 * 16);
;     __syncthreads();
;     const int i = wid * 32 + r32;
;     f32x16 o[4] = {};
;     const int vb0 = (int)(uintptr_t)lds + v_rd_base(lane);
	v_mov_b32_e32 v16, v72
	v_mov_b32_e32 v17, v74
	v_fma_f32 v8, v126, v22, v8
	v_fma_f32 v9, v126, v23, v9
	v_fma_f32 v10, v92, v46, v10
	v_fma_f32 v11, v92, v47, v11
	v_fma_f32 v12, v20, 0, v12
	v_fma_f32 v13, v21, 0, v13
	v_bfe_u32 v33, v15, 16, 1
	v_add3_u32 v34, v14, v34, s81
	v_add3_u32 v14, v26, v32, s81
	v_bfe_u32 v32, v25, 16, 1
	v_fma_f32 v6, v98, v66, v6
	v_fma_f32 v7, v98, v67, v7
	v_fma_f32 v4, v102, v16, v4
	v_fma_f32 v5, v102, v17, v5
	v_mov_b32_e32 v74, v73
	v_fma_f32 v8, v92, v28, v8
	v_fma_f32 v9, v92, v29, v9
	v_fma_f32 v10, v98, v54, v10
	v_fma_f32 v11, v98, v55, v11
	v_mov_b32_e32 v17, v70
	v_mov_b32_e32 v70, v69
	v_bfe_u32 v3, v27, 16, 1
	v_add3_u32 v33, v15, v33, s81
	v_bfe_u32 v15, v12, 16, 1
	v_add3_u32 v25, v25, v32, s81
	v_fma_f32 v6, v102, v74, v6
	v_fma_f32 v7, v102, v75, v7
	v_fma_f32 v8, v98, v30, v8
	v_fma_f32 v9, v98, v31, v9
	v_mov_b32_e32 v16, v68
	v_fma_f32 v10, v102, v70, v10
	v_fma_f32 v11, v102, v71, v11
	v_add3_u32 v3, v27, v3, s81
	v_add3_u32 v12, v12, v15, s81
	v_lshrrev_b32_e32 v15, 16, v25
	v_fma_f32 v8, v102, v16, v8
	v_fma_f32 v9, v102, v17, v9
	v_bfe_u32 v16, v10, 16, 1
	v_bfe_u32 v18, v6, 16, 1
	v_bfe_u32 v26, v13, 16, 1
	v_bfe_u32 v27, v24, 16, 1
	v_and_or_b32 v15, v3, s82, v15
	v_bfe_u32 v3, v11, 16, 1
	v_bfe_u32 v17, v7, 16, 1
	v_add3_u32 v18, v6, v18, s81
	v_add3_u32 v6, v10, v16, s81
	v_bfe_u32 v16, v9, 16, 1
	v_add3_u32 v24, v24, v27, s81
	v_add3_u32 v13, v13, v26, s81
	v_add3_u32 v17, v7, v17, s81
	v_add3_u32 v3, v11, v3, s81
	v_bfe_u32 v7, v4, 16, 1
	v_bfe_u32 v10, v5, 16, 1
	v_bfe_u32 v11, v8, 16, 1
	v_add3_u32 v9, v9, v16, s81
	v_lshrrev_b32_e32 v12, 16, v12
	v_lshrrev_b32_e32 v13, 16, v13
	v_lshrrev_b32_e32 v24, 16, v24
	v_add3_u32 v8, v8, v11, s81
	v_add3_u32 v5, v5, v10, s81
	v_add3_u32 v4, v4, v7, s81
	v_lshrrev_b32_e32 v7, 16, v9
	v_and_or_b32 v14, v14, s82, v24
	v_and_or_b32 v13, v33, s82, v13
	v_and_or_b32 v12, v34, s82, v12
	v_lshrrev_b32_e32 v4, 16, v4
	v_lshrrev_b32_e32 v5, 16, v5
	v_lshrrev_b32_e32 v8, 16, v8
	v_and_or_b32 v7, v3, s82, v7
	v_add_u32_e32 v3, s4, v137
	v_or_b32_e32 v114, v119, v125
	v_and_or_b32 v6, v6, s82, v8
	v_and_or_b32 v5, v17, s82, v5
	v_and_or_b32 v4, v18, s82, v4
	ds_write_b128 v3, v[12:15]
	v_add_u32_e32 v3, s5, v137
	v_ashrrev_i32_e32 v115, 31, v114
	ds_write_b128 v3, v[4:7]
	v_bfe_u32 v120, v135, 5, 1
	v_lshlrev_b64 v[4:5], 7, v[114:115]
	v_lshl_add_u64 v[4:5], s[6:7], 0, v[4:5]
	v_lshlrev_b32_e32 v6, 4, v120
	v_mov_b32_e32 v7, v117
	v_lshl_add_u64 v[4:5], v[4:5], 0, v[6:7]
	global_load_dwordx4 v[110:113], v[4:5], off
	global_load_dwordx4 v[106:109], v[4:5], off offset:32
	global_load_dwordx4 v[102:105], v[4:5], off offset:64
	global_load_dwordx4 v[98:101], v[4:5], off offset:96
	v_and_b32_e32 v124, 63, v135
	s_cmp_lg_u32 0, -1
	v_lshlrev_b32_e32 v3, 3, v124
	v_lshlrev_b32_e32 v4, 1, v135
	s_cselect_b32 s4, 0, 0
	v_and_b32_e32 v115, 24, v3
	v_and_b32_e32 v121, 0xc0, v136
	v_and_b32_e32 v122, 32, v4
	v_and_b32_e32 v123, 0x100, v3
	v_lshlrev_b32_e32 v3, 7, v125
	v_and_b32_e32 v4, 0x70, v133
	v_or_b32_e32 v5, 32, v6
	v_or_b32_e32 v7, 64, v6
	v_or_b32_e32 v8, 0x60, v6
	v_lshlrev_b32_e32 v9, 2, v120
	s_add_i32 s4, s4, 0x8000
	v_sub_u32_e32 v126, v114, v9
	v_add3_u32 v9, v123, s4, v121
	v_bitop3_b32 v8, v8, v3, v4 bitop3:0xde
	v_bitop3_b32 v7, v7, v3, v4 bitop3:0xde
	v_bitop3_b32 v5, v5, v3, v4 bitop3:0xde
	v_bitop3_b32 v3, v6, v3, v4 bitop3:0xde
	v_add3_u32 v128, v9, v122, v115
	v_add_u32_e32 v132, 0, v8
	v_add_u32_e32 v133, 0, v7
	v_add_u32_e32 v134, 0, v5
	v_add_u32_e32 v135, 0, v3
	v_mov_b32_e32 v3, v2
	v_mov_b32_e32 v4, v2
	v_mov_b32_e32 v5, v2
	v_mov_b32_e32 v6, v2
	v_mov_b32_e32 v7, v2
	v_mov_b32_e32 v8, v2
	v_mov_b32_e32 v9, v2
	v_mov_b32_e32 v10, v2
	v_mov_b32_e32 v11, v2
	v_mov_b32_e32 v12, v2
	v_mov_b32_e32 v13, v2
	v_mov_b32_e32 v14, v2
	v_mov_b32_e32 v15, v2
	v_mov_b32_e32 v16, v2
	v_mov_b32_e32 v17, v2
	v_mov_b32_e32 v18, v2
	v_mov_b32_e32 v19, v2
	v_mov_b32_e32 v20, v2
	v_mov_b32_e32 v21, v2
	v_mov_b32_e32 v22, v2
	v_mov_b32_e32 v23, v2
	v_mov_b32_e32 v24, v2
	v_mov_b32_e32 v25, v2
	v_mov_b32_e32 v26, v2
	v_mov_b32_e32 v27, v2
	v_mov_b32_e32 v28, v2
	v_mov_b32_e32 v29, v2
	v_mov_b32_e32 v30, v2
	v_mov_b32_e32 v31, v2
	v_mov_b32_e32 v32, v2
	v_mov_b32_e32 v33, v2
	v_mov_b32_e32 v34, v2
	v_mov_b32_e32 v35, v2
	v_mov_b32_e32 v36, v2
	v_mov_b32_e32 v37, v2
	v_mov_b32_e32 v38, v2
	v_mov_b32_e32 v39, v2
	v_mov_b32_e32 v40, v2
	v_mov_b32_e32 v41, v2
	v_mov_b32_e32 v42, v2
	v_mov_b32_e32 v43, v2
	v_mov_b32_e32 v44, v2
	v_mov_b32_e32 v45, v2
	v_mov_b32_e32 v46, v2
	v_mov_b32_e32 v47, v2
	v_mov_b32_e32 v48, v2
	v_mov_b32_e32 v49, v2
	v_mov_b32_e32 v50, v2
	v_mov_b32_e32 v51, v2
	v_mov_b32_e32 v52, v2
	v_mov_b32_e32 v53, v2
	v_mov_b32_e32 v54, v2
	v_mov_b32_e32 v55, v2
	v_mov_b32_e32 v56, v2
	v_mov_b32_e32 v57, v2
	v_mov_b32_e32 v58, v2
	v_mov_b32_e32 v59, v2
	v_mov_b32_e32 v60, v2
	v_mov_b32_e32 v61, v2
	v_mov_b32_e32 v62, v2
	v_mov_b32_e32 v63, v2
	v_mov_b32_e32 v64, v2
	v_mov_b32_e32 v65, v2
	s_waitcnt lgkmcnt(0)
	s_barrier
; __device__ __forceinline__ void qkt(f32x16& p0, f32x16& p1, const char* Ks, const bf16x8* qr, int r32, int hi) {
;     p0 = f32x16{}; p1 = f32x16{};
; #pragma unroll
;     for (int d0 = 0; d0 < 4; ++d0) { const int cb = (d0 * 16 + hi * 8) * 2;
;         const bf16x8 b0 = *reinterpret_cast<const bf16x8*>(Ks + KSWZ64(r32, cb));
;         const bf16x8 b1 = *reinterpret_cast<const bf16x8*>(Ks + KSWZ64(32 + r32, cb));
;         p0 = __builtin_amdgcn_mfma_f32_32x32x16_bf16(b0, qr[d0], p0, 0, 0, 0);
;         p1 = __builtin_amdgcn_mfma_f32_32x32x16_bf16(b1, qr[d0], p1, 0, 0, 0); }
; __device__ __forceinline__ void out_unit(const bf16* __restrict__ Qc, const bf16* __restrict__ Kc, const bf16* __restrict__ Vc, const float* __restrict__ ST, int c, ...
;     ...
;     for (int t = 0; t < 4; ++t) {
;         f32x16 p0, p1;
;         qkt(p0, p1, lds + t * 8192, qr, r32, hi);
;         const float fi = (float)(i - 64 * t - 4 * hi);
; #pragma unroll
;         for (int r = 0; r < 16; ++r) {
;             const float d0 = fi - (float)((r & 3) + 8 * (r >> 2)), d1 = d0 - 32.f;
;             const float x0 = d0 >= 0.f ? d0 * lgf2 : -d0 * lgb2, x1 = d1 >= 0.f ? d1 * lgf2 : -d1 * lgb2;
;             p0[r] *= __builtin_amdgcn_exp2f(x0); p1[r] *= __builtin_amdgcn_exp2f(x1);
;         }
;         bf16x8 pa0, pa1, pa2, pa3;
;     ...
;         PK4(p0, 0, pa0); PK4(p0, 8, pa1); PK4(p1, 0, pa2); PK4(p1, 8, pa3);
.LBB0_632:
	v_add_u32_e32 v70, s59, v135
	ds_read_b128 v[66:69], v70
	ds_read_b128 v[82:85], v70 offset:4096
	v_add_u32_e32 v140, s59, v134
	ds_read_b128 v[136:139], v140
	ds_read_b128 v[140:143], v140 offset:4096
	v_add_u32_e32 v144, s59, v133
	s_waitcnt vmcnt(3) lgkmcnt(3)
	v_mfma_f32_32x32x16_bf16 v[66:81], v[66:69], v[110:113], 0
	v_add_u32_e32 v148, s59, v132
	v_cvt_f32_i32_e32 v152, v126
	v_cmp_gt_i32_e32 vcc, 0, v126
	v_add_f32_e32 v153, 0xc2000000, v152
	s_waitcnt lgkmcnt(2)
	v_mfma_f32_32x32x16_bf16 v[82:97], v[82:85], v[110:113], 0
	s_waitcnt vmcnt(2) lgkmcnt(1)
	v_mfma_f32_32x32x16_bf16 v[66:81], v[136:139], v[106:109], v[66:81]
	s_waitcnt lgkmcnt(0)
	v_mfma_f32_32x32x16_bf16 v[82:97], v[140:143], v[106:109], v[82:97]
	ds_read_b128 v[136:139], v144
	ds_read_b128 v[140:143], v144 offset:4096
	ds_read_b128 v[144:147], v148
	ds_read_b128 v[148:151], v148 offset:4096
	s_waitcnt vmcnt(1) lgkmcnt(3)
	v_mfma_f32_32x32x16_bf16 v[66:81], v[136:139], v[102:105], v[66:81]
	v_mul_f32_e32 v136, v129, v152
	v_mul_f32_e64 v137, v131, -v152
	v_cndmask_b32_e32 v136, v136, v137, vcc
	v_exp_f32_e32 v136, v136
	v_mul_f32_e32 v137, v129, v153
	v_mul_f32_e64 v138, v131, -v153
	v_cmp_nle_f32_e32 vcc, 0, v153
	s_waitcnt lgkmcnt(2)
	v_mfma_f32_32x32x16_bf16 v[82:97], v[140:143], v[102:105], v[82:97]
	v_cndmask_b32_e32 v137, v137, v138, vcc
	s_waitcnt vmcnt(0) lgkmcnt(1)
	v_mfma_f32_32x32x16_bf16 v[66:81], v[144:147], v[98:101], v[66:81]
	s_waitcnt lgkmcnt(0)
	v_mfma_f32_32x32x16_bf16 v[82:97], v[148:151], v[98:101], v[82:97]
	s_nop 9
	v_mul_f32_e32 v66, v136, v66
	v_exp_f32_e32 v136, v137
	v_add_f32_e32 v137, -1.0, v152
	v_add_f32_e32 v138, 0xc2000000, v137
	v_mul_f32_e32 v139, v129, v137
	v_mul_f32_e64 v144, v131, -v137
	v_cmp_nle_f32_e32 vcc, 0, v137
	v_mul_f32_e64 v140, v131, -v138
	v_mul_f32_e32 v82, v136, v82
	v_cndmask_b32_e32 v137, v139, v144, vcc
	v_mul_f32_e32 v139, v129, v138
	v_cmp_nle_f32_e32 vcc, 0, v138
	v_exp_f32_e32 v137, v137
	v_add_f32_e32 v136, -2.0, v152
	v_cndmask_b32_e32 v138, v139, v140, vcc
	v_exp_f32_e32 v138, v138
	v_mul_f32_e32 v67, v137, v67
	v_add_f32_e32 v137, 0xc2000000, v136
	v_mul_f32_e64 v139, v131, -v136
	v_mul_f32_e32 v83, v138, v83
	v_mul_f32_e32 v138, v129, v136
	v_cmp_nle_f32_e32 vcc, 0, v136
	v_cvt_pk_bf16_f32 v66, v66, v67
	s_nop 1
	v_cndmask_b32_e32 v136, v138, v139, vcc
	v_mul_f32_e32 v138, v129, v137
	v_mul_f32_e64 v139, v131, -v137
	v_cmp_nle_f32_e32 vcc, 0, v137
	v_exp_f32_e32 v136, v136
	s_nop 0
	v_cndmask_b32_e32 v137, v138, v139, vcc
	v_add_f32_e32 v138, 0xc0400000, v152
	v_add_f32_e32 v139, 0xc2000000, v138
	v_mul_f32_e32 v140, v129, v138
	v_mul_f32_e64 v141, v131, -v138
	v_cmp_nle_f32_e32 vcc, 0, v138
	v_exp_f32_e32 v137, v137
	v_mul_f32_e32 v68, v136, v68
	v_cndmask_b32_e32 v138, v140, v141, vcc
	v_mul_f32_e32 v140, v129, v139
	v_mul_f32_e64 v141, v131, -v139
	v_cmp_nle_f32_e32 vcc, 0, v139
	v_exp_f32_e32 v138, v138
	v_add_f32_e32 v136, 0xc1000000, v152
	v_cndmask_b32_e32 v139, v140, v141, vcc
	v_exp_f32_e32 v139, v139
	v_mul_f32_e32 v84, v137, v84
	v_mul_f32_e32 v69, v138, v69
	v_add_f32_e32 v137, 0xc2000000, v136
	v_mul_f32_e32 v85, v139, v85
	v_mul_f32_e32 v138, v129, v136
	v_mul_f32_e64 v139, v131, -v136
	v_cmp_nle_f32_e32 vcc, 0, v136
	v_cvt_pk_bf16_f32 v67, v68, v69
	s_nop 1
	v_cndmask_b32_e32 v136, v138, v139, vcc
	v_mul_f32_e32 v138, v129, v137
	v_mul_f32_e64 v139, v131, -v137
	v_cmp_nle_f32_e32 vcc, 0, v137
	v_exp_f32_e32 v136, v136
	s_nop 0
	v_cndmask_b32_e32 v137, v138, v139, vcc
	v_add_f32_e32 v138, 0xc1100000, v152
	v_add_f32_e32 v139, 0xc2000000, v138
	v_mul_f32_e32 v140, v129, v138
	v_mul_f32_e64 v141, v131, -v138
	v_cmp_nle_f32_e32 vcc, 0, v138
	v_exp_f32_e32 v137, v137
	v_mul_f32_e32 v70, v136, v70
	v_cndmask_b32_e32 v138, v140, v141, vcc
	v_mul_f32_e32 v140, v129, v139
	v_mul_f32_e64 v141, v131, -v139
	v_cmp_nle_f32_e32 vcc, 0, v139
	v_exp_f32_e32 v138, v138
	v_add_f32_e32 v136, 0xc1200000, v152
	v_cndmask_b32_e32 v139, v140, v141, vcc
	v_exp_f32_e32 v139, v139
	v_mul_f32_e32 v86, v137, v86
	v_mul_f32_e32 v71, v138, v71
	v_add_f32_e32 v137, 0xc2000000, v136
	v_mul_f32_e32 v87, v139, v87
	v_mul_f32_e32 v138, v129, v136
	v_mul_f32_e64 v139, v131, -v136
	v_cmp_nle_f32_e32 vcc, 0, v136
	v_cvt_pk_bf16_f32 v68, v70, v71
	s_nop 0
	v_permlane32_swap_b32_e32 v66, v68
	v_cndmask_b32_e32 v136, v138, v139, vcc
	v_mul_f32_e32 v138, v129, v137
	v_mul_f32_e64 v139, v131, -v137
	v_cmp_nle_f32_e32 vcc, 0, v137
	v_exp_f32_e32 v136, v136
	s_nop 0
	v_cndmask_b32_e32 v137, v138, v139, vcc
	v_add_f32_e32 v138, 0xc1300000, v152
	v_add_f32_e32 v139, 0xc2000000, v138
	v_mul_f32_e32 v140, v129, v138
	v_mul_f32_e64 v141, v131, -v138
	v_cmp_nle_f32_e32 vcc, 0, v138
	v_exp_f32_e32 v137, v137
	v_mul_f32_e32 v72, v136, v72
	v_cndmask_b32_e32 v138, v140, v141, vcc
	v_mul_f32_e32 v140, v129, v139
	v_mul_f32_e64 v141, v131, -v139
	v_cmp_nle_f32_e32 vcc, 0, v139
	v_exp_f32_e32 v138, v138
	v_add_f32_e32 v136, 0xc1800000, v152
	v_cndmask_b32_e32 v139, v140, v141, vcc
	v_exp_f32_e32 v139, v139
	v_mul_f32_e32 v88, v137, v88
	v_mul_f32_e32 v73, v138, v73
	v_add_f32_e32 v137, 0xc2000000, v136
	v_mul_f32_e32 v89, v139, v89
	v_mul_f32_e32 v138, v129, v136
	v_mul_f32_e64 v139, v131, -v136
	v_cmp_nle_f32_e32 vcc, 0, v136
	v_cvt_pk_bf16_f32 v69, v72, v73
	s_nop 0
	v_permlane32_swap_b32_e32 v67, v69
	v_cndmask_b32_e32 v136, v138, v139, vcc
	v_mul_f32_e32 v138, v129, v137
	v_mul_f32_e64 v139, v131, -v137
	v_cmp_nle_f32_e32 vcc, 0, v137
	v_exp_f32_e32 v136, v136
	s_nop 0
	v_cndmask_b32_e32 v137, v138, v139, vcc
	v_add_f32_e32 v138, 0xc1880000, v152
	v_add_f32_e32 v139, 0xc2000000, v138
	v_mul_f32_e32 v140, v129, v138
; #define SBAR() __builtin_amdgcn_sched_barrier(0)
; template <int D0> __device__ __forceinline__ void pv_one(f32x16& od, int vb, bf16x8 pa0, bf16x8 pa1, bf16x8 pa2, bf16x8 pa3) {
;     const s16x4 l0 = tr_read<v_rd_off(D0, 0, 0)>(vb), h0 = tr_read<v_rd_off(D0, 0, 1)>(vb), l1 = tr_read<v_rd_off(D0, 1, 0)>(vb), h1 = tr_read<v_rd_off(D0, 1, 1)>(vb);
;     const s16x4 l2 = tr_read<v_rd_off(D0, 2, 0)>(vb), h2 = tr_read<v_rd_off(D0, 2, 1)>(vb), l3 = tr_read<v_rd_off(D0, 3, 0)>(vb), h3 = tr_read<v_rd_off(D0, 3, 1)>(vb);
;     asm volatile("s_waitcnt lgkmcnt(0)" ::: "memory"); SBAR();
;     ...
;     od = __builtin_amdgcn_mfma_f32_32x32x16_bf16(pa0, PK(l0, h0), od, 0, 0, 0);
;     od = __builtin_amdgcn_mfma_f32_32x32x16_bf16(pa1, PK(l1, h1), od, 0, 0, 0);
;     od = __builtin_amdgcn_mfma_f32_32x32x16_bf16(pa2, PK(l2, h2), od, 0, 0, 0);
;     od = __builtin_amdgcn_mfma_f32_32x32x16_bf16(pa3, PK(l3, h3), od, 0, 0, 0);
;     ...
; }
; template <int KS> __device__ __forceinline__ void pv_ks(f32x16* o, int vb, bf16x8 pa) {
;     const s16x4 l0 = tr_read<v_rd_off(0, KS, 0)>(vb), h0 = tr_read<v_rd_off(0, KS, 1)>(vb), l1 = tr_read<v_rd_off(1, KS, 0)>(vb), h1 = tr_read<v_rd_off(1, KS, 1)>(vb);
;     const s16x4 l2 = tr_read<v_rd_off(2, KS, 0)>(vb), h2 = tr_read<v_rd_off(2, KS, 1)>(vb), l3 = tr_read<v_rd_off(3, KS, 0)>(vb), h3 = tr_read<v_rd_off(3, KS, 1)>(vb);
;     asm volatile("s_waitcnt lgkmcnt(0)" ::: "memory"); SBAR();
;     ...
;     o[0] = __builtin_amdgcn_mfma_f32_32x32x16_bf16(pa, PK(l0, h0), o[0], 0, 0, 0);
;     o[1] = __builtin_amdgcn_mfma_f32_32x32x16_bf16(pa, PK(l1, h1), o[1], 0, 0, 0);
;     o[2] = __builtin_amdgcn_mfma_f32_32x32x16_bf16(pa, PK(l2, h2), o[2], 0, 0, 0);
; __device__ __forceinline__ void out_unit(const bf16* __restrict__ Qc, const bf16* __restrict__ Kc, const bf16* __restrict__ Vc, const float* __restrict__ ST, int c, ...
;     ...
;         for (int r = 0; r < 16; ++r) {
;             const float d0 = fi - (float)((r & 3) + 8 * (r >> 2)), d1 = d0 - 32.f;
;             const float x0 = d0 >= 0.f ? d0 * lgf2 : -d0 * lgb2, x1 = d1 >= 0.f ? d1 * lgf2 : -d1 * lgb2;
;             p0[r] *= __builtin_amdgcn_exp2f(x0); p1[r] *= __builtin_amdgcn_exp2f(x1);
;         }
;         bf16x8 pa0, pa1, pa2, pa3;
;     ...
;         PK4(p0, 0, pa0); PK4(p0, 8, pa1); PK4(p1, 0, pa2); PK4(p1, 8, pa3);
;     ...
;         SBAR();
;         pv_d0(o, vb0 + 32768 + t * 16384, pa0, pa1, pa2, pa3);
	v_mul_f32_e64 v141, v131, -v138
	v_cmp_nle_f32_e32 vcc, 0, v138
	v_exp_f32_e32 v137, v137
	v_mul_f32_e32 v74, v136, v74
	v_cndmask_b32_e32 v138, v140, v141, vcc
	v_mul_f32_e32 v140, v129, v139
	v_mul_f32_e64 v141, v131, -v139
	v_cmp_nle_f32_e32 vcc, 0, v139
	v_exp_f32_e32 v138, v138
	v_add_f32_e32 v136, 0xc1900000, v152
	v_cndmask_b32_e32 v139, v140, v141, vcc
	v_exp_f32_e32 v139, v139
	v_mul_f32_e32 v90, v137, v90
	v_mul_f32_e32 v75, v138, v75
	v_add_f32_e32 v137, 0xc2000000, v136
	v_mul_f32_e32 v91, v139, v91
	v_mul_f32_e32 v138, v129, v136
	v_mul_f32_e64 v139, v131, -v136
	v_cmp_nle_f32_e32 vcc, 0, v136
	v_cvt_pk_bf16_f32 v70, v74, v75
	s_nop 1
	v_cndmask_b32_e32 v136, v138, v139, vcc
	v_mul_f32_e32 v138, v129, v137
	v_mul_f32_e64 v139, v131, -v137
	v_cmp_nle_f32_e32 vcc, 0, v137
	v_exp_f32_e32 v136, v136
	s_nop 0
	v_cndmask_b32_e32 v137, v138, v139, vcc
	v_add_f32_e32 v138, 0xc1980000, v152
	v_add_f32_e32 v139, 0xc2000000, v138
	v_mul_f32_e32 v140, v129, v138
	v_mul_f32_e64 v141, v131, -v138
	v_cmp_nle_f32_e32 vcc, 0, v138
	v_exp_f32_e32 v137, v137
	v_mul_f32_e32 v76, v136, v76
	v_cndmask_b32_e32 v138, v140, v141, vcc
	v_mul_f32_e32 v140, v129, v139
	v_mul_f32_e64 v141, v131, -v139
	v_cmp_nle_f32_e32 vcc, 0, v139
	v_exp_f32_e32 v138, v138
	v_add_f32_e32 v136, 0xc1c00000, v152
	v_cndmask_b32_e32 v139, v140, v141, vcc
	v_exp_f32_e32 v139, v139
	v_mul_f32_e32 v92, v137, v92
	v_mul_f32_e32 v77, v138, v77
	v_add_f32_e32 v137, 0xc2000000, v136
	v_mul_f32_e32 v93, v139, v93
	v_mul_f32_e32 v138, v129, v136
	v_mul_f32_e64 v139, v131, -v136
	v_cmp_nle_f32_e32 vcc, 0, v136
	v_cvt_pk_bf16_f32 v71, v76, v77
	s_nop 1
	v_cndmask_b32_e32 v136, v138, v139, vcc
	v_mul_f32_e32 v138, v129, v137
	v_mul_f32_e64 v139, v131, -v137
	v_cmp_nle_f32_e32 vcc, 0, v137
	v_exp_f32_e32 v136, v136
	s_nop 0
	v_cndmask_b32_e32 v137, v138, v139, vcc
	v_add_f32_e32 v138, 0xc1c80000, v152
	v_add_f32_e32 v139, 0xc2000000, v138
	v_mul_f32_e32 v140, v129, v138
	v_mul_f32_e64 v141, v131, -v138
	v_cmp_nle_f32_e32 vcc, 0, v138
	v_exp_f32_e32 v137, v137
	v_mul_f32_e32 v78, v136, v78
	v_cndmask_b32_e32 v138, v140, v141, vcc
	v_mul_f32_e32 v140, v129, v139
	v_mul_f32_e64 v141, v131, -v139
	v_cmp_nle_f32_e32 vcc, 0, v139
	v_exp_f32_e32 v138, v138
	v_add_f32_e32 v136, 0xc1d00000, v152
	v_cndmask_b32_e32 v139, v140, v141, vcc
	v_exp_f32_e32 v139, v139
	v_mul_f32_e32 v94, v137, v94
	v_mul_f32_e32 v79, v138, v79
	v_add_f32_e32 v137, 0xc2000000, v136
	v_mul_f32_e32 v95, v139, v95
	v_mul_f32_e32 v138, v129, v136
	v_mul_f32_e64 v139, v131, -v136
	v_cmp_nle_f32_e32 vcc, 0, v136
	v_cvt_pk_bf16_f32 v72, v78, v79
	s_nop 0
	v_permlane32_swap_b32_e32 v70, v72
	v_cndmask_b32_e32 v136, v138, v139, vcc
	v_mul_f32_e32 v138, v129, v137
	v_mul_f32_e64 v139, v131, -v137
	v_cmp_nle_f32_e32 vcc, 0, v137
	v_exp_f32_e32 v136, v136
	s_nop 0
	v_cndmask_b32_e32 v137, v138, v139, vcc
	v_add_f32_e32 v138, 0xc1d80000, v152
	v_add_f32_e32 v139, 0xc2000000, v138
	v_mul_f32_e32 v140, v129, v138
	v_mul_f32_e64 v141, v131, -v138
	v_cmp_nle_f32_e32 vcc, 0, v138
	v_exp_f32_e32 v137, v137
	v_mul_f32_e32 v80, v136, v80
	v_cndmask_b32_e32 v138, v140, v141, vcc
	v_mul_f32_e32 v140, v129, v139
	v_mul_f32_e64 v141, v131, -v139
	v_cmp_nle_f32_e32 vcc, 0, v139
	v_exp_f32_e32 v138, v138
	v_mul_f32_e32 v96, v137, v96
	v_cndmask_b32_e32 v139, v140, v141, vcc
	v_exp_f32_e32 v139, v139
	v_mul_f32_e32 v81, v138, v81
	v_cvt_pk_bf16_f32 v73, v80, v81
	v_cvt_pk_bf16_f32 v74, v82, v83
	v_mul_f32_e32 v97, v139, v97
	v_cvt_pk_bf16_f32 v75, v84, v85
	v_cvt_pk_bf16_f32 v76, v86, v87
	v_cvt_pk_bf16_f32 v77, v88, v89
	v_cvt_pk_bf16_f32 v78, v90, v91
	v_cvt_pk_bf16_f32 v79, v92, v93
	v_cvt_pk_bf16_f32 v80, v94, v95
	v_cvt_pk_bf16_f32 v81, v96, v97
	v_permlane32_swap_b32_e32 v71, v73
	v_permlane32_swap_b32_e32 v74, v76
	v_permlane32_swap_b32_e32 v75, v77
	v_permlane32_swap_b32_e32 v78, v80
	v_permlane32_swap_b32_e32 v79, v81
	ds_read_b64_tr_b16 v[82:83], v128 offset:0
	ds_read_b64_tr_b16 v[84:85], v128 offset:0x800
	ds_read_b64_tr_b16 v[86:87], v128 offset:0x1000
	ds_read_b64_tr_b16 v[88:89], v128 offset:0x1800
	ds_read_b64_tr_b16 v[90:91], v128 offset:0x2000
	ds_read_b64_tr_b16 v[92:93], v128 offset:0x2800
	ds_read_b64_tr_b16 v[94:95], v128 offset:0x3000
	ds_read_b64_tr_b16 v[96:97], v128 offset:0x3800
	s_waitcnt lgkmcnt(0)
	s_nop 0
	v_mfma_f32_32x32x16_bf16 v[50:65], v[66:69], v[82:85], v[50:65]
	ds_read_b64_tr_b16 v[82:83], v128 offset:0x200
	ds_read_b64_tr_b16 v[84:85], v128 offset:0xa00
	v_mfma_f32_32x32x16_bf16 v[50:65], v[70:73], v[86:89], v[50:65]
	ds_read_b64_tr_b16 v[86:87], v128 offset:0x1200
	ds_read_b64_tr_b16 v[88:89], v128 offset:0x1a00
	v_mfma_f32_32x32x16_bf16 v[50:65], v[74:77], v[90:93], v[50:65]
	ds_read_b64_tr_b16 v[90:91], v128 offset:0x2200
	ds_read_b64_tr_b16 v[92:93], v128 offset:0x2a00
	ds_read_b64_tr_b16 v[136:137], v128 offset:0x3200
	ds_read_b64_tr_b16 v[138:139], v128 offset:0x3a00
	s_waitcnt lgkmcnt(0)
	v_mfma_f32_32x32x16_bf16 v[50:65], v[78:81], v[94:97], v[50:65]
	v_mfma_f32_32x32x16_bf16 v[34:49], v[66:69], v[82:85], v[34:49]
	ds_read_b64_tr_b16 v[82:83], v128 offset:0x400
	ds_read_b64_tr_b16 v[84:85], v128 offset:0xc00
	v_mfma_f32_32x32x16_bf16 v[34:49], v[70:73], v[86:89], v[34:49]
	ds_read_b64_tr_b16 v[86:87], v128 offset:0x1400
	ds_read_b64_tr_b16 v[88:89], v128 offset:0x1c00
	v_mfma_f32_32x32x16_bf16 v[34:49], v[74:77], v[90:93], v[34:49]
	ds_read_b64_tr_b16 v[90:91], v128 offset:0x2400
	ds_read_b64_tr_b16 v[92:93], v128 offset:0x2c00
	ds_read_b64_tr_b16 v[94:95], v128 offset:0x3400
	ds_read_b64_tr_b16 v[96:97], v128 offset:0x3c00
	s_waitcnt lgkmcnt(0)
	v_mfma_f32_32x32x16_bf16 v[34:49], v[78:81], v[136:139], v[34:49]
	v_mfma_f32_32x32x16_bf16 v[18:33], v[66:69], v[82:85], v[18:33]
	ds_read_b64_tr_b16 v[82:83], v128 offset:0x600
	ds_read_b64_tr_b16 v[84:85], v128 offset:0xe00
	v_mfma_f32_32x32x16_bf16 v[18:33], v[70:73], v[86:89], v[18:33]
	ds_read_b64_tr_b16 v[86:87], v128 offset:0x1600
	ds_read_b64_tr_b16 v[88:89], v128 offset:0x1e00
	v_mfma_f32_32x32x16_bf16 v[18:33], v[74:77], v[90:93], v[18:33]
	ds_read_b64_tr_b16 v[90:91], v128 offset:0x2600
	ds_read_b64_tr_b16 v[92:93], v128 offset:0x2e00
	ds_read_b64_tr_b16 v[136:137], v128 offset:0x3600
	ds_read_b64_tr_b16 v[138:139], v128 offset:0x3e00
	s_waitcnt lgkmcnt(0)
	v_mfma_f32_32x32x16_bf16 v[18:33], v[78:81], v[94:97], v[18:33]
	v_mfma_f32_32x32x16_bf16 v[2:17], v[66:69], v[82:85], v[2:17]
	s_addk_i32 s59, 0x2000
	v_subrev_u32_e32 v126, 64, v126
	v_add_u32_e32 v128, 0x4000, v128
	s_cmpk_lg_u32 s59, 0x8000
	v_mfma_f32_32x32x16_bf16 v[2:17], v[70:73], v[86:89], v[2:17]
	v_mfma_f32_32x32x16_bf16 v[2:17], v[74:77], v[90:93], v[2:17]
	v_mfma_f32_32x32x16_bf16 v[2:17], v[78:81], v[136:139], v[2:17]
	s_cbranch_scc1 .LBB0_632
; __device__ __forceinline__ unsigned pk2(float lo, float hi) { return f2bf(lo) | (f2bf(hi) << 16); }
; #define SBAR() __builtin_amdgcn_sched_barrier(0)
; #define SBAR() __builtin_amdgcn_sched_barrier(0)
; __device__ __forceinline__ bf16x8 scale8(bf16x8 v, float s) {
;     v4u w = *reinterpret_cast<v4u*>(&v), o;
; #pragma unroll
;     for (int i = 0; i < 4; ++i) { const float lo = __builtin_bit_cast(float, w[i] << 16) * s, hi = __builtin_bit_cast(float, w[i] & 0xffff0000u) * s; o[i] = pk2(lo, hi); }
;     return *reinterpret_cast<bf16x8*>(&o);
; }
; __device__ __forceinline__ void out_unit(const bf16* __restrict__ Qc, const bf16* __restrict__ Kc, const bf16* __restrict__ Vc, const float* __restrict__ ST, int c, ...
;     ...
;     {
;         const float af = __builtin_amdgcn_exp2f((float)(i + 1) * lgf2), ab = __builtin_amdgcn_exp2f((float)(256 - i) * lgb2);
;         SBAR();
;         pv_d0(o, vb0 + 98304, scale8(qr[0], af), scale8(qr[1], af), scale8(qr[2], af), scale8(qr[3], af));
	s_lshl_b32 s4, s84, 8
	s_lshl_b32 s5, s83, 11
	s_or_b32 s12, s4, s5
	s_lshl_b32 s4, s12, 10
	s_add_u32 s6, s68, s4
	s_addc_u32 s7, s69, 0
	s_lshl_b32 s4, s16, 7
	s_ashr_i32 s5, s4, 31
	v_or_b32_e32 v66, v115, v121
	s_lshl_b64 s[10:11], s[4:5], 1
	v_or3_b32 v75, v66, v122, v123
	s_add_u32 s8, s6, s10
	v_add_u32_e32 v66, 1, v114
	s_addc_u32 s9, s7, s11
	s_lshl_b64 s[4:5], s[4:5], 2
	v_cvt_f32_i32_e32 v66, v66
	v_sub_u32_e32 v67, 0x100, v114
	s_add_u32 s6, s56, s4
	v_cvt_f32_i32_e32 v67, v67
	s_addc_u32 s7, s57, s5
	s_lshl_b32 s4, s12, 11
	s_add_u32 s4, s22, s4
	v_mul_f32_e32 v66, v129, v66
	s_addc_u32 s5, s23, 0
	v_exp_f32_e32 v114, v66
	v_mul_f32_e32 v66, v131, v67
	s_add_u32 s4, s4, s10
	v_exp_f32_e32 v74, v66
	s_addc_u32 s5, s5, s11
	v_and_b32_e32 v79, 0xffff0000, v111
	v_and_b32_e32 v78, 0xffff0000, v110
	v_and_b32_e32 v83, 0xffff0000, v113
	v_and_b32_e32 v82, 0xffff0000, v112
	v_lshlrev_b32_e32 v77, 16, v111
	v_lshlrev_b32_e32 v76, 16, v110
	v_mul_f32_e32 v68, v114, v78
	v_mul_f32_e32 v69, v114, v79
	v_mul_f32_e32 v72, v114, v82
	v_mul_f32_e32 v73, v114, v83
	v_mul_f32_e32 v66, v114, v76
	v_mul_f32_e32 v67, v114, v77
	v_bfe_u32 v84, v73, 16, 1
	v_bfe_u32 v85, v72, 16, 1
	v_bfe_u32 v86, v69, 16, 1
	v_bfe_u32 v87, v68, 16, 1
	v_add3_u32 v87, v68, v87, s81
	v_add3_u32 v86, v69, v86, s81
	v_add3_u32 v68, v72, v85, s81
	v_add3_u32 v69, v73, v84, s81
	v_bfe_u32 v72, v66, 16, 1
	v_bfe_u32 v73, v67, 16, 1
	v_lshlrev_b32_e32 v81, 16, v113
	v_lshlrev_b32_e32 v80, 16, v112
	v_add3_u32 v67, v67, v73, s81
	v_add3_u32 v66, v66, v72, s81
	v_mul_f32_e32 v70, v114, v80
	v_mul_f32_e32 v71, v114, v81
	v_lshrrev_b32_e32 v66, 16, v66
	v_lshrrev_b32_e32 v67, 16, v67
	v_bfe_u32 v84, v70, 16, 1
	v_bfe_u32 v85, v71, 16, 1
	v_and_or_b32 v67, v86, s82, v67
	v_and_or_b32 v66, v87, s82, v66
	v_and_b32_e32 v87, 0xffff0000, v107
	v_and_b32_e32 v86, 0xffff0000, v106
	v_and_b32_e32 v91, 0xffff0000, v109
	v_and_b32_e32 v90, 0xffff0000, v108
	v_add3_u32 v71, v71, v85, s81
	v_add3_u32 v70, v70, v84, s81
	v_mul_f32_e32 v72, v114, v86
	v_mul_f32_e32 v73, v114, v87
	v_lshlrev_b32_e32 v89, 16, v109
	v_lshlrev_b32_e32 v88, 16, v108
	v_mul_f32_e32 v94, v114, v90
	v_mul_f32_e32 v95, v114, v91
	v_lshrrev_b32_e32 v70, 16, v70
	v_lshrrev_b32_e32 v71, 16, v71
	v_lshlrev_b32_e32 v85, 16, v107
	v_lshlrev_b32_e32 v84, 16, v106
	v_mul_f32_e32 v92, v114, v88
	v_mul_f32_e32 v93, v114, v89
	v_bfe_u32 v96, v95, 16, 1
	v_bfe_u32 v97, v94, 16, 1
	v_bfe_u32 v106, v73, 16, 1
	v_bfe_u32 v107, v72, 16, 1
	v_and_or_b32 v69, v69, s82, v71
	v_and_or_b32 v68, v68, s82, v70
	v_mul_f32_e32 v70, v114, v84
	v_mul_f32_e32 v71, v114, v85
	v_add3_u32 v107, v72, v107, s81
	v_add3_u32 v106, v73, v106, s81
	v_add3_u32 v72, v94, v97, s81
	v_add3_u32 v73, v95, v96, s81
	v_bfe_u32 v96, v92, 16, 1
	v_bfe_u32 v97, v93, 16, 1
	v_bfe_u32 v94, v70, 16, 1
	v_bfe_u32 v95, v71, 16, 1
	v_add3_u32 v93, v93, v97, s81
	v_add3_u32 v92, v92, v96, s81
	v_add3_u32 v71, v71, v95, s81
	v_add3_u32 v70, v70, v94, s81
	v_lshrrev_b32_e32 v92, 16, v92
	v_lshrrev_b32_e32 v93, 16, v93
	v_and_b32_e32 v95, 0xffff0000, v103
	v_and_b32_e32 v94, 0xffff0000, v102
	v_lshrrev_b32_e32 v70, 16, v70
	v_lshrrev_b32_e32 v71, 16, v71
	v_and_or_b32 v73, v73, s82, v93
	v_and_or_b32 v72, v72, s82, v92
	v_lshlrev_b32_e32 v93, 16, v103
	v_lshlrev_b32_e32 v92, 16, v102
	v_mul_f32_e32 v108, v114, v94
	v_mul_f32_e32 v109, v114, v95
	v_lshlrev_b32_e32 v97, 16, v105
	v_lshlrev_b32_e32 v96, 16, v104
	v_and_b32_e32 v103, 0xffff0000, v105
	v_and_b32_e32 v102, 0xffff0000, v104
	v_and_or_b32 v71, v106, s82, v71
	v_and_or_b32 v70, v107, s82, v70
	v_mul_f32_e32 v106, v114, v92
	v_mul_f32_e32 v107, v114, v93
	v_mul_f32_e32 v110, v114, v96
	v_mul_f32_e32 v111, v114, v97
	v_mul_f32_e32 v104, v114, v102
	v_mul_f32_e32 v105, v114, v103
	v_bfe_u32 v115, v109, 16, 1
	v_bfe_u32 v122, v108, 16, 1
	v_bfe_u32 v112, v105, 16, 1
	v_bfe_u32 v113, v104, 16, 1
	v_add3_u32 v108, v108, v122, s81
	v_add3_u32 v109, v109, v115, s81
	v_bfe_u32 v115, v110, 16, 1
	v_bfe_u32 v122, v111, 16, 1
	v_add3_u32 v104, v104, v113, s81
	v_add3_u32 v105, v105, v112, s81
	v_bfe_u32 v112, v106, 16, 1
	v_bfe_u32 v113, v107, 16, 1
	v_add3_u32 v111, v111, v122, s81
	v_add3_u32 v110, v110, v115, s81
	v_add3_u32 v107, v107, v113, s81
	v_add3_u32 v106, v106, v112, s81
	v_lshrrev_b32_e32 v110, 16, v110
	v_lshrrev_b32_e32 v111, 16, v111
	v_lshrrev_b32_e32 v106, 16, v106
	v_lshrrev_b32_e32 v107, 16, v107
	v_and_or_b32 v111, v105, s82, v111
	v_and_or_b32 v110, v104, s82, v110
	v_lshlrev_b32_e32 v105, 16, v99
	v_lshlrev_b32_e32 v104, 16, v98
	v_and_b32_e32 v99, 0xffff0000, v99
	v_and_b32_e32 v98, 0xffff0000, v98
	s_cmp_lg_u32 0, -1
	v_and_or_b32 v109, v109, s82, v107
	v_and_or_b32 v108, v108, s82, v106
	v_mul_f32_e32 v122, v114, v98
	v_mul_f32_e32 v123, v114, v99
	v_lshlrev_b32_e32 v107, 16, v101
	v_lshlrev_b32_e32 v106, 16, v100
	s_cselect_b32 s10, 0, 0
	v_mul_f32_e32 v128, v114, v106
	v_mul_f32_e32 v129, v114, v107
	v_bfe_u32 v132, v123, 16, 1
	v_bfe_u32 v133, v122, 16, 1
	s_add_i32 s11, s10, 0x18000
	v_add3_u32 v122, v122, v133, s81
	v_add3_u32 v123, v123, v132, s81
	v_bfe_u32 v132, v128, 16, 1
	v_bfe_u32 v133, v129, 16, 1
	v_add_u32_e32 v121, s11, v75
	v_add3_u32 v129, v129, v133, s81
	v_add3_u32 v128, v128, v132, s81
	ds_read_b64_tr_b16 v[132:133], v121 offset:0
	ds_read_b64_tr_b16 v[134:135], v121 offset:0x800
	ds_read_b64_tr_b16 v[136:137], v121 offset:0x1000
	ds_read_b64_tr_b16 v[138:139], v121 offset:0x1800
	ds_read_b64_tr_b16 v[140:141], v121 offset:0x2000
	v_and_b32_e32 v101, 0xffff0000, v101
	v_and_b32_e32 v100, 0xffff0000, v100
	ds_read_b64_tr_b16 v[142:143], v121 offset:0x2800
	v_mul_f32_e32 v112, v114, v104
	v_mul_f32_e32 v113, v114, v105
	v_mul_f32_e32 v115, v114, v101
	v_mul_f32_e32 v114, v114, v100
	ds_read_b64_tr_b16 v[144:145], v121 offset:0x3000
	v_bfe_u32 v126, v115, 16, 1
	v_bfe_u32 v131, v114, 16, 1
	ds_read_b64_tr_b16 v[146:147], v121 offset:0x3800
	v_add3_u32 v114, v114, v131, s81
	v_add3_u32 v115, v115, v126, s81
	v_bfe_u32 v126, v112, 16, 1
	v_bfe_u32 v131, v113, 16, 1
	s_waitcnt lgkmcnt(0)
; #define SBAR() __builtin_amdgcn_sched_barrier(0)
; #define SBAR() __builtin_amdgcn_sched_barrier(0)
; template <int D0> __device__ __forceinline__ void pv_one(f32x16& od, int vb, bf16x8 pa0, bf16x8 pa1, bf16x8 pa2, bf16x8 pa3) {
;     const s16x4 l0 = tr_read<v_rd_off(D0, 0, 0)>(vb), h0 = tr_read<v_rd_off(D0, 0, 1)>(vb), l1 = tr_read<v_rd_off(D0, 1, 0)>(vb), h1 = tr_read<v_rd_off(D0, 1, 1)>(vb);
;     const s16x4 l2 = tr_read<v_rd_off(D0, 2, 0)>(vb), h2 = tr_read<v_rd_off(D0, 2, 1)>(vb), l3 = tr_read<v_rd_off(D0, 3, 0)>(vb), h3 = tr_read<v_rd_off(D0, 3, 1)>(vb);
;     asm volatile("s_waitcnt lgkmcnt(0)" ::: "memory"); SBAR();
;     ...
;     od = __builtin_amdgcn_mfma_f32_32x32x16_bf16(pa0, PK(l0, h0), od, 0, 0, 0);
;     od = __builtin_amdgcn_mfma_f32_32x32x16_bf16(pa1, PK(l1, h1), od, 0, 0, 0);
;     od = __builtin_amdgcn_mfma_f32_32x32x16_bf16(pa2, PK(l2, h2), od, 0, 0, 0);
;     od = __builtin_amdgcn_mfma_f32_32x32x16_bf16(pa3, PK(l3, h3), od, 0, 0, 0);
;     ...
; }
; __device__ __forceinline__ void out_unit(const bf16* __restrict__ Qc, const bf16* __restrict__ Kc, const bf16* __restrict__ Vc, const float* __restrict__ ST, int c, ...
;     ...
;         const float af = __builtin_amdgcn_exp2f((float)(i + 1) * lgf2), ab = __builtin_amdgcn_exp2f((float)(256 - i) * lgb2);
;         SBAR();
;         pv_d0(o, vb0 + 98304, scale8(qr[0], af), scale8(qr[1], af), scale8(qr[2], af), scale8(qr[3], af));
;         pv_d0(o, vb0 + 114688, scale8(qr[0], ab), scale8(qr[1], ab), scale8(qr[2], ab), scale8(qr[3], ab));
	v_add3_u32 v113, v113, v131, s81
	v_add3_u32 v112, v112, v126, s81
	v_lshrrev_b32_e32 v112, 16, v112
	v_lshrrev_b32_e32 v113, 16, v113
	v_lshrrev_b32_e32 v126, 16, v128
	v_lshrrev_b32_e32 v128, 16, v129
	v_and_or_b32 v115, v115, s82, v128
	v_and_or_b32 v114, v114, s82, v126
	v_and_or_b32 v113, v123, s82, v113
	v_and_or_b32 v112, v122, s82, v112
	v_mfma_f32_32x32x16_bf16 v[50:65], v[66:69], v[132:135], v[50:65]
	ds_read_b64_tr_b16 v[132:133], v121 offset:0x200
	ds_read_b64_tr_b16 v[134:135], v121 offset:0xa00
	v_mfma_f32_32x32x16_bf16 v[50:65], v[70:73], v[136:139], v[50:65]
	ds_read_b64_tr_b16 v[136:137], v121 offset:0x1200
	ds_read_b64_tr_b16 v[138:139], v121 offset:0x1a00
	v_mfma_f32_32x32x16_bf16 v[50:65], v[108:111], v[140:143], v[50:65]
	ds_read_b64_tr_b16 v[140:141], v121 offset:0x2200
	ds_read_b64_tr_b16 v[142:143], v121 offset:0x2a00
	ds_read_b64_tr_b16 v[148:149], v121 offset:0x3200
	ds_read_b64_tr_b16 v[150:151], v121 offset:0x3a00
	s_waitcnt lgkmcnt(0)
	v_mfma_f32_32x32x16_bf16 v[50:65], v[112:115], v[144:147], v[50:65]
	v_mfma_f32_32x32x16_bf16 v[34:49], v[66:69], v[132:135], v[34:49]
	ds_read_b64_tr_b16 v[132:133], v121 offset:0x400
	ds_read_b64_tr_b16 v[134:135], v121 offset:0xc00
	v_mfma_f32_32x32x16_bf16 v[34:49], v[70:73], v[136:139], v[34:49]
	ds_read_b64_tr_b16 v[136:137], v121 offset:0x1400
	ds_read_b64_tr_b16 v[138:139], v121 offset:0x1c00
	v_mfma_f32_32x32x16_bf16 v[34:49], v[108:111], v[140:143], v[34:49]
	ds_read_b64_tr_b16 v[140:141], v121 offset:0x2400
	ds_read_b64_tr_b16 v[142:143], v121 offset:0x2c00
	ds_read_b64_tr_b16 v[144:145], v121 offset:0x3400
	ds_read_b64_tr_b16 v[146:147], v121 offset:0x3c00
	s_waitcnt lgkmcnt(0)
	v_mfma_f32_32x32x16_bf16 v[34:49], v[112:115], v[148:151], v[34:49]
	v_mfma_f32_32x32x16_bf16 v[18:33], v[66:69], v[132:135], v[18:33]
	ds_read_b64_tr_b16 v[132:133], v121 offset:0x600
	ds_read_b64_tr_b16 v[134:135], v121 offset:0xe00
	v_mfma_f32_32x32x16_bf16 v[18:33], v[70:73], v[136:139], v[18:33]
	ds_read_b64_tr_b16 v[136:137], v121 offset:0x1600
	ds_read_b64_tr_b16 v[138:139], v121 offset:0x1e00
	v_mfma_f32_32x32x16_bf16 v[18:33], v[108:111], v[140:143], v[18:33]
	ds_read_b64_tr_b16 v[140:141], v121 offset:0x2600
	ds_read_b64_tr_b16 v[142:143], v121 offset:0x2e00
	ds_read_b64_tr_b16 v[148:149], v121 offset:0x3600
	ds_read_b64_tr_b16 v[150:151], v121 offset:0x3e00
	s_waitcnt lgkmcnt(0)
	v_mfma_f32_32x32x16_bf16 v[18:33], v[112:115], v[144:147], v[18:33]
	v_mfma_f32_32x32x16_bf16 v[2:17], v[66:69], v[132:135], v[2:17]
	v_mul_f32_e64 v78, v74, v78
	v_mul_f32_e64 v79, v74, v79
	s_add_i32 s10, s10, 0x1c000
	v_mul_f32_e64 v76, v74, v76
	v_mul_f32_e64 v77, v74, v77
	v_mul_f32_e32 v80, v74, v80
	v_mul_f32_e32 v81, v74, v81
	v_bfe_u32 v68, v79, 16, 1
	v_bfe_u32 v69, v78, 16, 1
	v_add_u32_e32 v121, s10, v75
	v_mul_f32_e32 v82, v74, v82
	v_mul_f32_e32 v83, v74, v83
	v_add3_u32 v75, v78, v69, s81
	v_add3_u32 v78, v79, v68, s81
	v_mfma_f32_32x32x16_bf16 v[2:17], v[70:73], v[136:139], v[2:17]
	v_bfe_u32 v68, v76, 16, 1
	v_bfe_u32 v69, v77, 16, 1
	v_bfe_u32 v70, v80, 16, 1
	v_bfe_u32 v71, v81, 16, 1
	v_bfe_u32 v66, v83, 16, 1
	v_bfe_u32 v67, v82, 16, 1
	v_add3_u32 v71, v81, v71, s81
	v_add3_u32 v70, v80, v70, s81
	v_add3_u32 v69, v77, v69, s81
	v_add3_u32 v68, v76, v68, s81
	v_add3_u32 v67, v82, v67, s81
	v_add3_u32 v66, v83, v66, s81
	v_lshrrev_b32_e32 v72, 16, v68
	v_lshrrev_b32_e32 v73, 16, v69
	v_lshrrev_b32_e32 v68, 16, v70
	v_lshrrev_b32_e32 v69, 16, v71
	v_and_or_b32 v69, v66, s82, v69
	v_and_or_b32 v68, v67, s82, v68
	v_and_or_b32 v67, v78, s82, v73
	v_and_or_b32 v66, v75, s82, v72
	v_mul_f32_e32 v72, v74, v86
	v_mul_f32_e32 v73, v74, v87
	v_mul_f32_e32 v78, v74, v90
	v_mul_f32_e32 v79, v74, v91
	v_mul_f32_e32 v70, v74, v84
	v_mul_f32_e32 v71, v74, v85
	v_mul_f32_e32 v76, v74, v88
	v_mul_f32_e32 v77, v74, v89
	v_bfe_u32 v75, v79, 16, 1
	v_bfe_u32 v81, v73, 16, 1
	v_bfe_u32 v80, v78, 16, 1
	v_bfe_u32 v82, v72, 16, 1
	v_add3_u32 v81, v73, v81, s81
	v_add3_u32 v73, v79, v75, s81
	v_bfe_u32 v75, v70, 16, 1
	v_bfe_u32 v79, v76, 16, 1
	v_add3_u32 v82, v72, v82, s81
	v_add3_u32 v72, v78, v80, s81
	v_bfe_u32 v78, v71, 16, 1
	v_bfe_u32 v80, v77, 16, 1
	v_add3_u32 v76, v76, v79, s81
	v_add3_u32 v70, v70, v75, s81
	v_add3_u32 v77, v77, v80, s81
	v_add3_u32 v71, v71, v78, s81
	v_lshrrev_b32_e32 v70, 16, v70
	v_lshrrev_b32_e32 v75, 16, v76
	v_lshrrev_b32_e32 v71, 16, v71
	v_lshrrev_b32_e32 v76, 16, v77
	v_and_or_b32 v70, v82, s82, v70
	v_mul_f32_e32 v78, v74, v94
	v_mul_f32_e32 v79, v74, v95
	v_mul_f32_e32 v82, v74, v102
	v_mul_f32_e32 v83, v74, v103
	v_and_or_b32 v73, v73, s82, v76
	v_and_or_b32 v72, v72, s82, v75
	v_and_or_b32 v71, v81, s82, v71
	v_mul_f32_e32 v76, v74, v92
	v_mul_f32_e32 v77, v74, v93
	v_mul_f32_e32 v80, v74, v96
	v_mul_f32_e32 v81, v74, v97
	v_bfe_u32 v75, v83, 16, 1
	v_bfe_u32 v84, v82, 16, 1
	v_bfe_u32 v86, v78, 16, 1
	v_bfe_u32 v85, v79, 16, 1
	v_add3_u32 v86, v78, v86, s81
	v_add3_u32 v78, v82, v84, s81
	v_add3_u32 v75, v83, v75, s81
	v_bfe_u32 v82, v77, 16, 1
	v_bfe_u32 v83, v80, 16, 1
	v_bfe_u32 v84, v81, 16, 1
	v_add3_u32 v85, v79, v85, s81
	v_bfe_u32 v79, v76, 16, 1
	v_add3_u32 v81, v81, v84, s81
	v_add3_u32 v80, v80, v83, s81
	v_add3_u32 v77, v77, v82, s81
	v_add3_u32 v76, v76, v79, s81
	v_lshrrev_b32_e32 v77, 16, v77
	v_lshrrev_b32_e32 v80, 16, v80
	v_lshrrev_b32_e32 v79, 16, v81
	v_lshrrev_b32_e32 v76, 16, v76
	v_and_or_b32 v79, v75, s82, v79
	v_and_or_b32 v78, v78, s82, v80
	v_and_or_b32 v77, v85, s82, v77
	v_mul_f32_e32 v80, v74, v104
	v_mul_f32_e32 v81, v74, v105
	v_mul_f32_e32 v82, v74, v98
	v_mul_f32_e32 v83, v74, v99
	v_mul_f32_e32 v84, v74, v106
	v_mul_f32_e32 v85, v74, v107
	v_mul_f32_e32 v75, v74, v101
	v_mul_f32_e32 v74, v74, v100
	v_and_or_b32 v76, v86, s82, v76
	v_bfe_u32 v86, v75, 16, 1
	v_bfe_u32 v87, v74, 16, 1
	v_bfe_u32 v88, v83, 16, 1
	v_bfe_u32 v89, v82, 16, 1
	v_add3_u32 v74, v74, v87, s81
	v_add3_u32 v75, v75, v86, s81
	v_bfe_u32 v86, v84, 16, 1
	v_bfe_u32 v87, v85, 16, 1
	v_add3_u32 v89, v82, v89, s81
	v_add3_u32 v88, v83, v88, s81
	v_bfe_u32 v82, v80, 16, 1
	v_bfe_u32 v83, v81, 16, 1
	v_add3_u32 v85, v85, v87, s81
	v_add3_u32 v84, v84, v86, s81
	v_add3_u32 v81, v81, v83, s81
	v_add3_u32 v80, v80, v82, s81
	v_lshrrev_b32_e32 v82, 16, v84
	v_lshrrev_b32_e32 v83, 16, v85
	ds_read_b64_tr_b16 v[84:85], v121 offset:0
	v_lshrrev_b32_e32 v80, 16, v80
	v_lshrrev_b32_e32 v81, 16, v81
	ds_read_b64_tr_b16 v[86:87], v121 offset:0x800
	v_and_or_b32 v81, v88, s82, v81
	v_and_or_b32 v80, v89, s82, v80
	ds_read_b64_tr_b16 v[88:89], v121 offset:0x1000
	v_mfma_f32_32x32x16_bf16 v[2:17], v[108:111], v[140:143], v[2:17]
	ds_read_b64_tr_b16 v[90:91], v121 offset:0x1800
	ds_read_b64_tr_b16 v[92:93], v121 offset:0x2000
	ds_read_b64_tr_b16 v[94:95], v121 offset:0x2800
	ds_read_b64_tr_b16 v[96:97], v121 offset:0x3000
	ds_read_b64_tr_b16 v[98:99], v121 offset:0x3800
	s_waitcnt lgkmcnt(0)
; __device__ __forceinline__ int crow(int r, int hi) { return (r & 3) + 8 * (r >> 2) + 4 * hi; }
; __device__ __forceinline__ void out_unit(const bf16* __restrict__ Qc, const bf16* __restrict__ Kc, const bf16* __restrict__ Vc, const float* __restrict__ ST, int c, ...
;     ...
;         pv_d0(o, vb0 + 114688, scale8(qr[0], ab), scale8(qr[1], ab), scale8(qr[2], ab), scale8(qr[3], ab));
;     }
;     __syncthreads();
;     {
;         float* stg = (float*)(lds + wid * 16384);
; #pragma unroll
;         for (int r = 0; r < 16; ++r) { const int orow = crow(r, hi);
; #pragma unroll
;             for (int d0 = 0; d0 < 4; ++d0) stg[orow * 128 + d0 * 32 + r32] = o[d0][r]; }
;         const int c0 = (lane & 15) * 8, rq = lane >> 4;
;         v4u gv[8];
; #pragma unroll
;         for (int i = 0; i < 8; ++i) gv[i] = *(const v4u*)(RGc + (size_t)(wid * 32 + i * 4 + rq) * 512 + c0);
;         const f32x4 gn0 = *(const f32x4*)(gnorm + c0), gn1 = *(const f32x4*)(gnorm + c0 + 4);
;         asm volatile("s_waitcnt lgkmcnt(0)" ::: "memory");
	v_and_or_b32 v83, v75, s82, v83
	v_mfma_f32_32x32x16_bf16 v[2:17], v[112:115], v[148:151], v[2:17]
	v_and_or_b32 v82, v74, s82, v82
	v_mfma_f32_32x32x16_bf16 v[50:65], v[66:69], v[84:87], v[50:65]
	ds_read_b64_tr_b16 v[84:85], v121 offset:0x200
	ds_read_b64_tr_b16 v[86:87], v121 offset:0xa00
	v_mfma_f32_32x32x16_bf16 v[50:65], v[70:73], v[88:91], v[50:65]
	ds_read_b64_tr_b16 v[88:89], v121 offset:0x1200
	ds_read_b64_tr_b16 v[90:91], v121 offset:0x1a00
	v_mfma_f32_32x32x16_bf16 v[50:65], v[76:79], v[92:95], v[50:65]
	ds_read_b64_tr_b16 v[92:93], v121 offset:0x2200
	ds_read_b64_tr_b16 v[94:95], v121 offset:0x2a00
	ds_read_b64_tr_b16 v[100:101], v121 offset:0x3200
	ds_read_b64_tr_b16 v[102:103], v121 offset:0x3a00
	s_waitcnt lgkmcnt(0)
	v_mfma_f32_32x32x16_bf16 v[50:65], v[80:83], v[96:99], v[50:65]
	v_mfma_f32_32x32x16_bf16 v[34:49], v[66:69], v[84:87], v[34:49]
	ds_read_b64_tr_b16 v[84:85], v121 offset:0x400
	ds_read_b64_tr_b16 v[86:87], v121 offset:0xc00
	v_mfma_f32_32x32x16_bf16 v[34:49], v[70:73], v[88:91], v[34:49]
	ds_read_b64_tr_b16 v[88:89], v121 offset:0x1400
	ds_read_b64_tr_b16 v[90:91], v121 offset:0x1c00
	v_mfma_f32_32x32x16_bf16 v[34:49], v[76:79], v[92:95], v[34:49]
	ds_read_b64_tr_b16 v[92:93], v121 offset:0x2400
	ds_read_b64_tr_b16 v[94:95], v121 offset:0x2c00
	ds_read_b64_tr_b16 v[96:97], v121 offset:0x3400
	ds_read_b64_tr_b16 v[98:99], v121 offset:0x3c00
	s_waitcnt lgkmcnt(0)
	v_mfma_f32_32x32x16_bf16 v[34:49], v[80:83], v[100:103], v[34:49]
	v_mfma_f32_32x32x16_bf16 v[18:33], v[66:69], v[84:87], v[18:33]
	ds_read_b64_tr_b16 v[84:85], v121 offset:0x600
	ds_read_b64_tr_b16 v[86:87], v121 offset:0xe00
	v_mfma_f32_32x32x16_bf16 v[18:33], v[70:73], v[88:91], v[18:33]
	ds_read_b64_tr_b16 v[88:89], v121 offset:0x1600
	ds_read_b64_tr_b16 v[90:91], v121 offset:0x1e00
	v_mfma_f32_32x32x16_bf16 v[18:33], v[76:79], v[92:95], v[18:33]
	ds_read_b64_tr_b16 v[92:93], v121 offset:0x2600
	ds_read_b64_tr_b16 v[94:95], v121 offset:0x2e00
	ds_read_b64_tr_b16 v[100:101], v121 offset:0x3600
	ds_read_b64_tr_b16 v[102:103], v121 offset:0x3e00
	s_waitcnt lgkmcnt(0)
	v_mfma_f32_32x32x16_bf16 v[18:33], v[80:83], v[96:99], v[18:33]
	v_mfma_f32_32x32x16_bf16 v[2:17], v[66:69], v[84:87], v[2:17]
	v_lshl_add_u32 v74, v130, 14, 0
	v_lshlrev_b32_e32 v66, 11, v120
	v_lshlrev_b32_e32 v67, 2, v125
	v_add3_u32 v75, v74, v66, v67
	s_barrier
	v_mfma_f32_32x32x16_bf16 v[2:17], v[70:73], v[88:91], v[2:17]
	v_add_u32_e32 v70, 0x400, v75
	ds_write2_b32 v75, v50, v34 offset1:32
	ds_write2_b32 v75, v51, v35 offset0:128 offset1:160
	ds_write2_b32 v70, v52, v36 offset1:32
	ds_write2_b32 v70, v53, v37 offset0:128 offset1:160
	v_lshrrev_b32_e32 v52, 4, v124
	v_or_b32_e32 v50, v119, v52
	v_add_u32_e32 v36, 0x1000, v75
	v_ashrrev_i32_e32 v51, 31, v50
	v_mfma_f32_32x32x16_bf16 v[2:17], v[76:79], v[92:95], v[2:17]
	ds_write2_b32 v36, v54, v38 offset1:32
	ds_write2_b32 v36, v55, v39 offset0:128 offset1:160
	v_lshl_add_u64 v[38:39], s[8:9], 0, v[116:117]
	v_lshlrev_b64 v[34:35], 10, v[50:51]
	v_lshl_add_u64 v[34:35], v[38:39], 0, v[34:35]
	global_load_dwordx4 v[66:69], v[34:35], off
	v_add_u32_e32 v37, 0x1400, v75
	s_add_i32 s75, s75, s18
	v_mfma_f32_32x32x16_bf16 v[2:17], v[80:83], v[100:103], v[2:17]
	s_cmpk_gt_i32 s75, 0xff
	s_nop 10
	ds_write2_b32 v75, v18, v2 offset0:64 offset1:96
	ds_write2_b32 v75, v19, v3 offset0:192 offset1:224
	ds_write2_b32 v70, v20, v4 offset0:64 offset1:96
	ds_write2_b32 v70, v21, v5 offset0:192 offset1:224
	ds_write2_b32 v36, v22, v6 offset0:64 offset1:96
	ds_write2_b32 v36, v23, v7 offset0:192 offset1:224
	ds_write2_b32 v37, v56, v40 offset1:32
	ds_write2_b32 v37, v24, v8 offset0:64 offset1:96
	ds_write2_b32 v37, v57, v41 offset0:128 offset1:160
	ds_write2_b32 v37, v25, v9 offset0:192 offset1:224
	v_add_u32_e32 v2, 0x2000, v75
	ds_write2_b32 v2, v58, v42 offset1:32
	ds_write2_b32 v2, v26, v10 offset0:64 offset1:96
	ds_write2_b32 v2, v59, v43 offset0:128 offset1:160
	ds_write2_b32 v2, v27, v11 offset0:192 offset1:224
	v_add_u32_e32 v2, 0x2400, v75
	ds_write2_b32 v2, v60, v44 offset1:32
	ds_write2_b32 v2, v28, v12 offset0:64 offset1:96
	ds_write2_b32 v2, v61, v45 offset0:128 offset1:160
	ds_write2_b32 v2, v29, v13 offset0:192 offset1:224
	v_add_u32_e32 v2, 0x3000, v75
	v_add_u32_e32 v10, 0x3400, v75
	ds_write2_b32 v2, v62, v46 offset1:32
	ds_write2_b32 v2, v30, v14 offset0:64 offset1:96
	ds_write2_b32 v2, v63, v47 offset0:128 offset1:160
	ds_write2_b32 v2, v31, v15 offset0:192 offset1:224
	ds_write2_b32 v10, v64, v48 offset1:32
	ds_write2_b32 v10, v32, v16 offset0:64 offset1:96
	ds_write2_b32 v10, v65, v49 offset0:128 offset1:160
	global_load_dwordx4 v[2:5], v118, s[6:7] offset:16
	global_load_dwordx4 v[6:9], v118, s[6:7]
	ds_write2_b32 v10, v33, v17 offset0:192 offset1:224
	v_or_b32_e32 v10, 4, v50
	v_ashrrev_i32_e32 v11, 31, v10
	v_lshlrev_b64 v[10:11], 10, v[10:11]
	v_lshl_add_u64 v[10:11], v[38:39], 0, v[10:11]
	global_load_dwordx4 v[34:37], v[10:11], off
	v_or_b32_e32 v10, 8, v50
	v_or_b32_e32 v12, 12, v50
	v_ashrrev_i32_e32 v11, 31, v10
	v_ashrrev_i32_e32 v13, 31, v12
	v_lshlrev_b64 v[10:11], 10, v[10:11]
	v_lshlrev_b64 v[12:13], 10, v[12:13]
	v_lshl_add_u64 v[10:11], v[38:39], 0, v[10:11]
	v_lshl_add_u64 v[12:13], v[38:39], 0, v[12:13]
	global_load_dwordx4 v[30:33], v[10:11], off
	global_load_dwordx4 v[26:29], v[12:13], off
	v_or_b32_e32 v10, 16, v50
	v_or_b32_e32 v12, 20, v50
	v_ashrrev_i32_e32 v11, 31, v10
	v_ashrrev_i32_e32 v13, 31, v12
	v_lshlrev_b64 v[10:11], 10, v[10:11]
	v_lshlrev_b64 v[12:13], 10, v[12:13]
	v_lshl_add_u64 v[10:11], v[38:39], 0, v[10:11]
	v_lshl_add_u64 v[12:13], v[38:39], 0, v[12:13]
	global_load_dwordx4 v[22:25], v[10:11], off
	global_load_dwordx4 v[18:21], v[12:13], off
	v_or_b32_e32 v10, 24, v50
	v_or_b32_e32 v12, 28, v50
	v_ashrrev_i32_e32 v11, 31, v10
	v_ashrrev_i32_e32 v13, 31, v12
	v_lshlrev_b64 v[10:11], 10, v[10:11]
	v_lshlrev_b64 v[12:13], 10, v[12:13]
	v_lshl_add_u64 v[10:11], v[38:39], 0, v[10:11]
	v_lshl_add_u64 v[12:13], v[38:39], 0, v[12:13]
	v_add_u32_e32 v44, v74, v118
	global_load_dwordx4 v[14:17], v[10:11], off
	s_nop 0
	global_load_dwordx4 v[10:13], v[12:13], off
	s_waitcnt lgkmcnt(0)
; __device__ __forceinline__ unsigned pk2(float lo, float hi) { return f2bf(lo) | (f2bf(hi) << 16); }
; __device__ __forceinline__ void out_unit(const bf16* __restrict__ Qc, const bf16* __restrict__ Kc, const bf16* __restrict__ Vc, const float* __restrict__ ST, int c, ...
;     ...
;         for (int i = 0; i < 8; ++i) { const int row = i * 4 + rq;
;             const f32x4 y0 = *(const f32x4*)(stg + row * 128 + c0), y1 = *(const f32x4*)(stg + row * 128 + c0 + 4);
;             float ss = (y0.x * y0.x + y0.y * y0.y) + (y0.z * y0.z + y0.w * y0.w) + (y1.x * y1.x + y1.y * y1.y) + (y1.z * y1.z + y1.w * y1.w);
;             ss += __int_as_float(__builtin_amdgcn_update_dpp(0, __float_as_int(ss), 0xB1, 0xf, 0xf, true));
;             ss += __int_as_float(__builtin_amdgcn_update_dpp(0, __float_as_int(ss), 0x4E, 0xf, 0xf, true));
;             ss += __int_as_float(__builtin_amdgcn_update_dpp(0, __float_as_int(ss), 0x141, 0xf, 0xf, true));
;             ss += __int_as_float(__builtin_amdgcn_update_dpp(0, __float_as_int(ss), 0x140, 0xf, 0xf, true));
;             const float rstd = rsqrtf(ss * (1.f / 128.f) + 1e-6f);
;             float yv[8] = {y0.x, y0.y, y0.z, y0.w, y1.x, y1.y, y1.z, y1.w}; const float gnv[8] = {gn0.x, gn0.y, gn0.z, gn0.w, gn1.x, gn1.y, gn1.z, gn1.w};
;             v4u ov;
; #pragma unroll
;             for (int j = 0; j < 4; ++j) { const float ga = __builtin_bit_cast(float, gv[i][j] << 16), gb = __builtin_bit_cast(float, gv[i][j] & 0xffff0000u);
;                 const float sa = ga * __builtin_amdgcn_rcpf(1.f + __expf(-ga)), sb = gb * __builtin_amdgcn_rcpf(1.f + __expf(-gb));
;                 ov[j] = pk2(yv[2 * j] * rstd * gnv[2 * j] * sa, yv[2 * j + 1] * rstd * gnv[2 * j + 1] * sb); }
;             *(v4u*)(MIXc + (size_t)(wid * 32 + row) * 1024 + c0) = ov;
	v_lshl_add_u32 v40, v52, 9, v44
	ds_read_b128 v[46:49], v40
	ds_read_b128 v[54:57], v40 offset:16
	v_lshl_add_u64 v[38:39], s[4:5], 0, v[116:117]
	s_waitcnt lgkmcnt(1)
	v_mul_f32_e32 v40, v48, v48
	v_mul_f32_e32 v41, v49, v49
	v_mul_f32_e32 v42, v46, v46
	v_mul_f32_e32 v43, v47, v47
	v_mov_b32_e32 v74, v46
	v_pk_mov_b32 v[58:59], v[42:43], v[40:41] op_sel:[1,0]
	v_mov_b32_e32 v43, v41
	s_waitcnt lgkmcnt(0)
	v_mul_f32_e32 v40, v56, v56
	v_mul_f32_e32 v41, v57, v57
	v_add_f32_e32 v42, v58, v42
	v_add_f32_e32 v43, v59, v43
	v_mov_b32_e32 v60, v40
	v_mul_f32_e32 v58, v54, v54
	v_mul_f32_e32 v59, v55, v55
	v_mov_b32_e32 v75, v48
	v_mov_b32_e32 v61, v58
	v_mov_b32_e32 v58, v41
	v_add_f32_e32 v72, v60, v58
	v_add_f32_e32 v73, v61, v59
	v_mov_b32_e32 v48, v47
	v_mov_b32_e32 v76, v54
	v_mov_b32_e32 v77, v56
	v_mov_b32_e32 v56, v55
	s_waitcnt vmcnt(9)
	v_lshlrev_b32_e32 v62, 16, v66
	v_mul_f32_e32 v40, 0xbfb8aa3b, v62
	v_and_b32_e32 v64, 0xffff0000, v66
	v_exp_f32_e32 v40, v40
	v_mul_f32_e32 v45, 0xbfb8aa3b, v64
	v_exp_f32_e32 v45, v45
	v_lshlrev_b32_e32 v63, 16, v67
	v_add_f32_e32 v40, 1.0, v40
	v_rcp_f32_e32 v66, v40
	v_and_b32_e32 v65, 0xffff0000, v67
	v_add_f32_e32 v40, 1.0, v45
	v_mul_f32_e32 v45, 0xbfb8aa3b, v63
	v_exp_f32_e32 v45, v45
	v_mul_f32_e32 v53, 0xbfb8aa3b, v65
	v_exp_f32_e32 v53, v53
	v_rcp_f32_e32 v70, v40
	v_add_f32_e32 v40, 1.0, v45
	v_rcp_f32_e32 v67, v40
	v_add_f32_e32 v40, 1.0, v53
	v_lshlrev_b32_e32 v58, 16, v68
	v_rcp_f32_e32 v71, v40
	s_waitcnt vmcnt(7)
	v_mov_b32_e32 v40, v6
	v_mul_f32_e32 v6, 0xbfb8aa3b, v58
	v_and_b32_e32 v60, 0xffff0000, v68
	v_mov_b32_e32 v41, v8
	v_exp_f32_e32 v6, v6
	v_mul_f32_e32 v8, 0xbfb8aa3b, v60
	v_exp_f32_e32 v8, v8
	v_lshlrev_b32_e32 v59, 16, v69
	v_add_f32_e32 v6, 1.0, v6
	v_mul_f32_e32 v66, v66, v62
	v_mul_f32_e32 v67, v67, v63
	v_rcp_f32_e32 v62, v6
	v_and_b32_e32 v61, 0xffff0000, v69
	v_add_f32_e32 v6, 1.0, v8
	v_mul_f32_e32 v8, 0xbfb8aa3b, v59
	v_exp_f32_e32 v8, v8
	v_mul_f32_e32 v45, 0xbfb8aa3b, v61
	v_exp_f32_e32 v45, v45
	v_mul_f32_e32 v70, v70, v64
	v_mul_f32_e32 v71, v71, v65
	v_rcp_f32_e32 v64, v6
	v_add_f32_e32 v6, 1.0, v8
	v_rcp_f32_e32 v63, v6
	v_add_f32_e32 v6, 1.0, v45
	v_rcp_f32_e32 v65, v6
	v_or_b32_e32 v45, 4, v52
	v_lshl_add_u32 v53, v45, 9, v44
	v_mul_f32_e32 v46, v62, v58
	v_mul_f32_e32 v47, v63, v59
	v_mul_f32_e32 v68, v64, v60
	v_mul_f32_e32 v69, v65, v61
	ds_read_b128 v[58:61], v53
	ds_read_b128 v[62:65], v53 offset:16
	v_mov_b32_e32 v6, v2
	v_mov_b32_e32 v8, v7
	v_mov_b32_e32 v7, v4
	s_waitcnt lgkmcnt(1)
	v_mul_f32_e32 v54, v60, v60
	v_mul_f32_e32 v55, v61, v61
	v_mul_f32_e32 v78, v58, v58
	v_mul_f32_e32 v79, v59, v59
	v_mov_b32_e32 v4, v3
	v_pk_mov_b32 v[80:81], v[78:79], v[54:55] op_sel:[1,0]
	v_mov_b32_e32 v79, v55
	v_add_f32_e32 v54, v80, v78
	v_add_f32_e32 v55, v81, v79
	s_waitcnt lgkmcnt(0)
	v_mul_f32_e32 v78, v64, v64
	v_mul_f32_e32 v79, v65, v65
	v_mul_f32_e32 v80, v62, v62
	v_mul_f32_e32 v81, v63, v63
	v_mov_b32_e32 v82, v78
	v_mov_b32_e32 v83, v80
	v_mov_b32_e32 v80, v79
	v_add_f32_e32 v78, v82, v80
	v_add_f32_e32 v79, v83, v81
	v_mov_b32_e32 v80, v54
	v_mov_b32_e32 v81, v42
	v_mov_b32_e32 v42, v55
	v_add_f32_e32 v42, v80, v42
	v_add_f32_e32 v43, v81, v43
	v_mov_b32_e32 v54, v79
	v_mov_b32_e32 v55, v73
	v_add_f32_e32 v42, v42, v54
	v_add_f32_e32 v43, v43, v55
	v_mov_b32_e32 v79, v72
	v_add_f32_e32 v42, v78, v42
	v_add_f32_e32 v43, v79, v43
	s_nop 1
	v_mov_b32_dpp v55, v43 quad_perm:[1,0,3,2] row_mask:0xf bank_mask:0xf bound_ctrl:1
	v_mov_b32_dpp v54, v42 quad_perm:[1,0,3,2] row_mask:0xf bank_mask:0xf bound_ctrl:1
	v_add_f32_e32 v42, v42, v54
	v_add_f32_e32 v43, v43, v55
	s_nop 1
	v_mov_b32_dpp v55, v43 quad_perm:[2,3,0,1] row_mask:0xf bank_mask:0xf bound_ctrl:1
	v_mov_b32_dpp v54, v42 quad_perm:[2,3,0,1] row_mask:0xf bank_mask:0xf bound_ctrl:1
	v_add_f32_e32 v42, v42, v54
	v_add_f32_e32 v43, v43, v55
	s_nop 1
	v_mov_b32_dpp v55, v43 row_half_mirror row_mask:0xf bank_mask:0xf bound_ctrl:1
	v_mov_b32_dpp v54, v42 row_half_mirror row_mask:0xf bank_mask:0xf bound_ctrl:1
	v_add_f32_e32 v42, v42, v54
	v_add_f32_e32 v43, v43, v55
	s_nop 1
	v_mov_b32_dpp v55, v43 row_mirror row_mask:0xf bank_mask:0xf bound_ctrl:1
	v_mov_b32_dpp v54, v42 row_mirror row_mask:0xf bank_mask:0xf bound_ctrl:1
	v_add_f32_e32 v54, v42, v54
	v_add_f32_e32 v55, v43, v55
	v_mov_b64_e32 v[42:43], s[48:49]
	v_fma_f32 v54, v54, s46, v42
	v_fma_f32 v55, v55, s46, v42
	s_nop 0
	v_mul_f32_e32 v2, 0x4b800000, v55
	v_cmp_gt_f32_e32 vcc, s74, v55
	s_nop 1
	v_cndmask_b32_e32 v2, v55, v2, vcc
	v_rsq_f32_e32 v53, v2
	v_lshlrev_b64 v[2:3], 11, v[50:51]
	v_lshl_add_u64 v[2:3], v[38:39], 0, v[2:3]
	v_mul_f32_e32 v50, 0x45800000, v53
	v_cndmask_b32_e32 v50, v53, v50, vcc
	v_mul_f32_e32 v48, v48, v50
	v_mul_f32_e32 v49, v49, v50
	v_mul_f32_e32 v72, v74, v50
	v_mul_f32_e32 v73, v75, v50
	v_mul_f32_e32 v48, v8, v48
	v_mul_f32_e32 v49, v9, v49
	v_mul_f32_e32 v72, v40, v72
	v_mul_f32_e32 v73, v41, v73
	v_mul_f32_e32 v48, v70, v48
	v_mul_f32_e32 v49, v71, v49
	v_mul_f32_e32 v70, v76, v50
	v_mul_f32_e32 v71, v77, v50
	v_mul_f32_e32 v51, v57, v50
	v_mul_f32_e32 v50, v56, v50
	v_mul_f32_e32 v70, v6, v70
	v_mul_f32_e32 v71, v7, v71
	v_mul_f32_e32 v50, v4, v50
	v_mul_f32_e32 v51, v5, v51
	v_mul_f32_e32 v66, v66, v72
	v_mul_f32_e32 v67, v67, v73
	v_mul_f32_e32 v50, v68, v50
	v_mul_f32_e32 v51, v69, v51
	v_mul_f32_e32 v46, v46, v70
	v_mul_f32_e32 v47, v47, v71
	v_bfe_u32 v53, v51, 16, 1
	v_bfe_u32 v55, v50, 16, 1
	v_bfe_u32 v56, v49, 16, 1
	v_bfe_u32 v57, v48, 16, 1
	v_add3_u32 v57, v48, v57, s81
	v_add3_u32 v56, v49, v56, s81
	v_add3_u32 v48, v50, v55, s81
	v_add3_u32 v49, v51, v53, s81
	v_bfe_u32 v50, v66, 16, 1
	v_bfe_u32 v51, v67, 16, 1
	v_bfe_u32 v53, v46, 16, 1
	v_bfe_u32 v55, v47, 16, 1
	v_add3_u32 v47, v47, v55, s81
	v_add3_u32 v46, v46, v53, s81
	v_add3_u32 v51, v67, v51, s81
	v_add3_u32 v50, v66, v50, s81
	v_lshrrev_b32_e32 v50, 16, v50
	v_lshrrev_b32_e32 v51, 16, v51
	v_lshrrev_b32_e32 v46, 16, v46
	v_lshrrev_b32_e32 v47, 16, v47
	v_and_or_b32 v49, v49, s82, v47
	v_and_or_b32 v48, v48, s82, v46
	v_and_or_b32 v47, v56, s82, v51
	v_and_or_b32 v46, v57, s82, v50
	global_store_dwordx4 v[2:3], v[46:49], off
	v_mul_f32_e32 v2, 0x4b800000, v54
	v_cmp_gt_f32_e32 vcc, s74, v54
	s_waitcnt vmcnt(7)
; __device__ __forceinline__ unsigned pk2(float lo, float hi) { return f2bf(lo) | (f2bf(hi) << 16); }
; __device__ __forceinline__ void out_unit(const bf16* __restrict__ Qc, const bf16* __restrict__ Kc, const bf16* __restrict__ Vc, const float* __restrict__ ST, int c, ...
;     ...
;         for (int i = 0; i < 8; ++i) { const int row = i * 4 + rq;
;             const f32x4 y0 = *(const f32x4*)(stg + row * 128 + c0), y1 = *(const f32x4*)(stg + row * 128 + c0 + 4);
;             float ss = (y0.x * y0.x + y0.y * y0.y) + (y0.z * y0.z + y0.w * y0.w) + (y1.x * y1.x + y1.y * y1.y) + (y1.z * y1.z + y1.w * y1.w);
;             ss += __int_as_float(__builtin_amdgcn_update_dpp(0, __float_as_int(ss), 0xB1, 0xf, 0xf, true));
;             ss += __int_as_float(__builtin_amdgcn_update_dpp(0, __float_as_int(ss), 0x4E, 0xf, 0xf, true));
;             ss += __int_as_float(__builtin_amdgcn_update_dpp(0, __float_as_int(ss), 0x141, 0xf, 0xf, true));
;             ss += __int_as_float(__builtin_amdgcn_update_dpp(0, __float_as_int(ss), 0x140, 0xf, 0xf, true));
;             const float rstd = rsqrtf(ss * (1.f / 128.f) + 1e-6f);
;             float yv[8] = {y0.x, y0.y, y0.z, y0.w, y1.x, y1.y, y1.z, y1.w}; const float gnv[8] = {gn0.x, gn0.y, gn0.z, gn0.w, gn1.x, gn1.y, gn1.z, gn1.w};
;             v4u ov;
; #pragma unroll
;             for (int j = 0; j < 4; ++j) { const float ga = __builtin_bit_cast(float, gv[i][j] << 16), gb = __builtin_bit_cast(float, gv[i][j] & 0xffff0000u);
;                 const float sa = ga * __builtin_amdgcn_rcpf(1.f + __expf(-ga)), sb = gb * __builtin_amdgcn_rcpf(1.f + __expf(-gb));
;                 ov[j] = pk2(yv[2 * j] * rstd * gnv[2 * j] * sa, yv[2 * j + 1] * rstd * gnv[2 * j + 1] * sb); }
;             *(v4u*)(MIXc + (size_t)(wid * 32 + row) * 1024 + c0) = ov;
	v_lshlrev_b32_e32 v3, 16, v35
	v_mul_f32_e32 v48, 0xbfb8aa3b, v3
	v_cndmask_b32_e32 v2, v54, v2, vcc
	v_rsq_f32_e32 v50, v2
	v_lshlrev_b32_e32 v2, 16, v34
	v_and_b32_e32 v34, 0xffff0000, v34
	v_mul_f32_e32 v47, 0xbfb8aa3b, v34
	v_mul_f32_e32 v46, 0xbfb8aa3b, v2
	v_exp_f32_e32 v47, v47
	v_exp_f32_e32 v46, v46
	v_and_b32_e32 v35, 0xffff0000, v35
	v_exp_f32_e32 v49, v48
	v_mul_f32_e32 v48, 0xbfb8aa3b, v35
	v_exp_f32_e32 v51, v48
	v_add_f32_e32 v47, 1.0, v47
	v_add_f32_e32 v46, 1.0, v46
	v_rcp_f32_e32 v48, v47
	v_add_f32_e32 v47, 1.0, v49
	v_rcp_f32_e32 v46, v46
	v_rcp_f32_e32 v47, v47
	v_add_f32_e32 v49, 1.0, v51
	v_rcp_f32_e32 v49, v49
	v_mul_f32_e32 v51, 0x45800000, v50
	v_cndmask_b32_e32 v50, v50, v51, vcc
	v_mul_f32_e32 v2, v46, v2
	v_mul_f32_e32 v3, v47, v3
	v_mov_b32_e32 v46, v58
	v_mov_b32_e32 v47, v60
	v_mul_f32_e32 v46, v46, v50
	v_mul_f32_e32 v47, v47, v50
	v_mul_f32_e32 v34, v48, v34
	v_mul_f32_e32 v35, v49, v35
	v_mul_f32_e32 v46, v40, v46
	v_mul_f32_e32 v47, v41, v47
	v_mov_b32_e32 v60, v59
	v_lshlrev_b32_e32 v48, 16, v36
	v_mul_f32_e32 v2, v2, v46
	v_mul_f32_e32 v3, v3, v47
	v_mul_f32_e32 v46, v60, v50
	v_mul_f32_e32 v47, v61, v50
	v_mul_f32_e32 v51, 0xbfb8aa3b, v48
	v_and_b32_e32 v36, 0xffff0000, v36
	v_exp_f32_e32 v51, v51
	v_mul_f32_e32 v53, 0xbfb8aa3b, v36
	v_exp_f32_e32 v53, v53
	v_lshlrev_b32_e32 v49, 16, v37
	v_add_f32_e32 v51, 1.0, v51
	v_rcp_f32_e32 v54, v51
	v_add_f32_e32 v51, 1.0, v53
	v_mul_f32_e32 v53, 0xbfb8aa3b, v49
	v_exp_f32_e32 v53, v53
	v_and_b32_e32 v37, 0xffff0000, v37
	v_mul_f32_e32 v55, 0xbfb8aa3b, v37
	v_exp_f32_e32 v57, v55
	v_rcp_f32_e32 v56, v51
	v_add_f32_e32 v51, 1.0, v53
	v_rcp_f32_e32 v55, v51
	v_add_f32_e32 v51, 1.0, v57
	v_mul_f32_e32 v46, v8, v46
	v_mul_f32_e32 v47, v9, v47
	v_rcp_f32_e32 v57, v51
	v_mul_f32_e32 v34, v34, v46
	v_mul_f32_e32 v35, v35, v47
	v_mul_f32_e32 v46, v54, v48
	v_mul_f32_e32 v47, v55, v49
	v_mov_b32_e32 v48, v62
	v_mov_b32_e32 v49, v64
	v_mul_f32_e32 v48, v48, v50
	v_mul_f32_e32 v49, v49, v50
	v_mov_b32_e32 v64, v63
	v_mul_f32_e32 v48, v6, v48
	v_mul_f32_e32 v49, v7, v49
	v_mul_f32_e32 v36, v56, v36
	v_mul_f32_e32 v37, v57, v37
	v_mul_f32_e32 v46, v46, v48
	v_mul_f32_e32 v47, v47, v49
	v_mul_f32_e32 v48, v64, v50
	v_mul_f32_e32 v49, v65, v50
	v_bfe_u32 v50, v35, 16, 1
	v_mul_f32_e32 v48, v4, v48
	v_mul_f32_e32 v49, v5, v49
	v_bfe_u32 v51, v34, 16, 1
	v_mul_f32_e32 v36, v36, v48
	v_mul_f32_e32 v37, v37, v49
	v_add3_u32 v34, v34, v51, s81
	v_bfe_u32 v48, v37, 16, 1
	v_bfe_u32 v49, v36, 16, 1
	v_add3_u32 v37, v37, v48, s81
	v_bfe_u32 v48, v2, 16, 1
	v_add3_u32 v36, v36, v49, s81
	v_bfe_u32 v49, v3, 16, 1
	v_add3_u32 v2, v2, v48, s81
	v_add3_u32 v35, v35, v50, s81
	v_bfe_u32 v50, v46, 16, 1
	v_bfe_u32 v51, v47, 16, 1
	v_add3_u32 v3, v3, v49, s81
	v_lshrrev_b32_e32 v2, 16, v2
	v_add3_u32 v47, v47, v51, s81
	v_add3_u32 v46, v46, v50, s81
	v_lshrrev_b32_e32 v3, 16, v3
	v_and_or_b32 v34, v34, s82, v2
	v_or_b32_e32 v2, v45, v119
	v_or_b32_e32 v45, 8, v52
	v_lshrrev_b32_e32 v46, 16, v46
	v_lshrrev_b32_e32 v47, 16, v47
	v_and_or_b32 v35, v35, s82, v3
	v_ashrrev_i32_e32 v3, 31, v2
	v_lshl_add_u32 v50, v45, 9, v44
	v_and_or_b32 v37, v37, s82, v47
	v_and_or_b32 v36, v36, s82, v46
	ds_read_b128 v[46:49], v50
	v_lshlrev_b64 v[2:3], 11, v[2:3]
	v_lshl_add_u64 v[2:3], v[38:39], 0, v[2:3]
	global_store_dwordx4 v[2:3], v[34:37], off
	ds_read_b128 v[34:37], v50 offset:16
	s_waitcnt lgkmcnt(1)
	v_mul_f32_e32 v2, v48, v48
	v_mul_f32_e32 v3, v49, v49
	v_mul_f32_e32 v50, v46, v46
	v_mul_f32_e32 v51, v47, v47
	s_waitcnt vmcnt(7)
	v_lshlrev_b32_e32 v58, 16, v30
	v_pk_mov_b32 v[54:55], v[50:51], v[2:3] op_sel:[1,0]
	v_mov_b32_e32 v51, v3
	v_add_f32_e32 v2, v54, v50
	v_add_f32_e32 v3, v55, v51
	s_waitcnt lgkmcnt(0)
	v_mul_f32_e32 v50, v36, v36
	v_mul_f32_e32 v51, v37, v37
	v_and_b32_e32 v30, 0xffff0000, v30
	v_mov_b32_e32 v56, v50
	v_mul_f32_e32 v50, 0xbfb8aa3b, v58
	v_exp_f32_e32 v50, v50
	v_mul_f32_e32 v53, 0xbfb8aa3b, v30
	v_exp_f32_e32 v53, v53
	v_lshlrev_b32_e32 v59, 16, v31
	v_add_f32_e32 v50, 1.0, v50
	v_mul_f32_e32 v54, v34, v34
	v_mul_f32_e32 v55, v35, v35
	v_rcp_f32_e32 v60, v50
	v_and_b32_e32 v31, 0xffff0000, v31
	v_add_f32_e32 v50, 1.0, v53
	v_mul_f32_e32 v53, 0xbfb8aa3b, v59
	v_mov_b32_e32 v57, v54
	v_exp_f32_e32 v53, v53
	v_mul_f32_e32 v54, 0xbfb8aa3b, v31
	v_exp_f32_e32 v54, v54
	v_rcp_f32_e32 v62, v50
	v_add_f32_e32 v50, 1.0, v53
	v_rcp_f32_e32 v61, v50
	v_add_f32_e32 v50, 1.0, v54
	v_rcp_f32_e32 v63, v50
	v_mov_b32_e32 v54, v51
	v_mul_f32_e32 v58, v60, v58
	v_mul_f32_e32 v59, v61, v59
	v_add_f32_e32 v50, v56, v54
	v_add_f32_e32 v51, v57, v55
	v_mul_f32_e32 v60, v62, v30
	v_mul_f32_e32 v61, v63, v31
	v_lshlrev_b32_e32 v30, 16, v32
	v_mov_b32_e32 v62, v46
	v_mul_f32_e32 v46, 0xbfb8aa3b, v30
	v_and_b32_e32 v32, 0xffff0000, v32
	v_exp_f32_e32 v46, v46
	v_mul_f32_e32 v53, 0xbfb8aa3b, v32
	v_exp_f32_e32 v53, v53
	v_lshlrev_b32_e32 v31, 16, v33
	v_add_f32_e32 v46, 1.0, v46
	v_rcp_f32_e32 v54, v46
	v_and_b32_e32 v33, 0xffff0000, v33
	v_add_f32_e32 v46, 1.0, v53
	v_mul_f32_e32 v53, 0xbfb8aa3b, v31
	v_exp_f32_e32 v53, v53
	v_mul_f32_e32 v55, 0xbfb8aa3b, v33
	v_exp_f32_e32 v57, v55
	v_rcp_f32_e32 v56, v46
	v_add_f32_e32 v46, 1.0, v53
	v_rcp_f32_e32 v55, v46
	v_add_f32_e32 v46, 1.0, v57
	v_rcp_f32_e32 v57, v46
	v_or_b32_e32 v53, 12, v52
	v_mov_b32_e32 v63, v48
	v_mov_b32_e32 v48, v47
	v_mul_f32_e32 v46, v54, v30
	v_mul_f32_e32 v47, v55, v31
	v_lshl_add_u32 v54, v53, 9, v44
	v_mul_f32_e32 v64, v56, v32
	v_mul_f32_e32 v65, v57, v33
	ds_read_b128 v[30:33], v54
	ds_read_b128 v[54:57], v54 offset:16
	v_mov_b32_e32 v67, v36
	v_mov_b32_e32 v36, v35
	v_mov_b32_e32 v66, v34
	s_waitcnt lgkmcnt(1)
; __device__ __forceinline__ unsigned pk2(float lo, float hi) { return f2bf(lo) | (f2bf(hi) << 16); }
; __device__ __forceinline__ void out_unit(const bf16* __restrict__ Qc, const bf16* __restrict__ Kc, const bf16* __restrict__ Vc, const float* __restrict__ ST, int c, ...
;     ...
;         for (int i = 0; i < 8; ++i) { const int row = i * 4 + rq;
;             const f32x4 y0 = *(const f32x4*)(stg + row * 128 + c0), y1 = *(const f32x4*)(stg + row * 128 + c0 + 4);
;             float ss = (y0.x * y0.x + y0.y * y0.y) + (y0.z * y0.z + y0.w * y0.w) + (y1.x * y1.x + y1.y * y1.y) + (y1.z * y1.z + y1.w * y1.w);
;             ss += __int_as_float(__builtin_amdgcn_update_dpp(0, __float_as_int(ss), 0xB1, 0xf, 0xf, true));
;             ss += __int_as_float(__builtin_amdgcn_update_dpp(0, __float_as_int(ss), 0x4E, 0xf, 0xf, true));
;             ss += __int_as_float(__builtin_amdgcn_update_dpp(0, __float_as_int(ss), 0x141, 0xf, 0xf, true));
;             ss += __int_as_float(__builtin_amdgcn_update_dpp(0, __float_as_int(ss), 0x140, 0xf, 0xf, true));
;             const float rstd = rsqrtf(ss * (1.f / 128.f) + 1e-6f);
;             float yv[8] = {y0.x, y0.y, y0.z, y0.w, y1.x, y1.y, y1.z, y1.w}; const float gnv[8] = {gn0.x, gn0.y, gn0.z, gn0.w, gn1.x, gn1.y, gn1.z, gn1.w};
;             v4u ov;
; #pragma unroll
;             for (int j = 0; j < 4; ++j) { const float ga = __builtin_bit_cast(float, gv[i][j] << 16), gb = __builtin_bit_cast(float, gv[i][j] & 0xffff0000u);
;                 const float sa = ga * __builtin_amdgcn_rcpf(1.f + __expf(-ga)), sb = gb * __builtin_amdgcn_rcpf(1.f + __expf(-gb));
;                 ov[j] = pk2(yv[2 * j] * rstd * gnv[2 * j] * sa, yv[2 * j + 1] * rstd * gnv[2 * j + 1] * sb); }
;             *(v4u*)(MIXc + (size_t)(wid * 32 + row) * 1024 + c0) = ov;
	v_mul_f32_e32 v68, v32, v32
	v_mul_f32_e32 v69, v33, v33
	v_mul_f32_e32 v70, v30, v30
	v_mul_f32_e32 v71, v31, v31
	v_or_b32_e32 v34, v45, v119
	v_pk_mov_b32 v[72:73], v[70:71], v[68:69] op_sel:[1,0]
	v_mov_b32_e32 v71, v69
	v_add_f32_e32 v68, v72, v70
	v_add_f32_e32 v69, v73, v71
	s_waitcnt lgkmcnt(0)
	v_mul_f32_e32 v70, v56, v56
	v_mul_f32_e32 v71, v57, v57
	v_mul_f32_e32 v72, v54, v54
	v_mul_f32_e32 v73, v55, v55
	v_mov_b32_e32 v74, v70
	v_mov_b32_e32 v75, v72
	v_mov_b32_e32 v72, v71
	v_add_f32_e32 v70, v74, v72
	v_add_f32_e32 v71, v75, v73
	v_mov_b32_e32 v72, v68
	v_mov_b32_e32 v73, v2
	v_mov_b32_e32 v2, v69
	v_add_f32_e32 v2, v72, v2
	v_add_f32_e32 v3, v73, v3
	v_mov_b32_e32 v68, v71
	v_mov_b32_e32 v69, v51
	v_add_f32_e32 v2, v2, v68
	v_add_f32_e32 v3, v3, v69
	v_mov_b32_e32 v71, v50
	v_add_f32_e32 v2, v70, v2
	v_add_f32_e32 v3, v71, v3
	s_nop 1
	v_mov_b32_dpp v51, v3 quad_perm:[1,0,3,2] row_mask:0xf bank_mask:0xf bound_ctrl:1
	v_mov_b32_dpp v50, v2 quad_perm:[1,0,3,2] row_mask:0xf bank_mask:0xf bound_ctrl:1
	v_add_f32_e32 v2, v2, v50
	v_add_f32_e32 v3, v3, v51
	s_nop 1
	v_mov_b32_dpp v51, v3 quad_perm:[2,3,0,1] row_mask:0xf bank_mask:0xf bound_ctrl:1
	v_mov_b32_dpp v50, v2 quad_perm:[2,3,0,1] row_mask:0xf bank_mask:0xf bound_ctrl:1
	v_add_f32_e32 v2, v2, v50
	v_add_f32_e32 v3, v3, v51
	s_nop 1
	v_mov_b32_dpp v51, v3 row_half_mirror row_mask:0xf bank_mask:0xf bound_ctrl:1
	v_mov_b32_dpp v50, v2 row_half_mirror row_mask:0xf bank_mask:0xf bound_ctrl:1
	v_add_f32_e32 v2, v2, v50
	v_add_f32_e32 v3, v3, v51
	s_nop 1
	v_mov_b32_dpp v51, v3 row_mirror row_mask:0xf bank_mask:0xf bound_ctrl:1
	v_mov_b32_dpp v50, v2 row_mirror row_mask:0xf bank_mask:0xf bound_ctrl:1
	v_add_f32_e32 v2, v2, v50
	v_add_f32_e32 v3, v3, v51
	s_nop 0
	v_fma_f32 v2, v2, s46, v42
	v_fma_f32 v3, v3, s46, v42
	s_nop 0
	v_mul_f32_e32 v35, 0x4b800000, v3
	v_cmp_gt_f32_e32 vcc, s74, v3
	s_nop 1
	v_cndmask_b32_e32 v3, v3, v35, vcc
	v_rsq_f32_e32 v3, v3
	v_ashrrev_i32_e32 v35, 31, v34
	v_lshlrev_b64 v[34:35], 11, v[34:35]
	v_lshl_add_u64 v[50:51], v[38:39], 0, v[34:35]
	v_mul_f32_e32 v34, 0x45800000, v3
	v_cndmask_b32_e32 v34, v3, v34, vcc
	v_mul_f32_e32 v48, v48, v34
	v_mul_f32_e32 v49, v49, v34
	v_mul_f32_e32 v62, v62, v34
	v_mul_f32_e32 v63, v63, v34
	v_mul_f32_e32 v48, v8, v48
	v_mul_f32_e32 v49, v9, v49
	v_mul_f32_e32 v62, v40, v62
	v_mul_f32_e32 v63, v41, v63
	v_mul_f32_e32 v48, v60, v48
	v_mul_f32_e32 v49, v61, v49
	v_mul_f32_e32 v60, v66, v34
	v_mul_f32_e32 v61, v67, v34
	v_mul_f32_e32 v35, v37, v34
	v_mul_f32_e32 v34, v36, v34
	v_mul_f32_e32 v60, v6, v60
	v_mul_f32_e32 v61, v7, v61
	v_mul_f32_e32 v34, v4, v34
	v_mul_f32_e32 v35, v5, v35
	v_mul_f32_e32 v58, v58, v62
	v_mul_f32_e32 v59, v59, v63
	v_mul_f32_e32 v34, v64, v34
	v_mul_f32_e32 v35, v65, v35
	v_mul_f32_e32 v46, v46, v60
	v_mul_f32_e32 v47, v47, v61
	v_bfe_u32 v3, v35, 16, 1
	v_bfe_u32 v36, v34, 16, 1
	v_bfe_u32 v37, v49, 16, 1
	v_bfe_u32 v45, v48, 16, 1
	v_add3_u32 v45, v48, v45, s81
	v_add3_u32 v48, v49, v37, s81
	v_add3_u32 v34, v34, v36, s81
	v_add3_u32 v3, v35, v3, s81
	v_bfe_u32 v35, v58, 16, 1
	v_bfe_u32 v36, v59, 16, 1
	v_bfe_u32 v37, v46, 16, 1
	v_bfe_u32 v49, v47, 16, 1
	v_add3_u32 v47, v47, v49, s81
	v_add3_u32 v37, v46, v37, s81
	v_add3_u32 v36, v59, v36, s81
	v_add3_u32 v35, v58, v35, s81
	v_lshrrev_b32_e32 v46, 16, v35
	v_lshrrev_b32_e32 v35, 16, v36
	v_lshrrev_b32_e32 v36, 16, v37
	v_lshrrev_b32_e32 v37, 16, v47
	v_and_or_b32 v37, v3, s82, v37
	v_mul_f32_e32 v3, 0x4b800000, v2
	v_cmp_gt_f32_e32 vcc, s74, v2
	v_and_or_b32 v36, v34, s82, v36
	v_and_or_b32 v35, v48, s82, v35
	v_cndmask_b32_e32 v2, v2, v3, vcc
	v_and_or_b32 v34, v45, s82, v46
	v_rsq_f32_e32 v45, v2
	s_waitcnt vmcnt(6)
	v_lshlrev_b32_e32 v2, 16, v26
	v_and_b32_e32 v26, 0xffff0000, v26
	global_store_dwordx4 v[50:51], v[34:37], off
	v_lshlrev_b32_e32 v3, 16, v27
	v_and_b32_e32 v27, 0xffff0000, v27
	v_mul_f32_e32 v35, 0xbfb8aa3b, v26
	v_mul_f32_e32 v34, 0xbfb8aa3b, v2
	v_exp_f32_e32 v35, v35
	v_mul_f32_e32 v36, 0xbfb8aa3b, v3
	v_exp_f32_e32 v34, v34
	v_exp_f32_e32 v37, v36
	v_add_f32_e32 v35, 1.0, v35
	v_mul_f32_e32 v36, 0xbfb8aa3b, v27
	v_add_f32_e32 v34, 1.0, v34
	v_exp_f32_e32 v46, v36
	v_rcp_f32_e32 v36, v35
	v_add_f32_e32 v35, 1.0, v37
	v_rcp_f32_e32 v34, v34
	v_rcp_f32_e32 v35, v35
	v_add_f32_e32 v37, 1.0, v46
	v_mul_f32_e32 v46, 0x45800000, v45
	v_rcp_f32_e32 v37, v37
	v_cndmask_b32_e32 v46, v45, v46, vcc
	v_mul_f32_e32 v2, v34, v2
	v_mul_f32_e32 v3, v35, v3
	v_mov_b32_e32 v34, v30
	v_mov_b32_e32 v35, v32
	v_mul_f32_e32 v34, v34, v46
	v_mul_f32_e32 v35, v35, v46
	v_mov_b32_e32 v32, v31
	v_mul_f32_e32 v34, v40, v34
	v_mul_f32_e32 v35, v41, v35
	v_mul_f32_e32 v30, v32, v46
	v_mul_f32_e32 v31, v33, v46
	v_lshlrev_b32_e32 v32, 16, v28
	v_and_b32_e32 v28, 0xffff0000, v28
	v_mul_f32_e32 v2, v2, v34
	v_mul_f32_e32 v3, v3, v35
	v_lshlrev_b32_e32 v33, 16, v29
	v_mul_f32_e32 v35, 0xbfb8aa3b, v28
	v_mul_f32_e32 v26, v36, v26
	v_mul_f32_e32 v27, v37, v27
	v_mul_f32_e32 v34, 0xbfb8aa3b, v32
	v_exp_f32_e32 v35, v35
	v_mul_f32_e32 v36, 0xbfb8aa3b, v33
	v_exp_f32_e32 v34, v34
	v_exp_f32_e32 v37, v36
	v_and_b32_e32 v29, 0xffff0000, v29
	v_add_f32_e32 v35, 1.0, v35
	v_mul_f32_e32 v36, 0xbfb8aa3b, v29
	v_add_f32_e32 v34, 1.0, v34
	v_exp_f32_e32 v45, v36
	v_rcp_f32_e32 v36, v35
	v_add_f32_e32 v35, 1.0, v37
	v_rcp_f32_e32 v34, v34
	v_rcp_f32_e32 v35, v35
	v_add_f32_e32 v37, 1.0, v45
	v_mul_f32_e32 v30, v8, v30
	v_mul_f32_e32 v31, v9, v31
	v_rcp_f32_e32 v37, v37
	v_mul_f32_e32 v26, v26, v30
	v_mul_f32_e32 v27, v27, v31
	v_mul_f32_e32 v30, v34, v32
	v_mul_f32_e32 v31, v35, v33
	v_mov_b32_e32 v32, v54
	v_mov_b32_e32 v33, v56
	v_mul_f32_e32 v32, v32, v46
; __device__ __forceinline__ unsigned pk2(float lo, float hi) { return f2bf(lo) | (f2bf(hi) << 16); }
; __device__ __forceinline__ void out_unit(const bf16* __restrict__ Qc, const bf16* __restrict__ Kc, const bf16* __restrict__ Vc, const float* __restrict__ ST, int c, ...
;     ...
;         for (int i = 0; i < 8; ++i) { const int row = i * 4 + rq;
;             const f32x4 y0 = *(const f32x4*)(stg + row * 128 + c0), y1 = *(const f32x4*)(stg + row * 128 + c0 + 4);
;             float ss = (y0.x * y0.x + y0.y * y0.y) + (y0.z * y0.z + y0.w * y0.w) + (y1.x * y1.x + y1.y * y1.y) + (y1.z * y1.z + y1.w * y1.w);
;             ss += __int_as_float(__builtin_amdgcn_update_dpp(0, __float_as_int(ss), 0xB1, 0xf, 0xf, true));
;             ss += __int_as_float(__builtin_amdgcn_update_dpp(0, __float_as_int(ss), 0x4E, 0xf, 0xf, true));
;             ss += __int_as_float(__builtin_amdgcn_update_dpp(0, __float_as_int(ss), 0x141, 0xf, 0xf, true));
;             ss += __int_as_float(__builtin_amdgcn_update_dpp(0, __float_as_int(ss), 0x140, 0xf, 0xf, true));
;             const float rstd = rsqrtf(ss * (1.f / 128.f) + 1e-6f);
;             float yv[8] = {y0.x, y0.y, y0.z, y0.w, y1.x, y1.y, y1.z, y1.w}; const float gnv[8] = {gn0.x, gn0.y, gn0.z, gn0.w, gn1.x, gn1.y, gn1.z, gn1.w};
;             v4u ov;
; #pragma unroll
;             for (int j = 0; j < 4; ++j) { const float ga = __builtin_bit_cast(float, gv[i][j] << 16), gb = __builtin_bit_cast(float, gv[i][j] & 0xffff0000u);
;                 const float sa = ga * __builtin_amdgcn_rcpf(1.f + __expf(-ga)), sb = gb * __builtin_amdgcn_rcpf(1.f + __expf(-gb));
;                 ov[j] = pk2(yv[2 * j] * rstd * gnv[2 * j] * sa, yv[2 * j + 1] * rstd * gnv[2 * j + 1] * sb); }
;             *(v4u*)(MIXc + (size_t)(wid * 32 + row) * 1024 + c0) = ov;
	v_mul_f32_e32 v33, v33, v46
	v_mov_b32_e32 v56, v55
	v_mul_f32_e32 v32, v6, v32
	v_mul_f32_e32 v33, v7, v33
	v_mul_f32_e32 v28, v36, v28
	v_mul_f32_e32 v29, v37, v29
	v_mul_f32_e32 v30, v30, v32
	v_mul_f32_e32 v31, v31, v33
	v_mul_f32_e32 v32, v56, v46
	v_mul_f32_e32 v33, v57, v46
	v_bfe_u32 v34, v27, 16, 1
	v_mul_f32_e32 v32, v4, v32
	v_mul_f32_e32 v33, v5, v33
	v_bfe_u32 v35, v26, 16, 1
	v_mul_f32_e32 v28, v28, v32
	v_mul_f32_e32 v29, v29, v33
	v_add3_u32 v26, v26, v35, s81
	v_bfe_u32 v32, v29, 16, 1
	v_bfe_u32 v33, v28, 16, 1
	v_add3_u32 v29, v29, v32, s81
	v_bfe_u32 v32, v2, 16, 1
	v_add3_u32 v28, v28, v33, s81
	v_bfe_u32 v33, v3, 16, 1
	v_add3_u32 v2, v2, v32, s81
	v_add3_u32 v27, v27, v34, s81
	v_bfe_u32 v34, v30, 16, 1
	v_bfe_u32 v35, v31, 16, 1
	v_add3_u32 v3, v3, v33, s81
	v_lshrrev_b32_e32 v2, 16, v2
	v_add3_u32 v31, v31, v35, s81
	v_add3_u32 v30, v30, v34, s81
	v_lshrrev_b32_e32 v3, 16, v3
	v_and_or_b32 v26, v26, s82, v2
	v_or_b32_e32 v2, v53, v119
	v_or_b32_e32 v45, 16, v52
	v_lshrrev_b32_e32 v30, 16, v30
	v_lshrrev_b32_e32 v31, 16, v31
	v_and_or_b32 v27, v27, s82, v3
	v_ashrrev_i32_e32 v3, 31, v2
	v_lshl_add_u32 v34, v45, 9, v44
	v_and_or_b32 v29, v29, s82, v31
	v_and_or_b32 v28, v28, s82, v30
	ds_read_b128 v[30:33], v34
	v_lshlrev_b64 v[2:3], 11, v[2:3]
	v_lshl_add_u64 v[2:3], v[38:39], 0, v[2:3]
	global_store_dwordx4 v[2:3], v[26:29], off
	ds_read_b128 v[26:29], v34 offset:16
	s_waitcnt lgkmcnt(1)
	v_mul_f32_e32 v2, v32, v32
	v_mul_f32_e32 v3, v33, v33
	v_mul_f32_e32 v34, v30, v30
	v_mul_f32_e32 v35, v31, v31
	s_waitcnt vmcnt(7)
	v_lshlrev_b32_e32 v48, 16, v22
	v_pk_mov_b32 v[36:37], v[34:35], v[2:3] op_sel:[1,0]
	v_mov_b32_e32 v35, v3
	v_add_f32_e32 v2, v36, v34
	v_add_f32_e32 v3, v37, v35
	s_waitcnt lgkmcnt(0)
	v_mul_f32_e32 v34, v28, v28
	v_mul_f32_e32 v35, v29, v29
	v_mul_f32_e32 v36, v26, v26
	v_mul_f32_e32 v37, v27, v27
	v_mov_b32_e32 v46, v34
	v_mul_f32_e32 v34, 0xbfb8aa3b, v48
	v_and_b32_e32 v22, 0xffff0000, v22
	v_mov_b32_e32 v47, v36
	v_exp_f32_e32 v34, v34
	v_mul_f32_e32 v36, 0xbfb8aa3b, v22
	v_exp_f32_e32 v36, v36
	v_lshlrev_b32_e32 v49, 16, v23
	v_add_f32_e32 v34, 1.0, v34
	v_rcp_f32_e32 v50, v34
	v_and_b32_e32 v23, 0xffff0000, v23
	v_add_f32_e32 v34, 1.0, v36
	v_mul_f32_e32 v36, 0xbfb8aa3b, v49
	v_exp_f32_e32 v36, v36
	v_mul_f32_e32 v51, 0xbfb8aa3b, v23
	v_exp_f32_e32 v53, v51
	v_rcp_f32_e32 v54, v34
	v_add_f32_e32 v34, 1.0, v36
	v_rcp_f32_e32 v51, v34
	v_add_f32_e32 v34, 1.0, v53
	v_rcp_f32_e32 v55, v34
	v_mov_b32_e32 v36, v35
	v_mul_f32_e32 v48, v50, v48
	v_mul_f32_e32 v49, v51, v49
	v_add_f32_e32 v46, v46, v36
	v_add_f32_e32 v47, v47, v37
	v_mul_f32_e32 v50, v54, v22
	v_mul_f32_e32 v51, v55, v23
	v_lshlrev_b32_e32 v22, 16, v24
	v_mov_b32_e32 v54, v30
	v_mul_f32_e32 v30, 0xbfb8aa3b, v22
	v_and_b32_e32 v24, 0xffff0000, v24
	v_exp_f32_e32 v30, v30
	v_mul_f32_e32 v34, 0xbfb8aa3b, v24
	v_exp_f32_e32 v35, v34
	v_lshlrev_b32_e32 v23, 16, v25
	v_add_f32_e32 v30, 1.0, v30
	v_rcp_f32_e32 v34, v30
	v_and_b32_e32 v25, 0xffff0000, v25
	v_add_f32_e32 v30, 1.0, v35
	v_mul_f32_e32 v35, 0xbfb8aa3b, v23
	v_exp_f32_e32 v35, v35
	v_mul_f32_e32 v36, 0xbfb8aa3b, v25
	v_exp_f32_e32 v37, v36
	v_rcp_f32_e32 v36, v30
	v_add_f32_e32 v30, 1.0, v35
	v_rcp_f32_e32 v35, v30
	v_add_f32_e32 v30, 1.0, v37
	v_rcp_f32_e32 v37, v30
	v_or_b32_e32 v53, 20, v52
	v_mov_b32_e32 v55, v32
	v_mov_b32_e32 v32, v31
	v_mul_f32_e32 v30, v34, v22
	v_mul_f32_e32 v31, v35, v23
	v_lshl_add_u32 v34, v53, 9, v44
	v_mul_f32_e32 v56, v36, v24
	v_mul_f32_e32 v57, v37, v25
	ds_read_b128 v[22:25], v34
	ds_read_b128 v[34:37], v34 offset:16
	v_mov_b32_e32 v59, v28
	v_mov_b32_e32 v28, v27
	v_mov_b32_e32 v58, v26
	s_waitcnt lgkmcnt(1)
	v_mul_f32_e32 v60, v24, v24
	v_mul_f32_e32 v61, v25, v25
	v_mul_f32_e32 v62, v22, v22
	v_mul_f32_e32 v63, v23, v23
	v_or_b32_e32 v26, v45, v119
	v_pk_mov_b32 v[64:65], v[62:63], v[60:61] op_sel:[1,0]
	v_mov_b32_e32 v63, v61
	v_add_f32_e32 v60, v64, v62
	v_add_f32_e32 v61, v65, v63
	s_waitcnt lgkmcnt(0)
	v_mul_f32_e32 v62, v36, v36
	v_mul_f32_e32 v63, v37, v37
	v_mul_f32_e32 v64, v34, v34
	v_mul_f32_e32 v65, v35, v35
	v_mov_b32_e32 v66, v62
	v_mov_b32_e32 v67, v64
	v_mov_b32_e32 v64, v63
	v_add_f32_e32 v62, v66, v64
	v_add_f32_e32 v63, v67, v65
	v_mov_b32_e32 v64, v60
	v_mov_b32_e32 v65, v2
	v_mov_b32_e32 v2, v61
	v_add_f32_e32 v2, v64, v2
	v_add_f32_e32 v3, v65, v3
	v_mov_b32_e32 v60, v63
	v_mov_b32_e32 v61, v47
	v_add_f32_e32 v2, v2, v60
	v_add_f32_e32 v3, v3, v61
	v_mov_b32_e32 v63, v46
	v_add_f32_e32 v2, v62, v2
	v_add_f32_e32 v3, v63, v3
	s_nop 1
	v_mov_b32_dpp v47, v3 quad_perm:[1,0,3,2] row_mask:0xf bank_mask:0xf bound_ctrl:1
	v_mov_b32_dpp v46, v2 quad_perm:[1,0,3,2] row_mask:0xf bank_mask:0xf bound_ctrl:1
	v_add_f32_e32 v2, v2, v46
	v_add_f32_e32 v3, v3, v47
	s_nop 1
	v_mov_b32_dpp v47, v3 quad_perm:[2,3,0,1] row_mask:0xf bank_mask:0xf bound_ctrl:1
	v_mov_b32_dpp v46, v2 quad_perm:[2,3,0,1] row_mask:0xf bank_mask:0xf bound_ctrl:1
	v_add_f32_e32 v2, v2, v46
	v_add_f32_e32 v3, v3, v47
	s_nop 1
	v_mov_b32_dpp v47, v3 row_half_mirror row_mask:0xf bank_mask:0xf bound_ctrl:1
	v_mov_b32_dpp v46, v2 row_half_mirror row_mask:0xf bank_mask:0xf bound_ctrl:1
	v_add_f32_e32 v2, v2, v46
	v_add_f32_e32 v3, v3, v47
	s_nop 1
	v_mov_b32_dpp v47, v3 row_mirror row_mask:0xf bank_mask:0xf bound_ctrl:1
	v_mov_b32_dpp v46, v2 row_mirror row_mask:0xf bank_mask:0xf bound_ctrl:1
	v_add_f32_e32 v2, v2, v46
	v_add_f32_e32 v3, v3, v47
	s_nop 0
	v_fma_f32 v2, v2, s46, v42
	v_fma_f32 v3, v3, s46, v42
	s_nop 0
	v_mul_f32_e32 v27, 0x4b800000, v3
	v_cmp_gt_f32_e32 vcc, s74, v3
	s_nop 1
	v_cndmask_b32_e32 v3, v3, v27, vcc
	v_rsq_f32_e32 v3, v3
; __device__ __forceinline__ unsigned pk2(float lo, float hi) { return f2bf(lo) | (f2bf(hi) << 16); }
; __device__ __forceinline__ void out_unit(const bf16* __restrict__ Qc, const bf16* __restrict__ Kc, const bf16* __restrict__ Vc, const float* __restrict__ ST, int c, ...
;     ...
;         for (int i = 0; i < 8; ++i) { const int row = i * 4 + rq;
;             const f32x4 y0 = *(const f32x4*)(stg + row * 128 + c0), y1 = *(const f32x4*)(stg + row * 128 + c0 + 4);
;             float ss = (y0.x * y0.x + y0.y * y0.y) + (y0.z * y0.z + y0.w * y0.w) + (y1.x * y1.x + y1.y * y1.y) + (y1.z * y1.z + y1.w * y1.w);
;             ss += __int_as_float(__builtin_amdgcn_update_dpp(0, __float_as_int(ss), 0xB1, 0xf, 0xf, true));
;             ss += __int_as_float(__builtin_amdgcn_update_dpp(0, __float_as_int(ss), 0x4E, 0xf, 0xf, true));
;             ss += __int_as_float(__builtin_amdgcn_update_dpp(0, __float_as_int(ss), 0x141, 0xf, 0xf, true));
;             ss += __int_as_float(__builtin_amdgcn_update_dpp(0, __float_as_int(ss), 0x140, 0xf, 0xf, true));
;             const float rstd = rsqrtf(ss * (1.f / 128.f) + 1e-6f);
;             float yv[8] = {y0.x, y0.y, y0.z, y0.w, y1.x, y1.y, y1.z, y1.w}; const float gnv[8] = {gn0.x, gn0.y, gn0.z, gn0.w, gn1.x, gn1.y, gn1.z, gn1.w};
;             v4u ov;
; #pragma unroll
;             for (int j = 0; j < 4; ++j) { const float ga = __builtin_bit_cast(float, gv[i][j] << 16), gb = __builtin_bit_cast(float, gv[i][j] & 0xffff0000u);
;                 const float sa = ga * __builtin_amdgcn_rcpf(1.f + __expf(-ga)), sb = gb * __builtin_amdgcn_rcpf(1.f + __expf(-gb));
;                 ov[j] = pk2(yv[2 * j] * rstd * gnv[2 * j] * sa, yv[2 * j + 1] * rstd * gnv[2 * j + 1] * sb); }
;             *(v4u*)(MIXc + (size_t)(wid * 32 + row) * 1024 + c0) = ov;
	v_ashrrev_i32_e32 v27, 31, v26
	v_lshlrev_b64 v[26:27], 11, v[26:27]
	v_lshl_add_u64 v[46:47], v[38:39], 0, v[26:27]
	v_mul_f32_e32 v26, 0x45800000, v3
	v_cndmask_b32_e32 v26, v3, v26, vcc
	v_mul_f32_e32 v32, v32, v26
	v_mul_f32_e32 v33, v33, v26
	v_mul_f32_e32 v54, v54, v26
	v_mul_f32_e32 v55, v55, v26
	v_mul_f32_e32 v32, v8, v32
	v_mul_f32_e32 v33, v9, v33
	v_mul_f32_e32 v54, v40, v54
	v_mul_f32_e32 v55, v41, v55
	v_mul_f32_e32 v32, v50, v32
	v_mul_f32_e32 v33, v51, v33
	v_mul_f32_e32 v50, v58, v26
	v_mul_f32_e32 v51, v59, v26
	v_mul_f32_e32 v27, v29, v26
	v_mul_f32_e32 v26, v28, v26
	v_mul_f32_e32 v50, v6, v50
	v_mul_f32_e32 v51, v7, v51
	v_mul_f32_e32 v26, v4, v26
	v_mul_f32_e32 v27, v5, v27
	v_mul_f32_e32 v48, v48, v54
	v_mul_f32_e32 v49, v49, v55
	v_mul_f32_e32 v26, v56, v26
	v_mul_f32_e32 v27, v57, v27
	v_mul_f32_e32 v30, v30, v50
	v_mul_f32_e32 v31, v31, v51
	v_bfe_u32 v3, v27, 16, 1
	v_bfe_u32 v28, v26, 16, 1
	v_bfe_u32 v29, v33, 16, 1
	v_bfe_u32 v45, v32, 16, 1
	v_add3_u32 v32, v32, v45, s81
	v_add3_u32 v33, v33, v29, s81
	v_add3_u32 v26, v26, v28, s81
	v_add3_u32 v3, v27, v3, s81
	v_bfe_u32 v27, v48, 16, 1
	v_bfe_u32 v28, v49, 16, 1
	v_bfe_u32 v29, v30, 16, 1
	v_bfe_u32 v45, v31, 16, 1
	v_add3_u32 v31, v31, v45, s81
	v_add3_u32 v29, v30, v29, s81
	v_add3_u32 v28, v49, v28, s81
	v_add3_u32 v27, v48, v27, s81
	v_lshrrev_b32_e32 v30, 16, v27
	v_lshrrev_b32_e32 v27, 16, v28
	v_lshrrev_b32_e32 v28, 16, v29
	v_lshrrev_b32_e32 v29, 16, v31
	v_and_or_b32 v29, v3, s82, v29
	v_mul_f32_e32 v3, 0x4b800000, v2
	v_cmp_gt_f32_e32 vcc, s74, v2
	v_and_or_b32 v28, v26, s82, v28
	v_and_or_b32 v27, v33, s82, v27
	v_cndmask_b32_e32 v2, v2, v3, vcc
	v_and_or_b32 v26, v32, s82, v30
	v_rsq_f32_e32 v30, v2
	s_waitcnt vmcnt(6)
	v_lshlrev_b32_e32 v2, 16, v18
	v_and_b32_e32 v18, 0xffff0000, v18
	global_store_dwordx4 v[46:47], v[26:29], off
	v_lshlrev_b32_e32 v3, 16, v19
	v_and_b32_e32 v19, 0xffff0000, v19
	v_mul_f32_e32 v27, 0xbfb8aa3b, v18
	v_mul_f32_e32 v26, 0xbfb8aa3b, v2
	v_exp_f32_e32 v27, v27
	v_mul_f32_e32 v28, 0xbfb8aa3b, v3
	v_exp_f32_e32 v26, v26
	v_exp_f32_e32 v29, v28
	v_add_f32_e32 v27, 1.0, v27
	v_mul_f32_e32 v28, 0xbfb8aa3b, v19
	v_add_f32_e32 v26, 1.0, v26
	v_exp_f32_e32 v31, v28
	v_rcp_f32_e32 v28, v27
	v_add_f32_e32 v27, 1.0, v29
	v_rcp_f32_e32 v26, v26
	v_rcp_f32_e32 v27, v27
	v_add_f32_e32 v29, 1.0, v31
	v_mul_f32_e32 v31, 0x45800000, v30
	v_rcp_f32_e32 v29, v29
	v_cndmask_b32_e32 v30, v30, v31, vcc
	v_mul_f32_e32 v2, v26, v2
	v_mul_f32_e32 v3, v27, v3
	v_mov_b32_e32 v26, v22
	v_mov_b32_e32 v27, v24
	v_mul_f32_e32 v26, v26, v30
	v_mul_f32_e32 v27, v27, v30
	v_mov_b32_e32 v24, v23
	v_mul_f32_e32 v26, v40, v26
	v_mul_f32_e32 v27, v41, v27
	v_mul_f32_e32 v22, v24, v30
	v_mul_f32_e32 v23, v25, v30
	v_lshlrev_b32_e32 v24, 16, v20
	v_and_b32_e32 v20, 0xffff0000, v20
	v_mul_f32_e32 v2, v2, v26
	v_mul_f32_e32 v3, v3, v27
	v_lshlrev_b32_e32 v25, 16, v21
	v_mul_f32_e32 v27, 0xbfb8aa3b, v20
	v_mul_f32_e32 v18, v28, v18
	v_mul_f32_e32 v19, v29, v19
	v_mul_f32_e32 v26, 0xbfb8aa3b, v24
	v_exp_f32_e32 v27, v27
	v_mul_f32_e32 v28, 0xbfb8aa3b, v25
	v_exp_f32_e32 v26, v26
	v_exp_f32_e32 v29, v28
	v_and_b32_e32 v21, 0xffff0000, v21
	v_add_f32_e32 v27, 1.0, v27
	v_mul_f32_e32 v28, 0xbfb8aa3b, v21
	v_add_f32_e32 v26, 1.0, v26
	v_exp_f32_e32 v31, v28
	v_rcp_f32_e32 v28, v27
	v_add_f32_e32 v27, 1.0, v29
	v_rcp_f32_e32 v26, v26
	v_rcp_f32_e32 v27, v27
	v_add_f32_e32 v29, 1.0, v31
	v_mul_f32_e32 v22, v8, v22
	v_mul_f32_e32 v23, v9, v23
	v_rcp_f32_e32 v29, v29
	v_mul_f32_e32 v18, v18, v22
	v_mul_f32_e32 v19, v19, v23
	v_mul_f32_e32 v22, v26, v24
	v_mul_f32_e32 v23, v27, v25
	v_mov_b32_e32 v24, v34
	v_mov_b32_e32 v25, v36
	v_mul_f32_e32 v24, v24, v30
	v_mul_f32_e32 v25, v25, v30
	v_mov_b32_e32 v36, v35
	v_mul_f32_e32 v24, v6, v24
	v_mul_f32_e32 v25, v7, v25
	v_mul_f32_e32 v20, v28, v20
	v_mul_f32_e32 v21, v29, v21
	v_mul_f32_e32 v22, v22, v24
	v_mul_f32_e32 v23, v23, v25
	v_mul_f32_e32 v24, v36, v30
	v_mul_f32_e32 v25, v37, v30
	v_bfe_u32 v26, v19, 16, 1
	v_mul_f32_e32 v24, v4, v24
	v_mul_f32_e32 v25, v5, v25
	v_bfe_u32 v27, v18, 16, 1
	v_mul_f32_e32 v20, v20, v24
	v_mul_f32_e32 v21, v21, v25
	v_add3_u32 v18, v18, v27, s81
	v_bfe_u32 v24, v21, 16, 1
	v_bfe_u32 v25, v20, 16, 1
	v_add3_u32 v21, v21, v24, s81
	v_bfe_u32 v24, v2, 16, 1
	v_add3_u32 v20, v20, v25, s81
	v_bfe_u32 v25, v3, 16, 1
	v_add3_u32 v2, v2, v24, s81
	v_add3_u32 v19, v19, v26, s81
	v_bfe_u32 v26, v22, 16, 1
	v_bfe_u32 v27, v23, 16, 1
	v_add3_u32 v3, v3, v25, s81
	v_lshrrev_b32_e32 v2, 16, v2
	v_add3_u32 v23, v23, v27, s81
	v_add3_u32 v22, v22, v26, s81
	v_lshrrev_b32_e32 v3, 16, v3
	v_and_or_b32 v18, v18, s82, v2
	v_or_b32_e32 v2, v53, v119
	v_or_b32_e32 v45, 24, v52
	v_lshrrev_b32_e32 v22, 16, v22
	v_lshrrev_b32_e32 v23, 16, v23
	v_and_or_b32 v19, v19, s82, v3
	v_ashrrev_i32_e32 v3, 31, v2
	v_lshl_add_u32 v26, v45, 9, v44
	v_and_or_b32 v21, v21, s82, v23
	v_and_or_b32 v20, v20, s82, v22
	ds_read_b128 v[22:25], v26
	v_lshlrev_b64 v[2:3], 11, v[2:3]
	v_lshl_add_u64 v[2:3], v[38:39], 0, v[2:3]
	global_store_dwordx4 v[2:3], v[18:21], off
	ds_read_b128 v[18:21], v26 offset:16
	s_waitcnt lgkmcnt(1)
	v_mul_f32_e32 v2, v24, v24
	v_mul_f32_e32 v3, v25, v25
	v_mul_f32_e32 v26, v22, v22
	v_mul_f32_e32 v27, v23, v23
	s_waitcnt vmcnt(7)
	v_lshlrev_b32_e32 v32, 16, v14
	v_pk_mov_b32 v[28:29], v[26:27], v[2:3] op_sel:[1,0]
	v_mov_b32_e32 v27, v3
	v_add_f32_e32 v2, v28, v26
	v_add_f32_e32 v3, v29, v27
	s_waitcnt lgkmcnt(0)
; __device__ __forceinline__ unsigned pk2(float lo, float hi) { return f2bf(lo) | (f2bf(hi) << 16); }
; __device__ __forceinline__ void out_unit(const bf16* __restrict__ Qc, const bf16* __restrict__ Kc, const bf16* __restrict__ Vc, const float* __restrict__ ST, int c, ...
;     ...
;         for (int i = 0; i < 8; ++i) { const int row = i * 4 + rq;
;             const f32x4 y0 = *(const f32x4*)(stg + row * 128 + c0), y1 = *(const f32x4*)(stg + row * 128 + c0 + 4);
;             float ss = (y0.x * y0.x + y0.y * y0.y) + (y0.z * y0.z + y0.w * y0.w) + (y1.x * y1.x + y1.y * y1.y) + (y1.z * y1.z + y1.w * y1.w);
;             ss += __int_as_float(__builtin_amdgcn_update_dpp(0, __float_as_int(ss), 0xB1, 0xf, 0xf, true));
;             ss += __int_as_float(__builtin_amdgcn_update_dpp(0, __float_as_int(ss), 0x4E, 0xf, 0xf, true));
;             ss += __int_as_float(__builtin_amdgcn_update_dpp(0, __float_as_int(ss), 0x141, 0xf, 0xf, true));
;             ss += __int_as_float(__builtin_amdgcn_update_dpp(0, __float_as_int(ss), 0x140, 0xf, 0xf, true));
;             const float rstd = rsqrtf(ss * (1.f / 128.f) + 1e-6f);
;             float yv[8] = {y0.x, y0.y, y0.z, y0.w, y1.x, y1.y, y1.z, y1.w}; const float gnv[8] = {gn0.x, gn0.y, gn0.z, gn0.w, gn1.x, gn1.y, gn1.z, gn1.w};
;             v4u ov;
; #pragma unroll
;             for (int j = 0; j < 4; ++j) { const float ga = __builtin_bit_cast(float, gv[i][j] << 16), gb = __builtin_bit_cast(float, gv[i][j] & 0xffff0000u);
;                 const float sa = ga * __builtin_amdgcn_rcpf(1.f + __expf(-ga)), sb = gb * __builtin_amdgcn_rcpf(1.f + __expf(-gb));
;                 ov[j] = pk2(yv[2 * j] * rstd * gnv[2 * j] * sa, yv[2 * j + 1] * rstd * gnv[2 * j + 1] * sb); }
;             *(v4u*)(MIXc + (size_t)(wid * 32 + row) * 1024 + c0) = ov;
	v_mul_f32_e32 v26, v20, v20
	v_mul_f32_e32 v27, v21, v21
	v_mul_f32_e32 v28, v18, v18
	v_mul_f32_e32 v29, v19, v19
	v_mov_b32_e32 v30, v26
	v_mul_f32_e32 v26, 0xbfb8aa3b, v32
	v_and_b32_e32 v14, 0xffff0000, v14
	v_mov_b32_e32 v31, v28
	v_exp_f32_e32 v26, v26
	v_mul_f32_e32 v28, 0xbfb8aa3b, v14
	v_exp_f32_e32 v28, v28
	v_lshlrev_b32_e32 v33, 16, v15
	v_add_f32_e32 v26, 1.0, v26
	v_rcp_f32_e32 v34, v26
	v_and_b32_e32 v15, 0xffff0000, v15
	v_add_f32_e32 v26, 1.0, v28
	v_mul_f32_e32 v28, 0xbfb8aa3b, v33
	v_exp_f32_e32 v28, v28
	v_mul_f32_e32 v35, 0xbfb8aa3b, v15
	v_exp_f32_e32 v37, v35
	v_rcp_f32_e32 v36, v26
	v_add_f32_e32 v26, 1.0, v28
	v_rcp_f32_e32 v35, v26
	v_add_f32_e32 v26, 1.0, v37
	v_rcp_f32_e32 v37, v26
	v_mov_b32_e32 v28, v27
	v_mul_f32_e32 v32, v34, v32
	v_mul_f32_e32 v33, v35, v33
	v_add_f32_e32 v30, v30, v28
	v_add_f32_e32 v31, v31, v29
	v_mul_f32_e32 v34, v36, v14
	v_mul_f32_e32 v35, v37, v15
	v_lshlrev_b32_e32 v14, 16, v16
	v_mov_b32_e32 v36, v22
	v_mul_f32_e32 v22, 0xbfb8aa3b, v14
	v_and_b32_e32 v16, 0xffff0000, v16
	v_exp_f32_e32 v22, v22
	v_mul_f32_e32 v26, 0xbfb8aa3b, v16
	v_exp_f32_e32 v27, v26
	v_lshlrev_b32_e32 v15, 16, v17
	v_add_f32_e32 v22, 1.0, v22
	v_rcp_f32_e32 v26, v22
	v_and_b32_e32 v17, 0xffff0000, v17
	v_add_f32_e32 v22, 1.0, v27
	v_mul_f32_e32 v27, 0xbfb8aa3b, v15
	v_exp_f32_e32 v27, v27
	v_mul_f32_e32 v28, 0xbfb8aa3b, v17
	v_exp_f32_e32 v29, v28
	v_rcp_f32_e32 v28, v22
	v_add_f32_e32 v22, 1.0, v27
	v_rcp_f32_e32 v27, v22
	v_add_f32_e32 v22, 1.0, v29
	v_rcp_f32_e32 v29, v22
	v_or_b32_e32 v56, 28, v52
	v_mov_b32_e32 v37, v24
	v_mov_b32_e32 v24, v23
	v_mul_f32_e32 v22, v26, v14
	v_mul_f32_e32 v23, v27, v15
	v_lshl_add_u32 v26, v56, 9, v44
	v_mul_f32_e32 v46, v28, v16
	v_mul_f32_e32 v47, v29, v17
	ds_read_b128 v[14:17], v26
	ds_read_b128 v[26:29], v26 offset:16
	v_mov_b32_e32 v48, v18
	v_or_b32_e32 v18, v45, v119
	v_mov_b32_e32 v49, v20
	s_waitcnt lgkmcnt(1)
	v_mul_f32_e32 v44, v16, v16
	v_mul_f32_e32 v45, v17, v17
	v_mul_f32_e32 v50, v14, v14
	v_mul_f32_e32 v51, v15, v15
	v_mov_b32_e32 v20, v19
	v_pk_mov_b32 v[52:53], v[50:51], v[44:45] op_sel:[1,0]
	v_mov_b32_e32 v51, v45
	v_add_f32_e32 v44, v52, v50
	v_add_f32_e32 v45, v53, v51
	s_waitcnt lgkmcnt(0)
	v_mul_f32_e32 v50, v28, v28
	v_mul_f32_e32 v51, v29, v29
	v_mul_f32_e32 v52, v26, v26
	v_mul_f32_e32 v53, v27, v27
	v_mov_b32_e32 v54, v50
	v_mov_b32_e32 v55, v52
	v_mov_b32_e32 v52, v51
	v_add_f32_e32 v50, v54, v52
	v_add_f32_e32 v51, v55, v53
	v_mov_b32_e32 v52, v44
	v_mov_b32_e32 v53, v2
	v_mov_b32_e32 v2, v45
	v_add_f32_e32 v2, v52, v2
	v_add_f32_e32 v3, v53, v3
	v_mov_b32_e32 v44, v51
	v_mov_b32_e32 v45, v31
	v_add_f32_e32 v2, v2, v44
	v_add_f32_e32 v3, v3, v45
	v_mov_b32_e32 v51, v30
	v_add_f32_e32 v2, v50, v2
	v_add_f32_e32 v3, v51, v3
	s_nop 1
	v_mov_b32_dpp v31, v3 quad_perm:[1,0,3,2] row_mask:0xf bank_mask:0xf bound_ctrl:1
	v_mov_b32_dpp v30, v2 quad_perm:[1,0,3,2] row_mask:0xf bank_mask:0xf bound_ctrl:1
	v_add_f32_e32 v2, v2, v30
	v_add_f32_e32 v3, v3, v31
	s_nop 1
	v_mov_b32_dpp v31, v3 quad_perm:[2,3,0,1] row_mask:0xf bank_mask:0xf bound_ctrl:1
	v_mov_b32_dpp v30, v2 quad_perm:[2,3,0,1] row_mask:0xf bank_mask:0xf bound_ctrl:1
	v_add_f32_e32 v2, v2, v30
	v_add_f32_e32 v3, v3, v31
	s_nop 1
	v_mov_b32_dpp v31, v3 row_half_mirror row_mask:0xf bank_mask:0xf bound_ctrl:1
	v_mov_b32_dpp v30, v2 row_half_mirror row_mask:0xf bank_mask:0xf bound_ctrl:1
	v_add_f32_e32 v2, v2, v30
	v_add_f32_e32 v3, v3, v31
	s_nop 1
	v_mov_b32_dpp v31, v3 row_mirror row_mask:0xf bank_mask:0xf bound_ctrl:1
	v_mov_b32_dpp v30, v2 row_mirror row_mask:0xf bank_mask:0xf bound_ctrl:1
	v_add_f32_e32 v2, v2, v30
	v_add_f32_e32 v3, v3, v31
	s_nop 0
	v_fma_f32 v2, v2, s46, v42
	v_fma_f32 v3, v3, s46, v42
	s_nop 0
	v_mul_f32_e32 v19, 0x4b800000, v3
	v_cmp_gt_f32_e32 vcc, s74, v3
	s_nop 1
	v_cndmask_b32_e32 v3, v3, v19, vcc
	v_rsq_f32_e32 v3, v3
	v_ashrrev_i32_e32 v19, 31, v18
	v_lshlrev_b64 v[18:19], 11, v[18:19]
	v_lshl_add_u64 v[30:31], v[38:39], 0, v[18:19]
	v_mul_f32_e32 v18, 0x45800000, v3
	v_cndmask_b32_e32 v18, v3, v18, vcc
	v_mul_f32_e32 v24, v24, v18
	v_mul_f32_e32 v25, v25, v18
	v_mul_f32_e32 v36, v36, v18
	v_mul_f32_e32 v37, v37, v18
	v_mul_f32_e32 v24, v8, v24
	v_mul_f32_e32 v25, v9, v25
	v_mul_f32_e32 v36, v40, v36
	v_mul_f32_e32 v37, v41, v37
	v_mul_f32_e32 v24, v34, v24
	v_mul_f32_e32 v25, v35, v25
	v_mul_f32_e32 v34, v48, v18
	v_mul_f32_e32 v35, v49, v18
	v_mul_f32_e32 v19, v21, v18
	v_mul_f32_e32 v18, v20, v18
	v_mul_f32_e32 v34, v6, v34
	v_mul_f32_e32 v35, v7, v35
	v_mul_f32_e32 v18, v4, v18
	v_mul_f32_e32 v19, v5, v19
	v_mul_f32_e32 v32, v32, v36
	v_mul_f32_e32 v33, v33, v37
	v_mul_f32_e32 v18, v46, v18
	v_mul_f32_e32 v19, v47, v19
	v_mul_f32_e32 v22, v22, v34
	v_mul_f32_e32 v23, v23, v35
	v_bfe_u32 v3, v19, 16, 1
	v_bfe_u32 v20, v18, 16, 1
	v_bfe_u32 v21, v25, 16, 1
	v_bfe_u32 v34, v24, 16, 1
	v_add3_u32 v24, v24, v34, s81
	v_add3_u32 v25, v25, v21, s81
	v_add3_u32 v18, v18, v20, s81
	v_add3_u32 v3, v19, v3, s81
	v_bfe_u32 v19, v32, 16, 1
	v_bfe_u32 v20, v33, 16, 1
	v_bfe_u32 v21, v22, 16, 1
	v_bfe_u32 v34, v23, 16, 1
	v_add3_u32 v23, v23, v34, s81
	v_add3_u32 v21, v22, v21, s81
	v_add3_u32 v20, v33, v20, s81
	v_add3_u32 v19, v32, v19, s81
	v_lshrrev_b32_e32 v22, 16, v19
	v_lshrrev_b32_e32 v19, 16, v20
	v_lshrrev_b32_e32 v20, 16, v21
	v_lshrrev_b32_e32 v21, 16, v23
	v_and_or_b32 v21, v3, s82, v21
	v_mul_f32_e32 v3, 0x4b800000, v2
	v_cmp_gt_f32_e32 vcc, s74, v2
	v_and_or_b32 v20, v18, s82, v20
	v_and_or_b32 v19, v25, s82, v19
	v_cndmask_b32_e32 v2, v2, v3, vcc
	v_and_or_b32 v18, v24, s82, v22
	v_rsq_f32_e32 v22, v2
	s_waitcnt vmcnt(6)
; __device__ __forceinline__ unsigned pk2(float lo, float hi) { return f2bf(lo) | (f2bf(hi) << 16); }
; __device__ __forceinline__ void out_unit(const bf16* __restrict__ Qc, const bf16* __restrict__ Kc, const bf16* __restrict__ Vc, const float* __restrict__ ST, int c, ...
;     ...
;         for (int i = 0; i < 8; ++i) { const int row = i * 4 + rq;
;             const f32x4 y0 = *(const f32x4*)(stg + row * 128 + c0), y1 = *(const f32x4*)(stg + row * 128 + c0 + 4);
;             float ss = (y0.x * y0.x + y0.y * y0.y) + (y0.z * y0.z + y0.w * y0.w) + (y1.x * y1.x + y1.y * y1.y) + (y1.z * y1.z + y1.w * y1.w);
;             ss += __int_as_float(__builtin_amdgcn_update_dpp(0, __float_as_int(ss), 0xB1, 0xf, 0xf, true));
;             ss += __int_as_float(__builtin_amdgcn_update_dpp(0, __float_as_int(ss), 0x4E, 0xf, 0xf, true));
;             ss += __int_as_float(__builtin_amdgcn_update_dpp(0, __float_as_int(ss), 0x141, 0xf, 0xf, true));
;             ss += __int_as_float(__builtin_amdgcn_update_dpp(0, __float_as_int(ss), 0x140, 0xf, 0xf, true));
;             const float rstd = rsqrtf(ss * (1.f / 128.f) + 1e-6f);
;             float yv[8] = {y0.x, y0.y, y0.z, y0.w, y1.x, y1.y, y1.z, y1.w}; const float gnv[8] = {gn0.x, gn0.y, gn0.z, gn0.w, gn1.x, gn1.y, gn1.z, gn1.w};
;             v4u ov;
; #pragma unroll
;             for (int j = 0; j < 4; ++j) { const float ga = __builtin_bit_cast(float, gv[i][j] << 16), gb = __builtin_bit_cast(float, gv[i][j] & 0xffff0000u);
;                 const float sa = ga * __builtin_amdgcn_rcpf(1.f + __expf(-ga)), sb = gb * __builtin_amdgcn_rcpf(1.f + __expf(-gb));
;                 ov[j] = pk2(yv[2 * j] * rstd * gnv[2 * j] * sa, yv[2 * j + 1] * rstd * gnv[2 * j + 1] * sb); }
;             *(v4u*)(MIXc + (size_t)(wid * 32 + row) * 1024 + c0) = ov;
;         }
;     }
;     __syncthreads();
	v_lshlrev_b32_e32 v2, 16, v10
	v_and_b32_e32 v10, 0xffff0000, v10
	global_store_dwordx4 v[30:31], v[18:21], off
	v_lshlrev_b32_e32 v3, 16, v11
	v_and_b32_e32 v11, 0xffff0000, v11
	v_mul_f32_e32 v19, 0xbfb8aa3b, v10
	v_mul_f32_e32 v18, 0xbfb8aa3b, v2
	v_exp_f32_e32 v19, v19
	v_mul_f32_e32 v20, 0xbfb8aa3b, v3
	v_exp_f32_e32 v18, v18
	v_exp_f32_e32 v21, v20
	v_add_f32_e32 v19, 1.0, v19
	v_mul_f32_e32 v20, 0xbfb8aa3b, v11
	v_add_f32_e32 v18, 1.0, v18
	v_exp_f32_e32 v23, v20
	v_rcp_f32_e32 v20, v19
	v_add_f32_e32 v19, 1.0, v21
	v_rcp_f32_e32 v18, v18
	v_rcp_f32_e32 v19, v19
	v_add_f32_e32 v21, 1.0, v23
	v_mul_f32_e32 v23, 0x45800000, v22
	v_rcp_f32_e32 v21, v21
	v_cndmask_b32_e32 v22, v22, v23, vcc
	v_mul_f32_e32 v2, v18, v2
	v_mul_f32_e32 v3, v19, v3
	v_mov_b32_e32 v18, v14
	v_mov_b32_e32 v19, v16
	v_mul_f32_e32 v18, v18, v22
	v_mul_f32_e32 v19, v19, v22
	v_mov_b32_e32 v16, v15
	v_mul_f32_e32 v18, v40, v18
	v_mul_f32_e32 v19, v41, v19
	v_mul_f32_e32 v14, v16, v22
	v_mul_f32_e32 v15, v17, v22
	v_lshlrev_b32_e32 v16, 16, v12
	v_and_b32_e32 v12, 0xffff0000, v12
	v_mul_f32_e32 v2, v2, v18
	v_mul_f32_e32 v3, v3, v19
	v_lshlrev_b32_e32 v17, 16, v13
	v_mul_f32_e32 v19, 0xbfb8aa3b, v12
	v_mul_f32_e32 v10, v20, v10
	v_mul_f32_e32 v11, v21, v11
	v_mul_f32_e32 v18, 0xbfb8aa3b, v16
	v_exp_f32_e32 v19, v19
	v_mul_f32_e32 v20, 0xbfb8aa3b, v17
	v_exp_f32_e32 v18, v18
	v_and_b32_e32 v13, 0xffff0000, v13
	v_exp_f32_e32 v21, v20
	v_mul_f32_e32 v20, 0xbfb8aa3b, v13
	v_exp_f32_e32 v23, v20
	v_add_f32_e32 v19, 1.0, v19
	v_add_f32_e32 v18, 1.0, v18
	v_rcp_f32_e32 v20, v19
	v_add_f32_e32 v19, 1.0, v21
	v_rcp_f32_e32 v18, v18
	v_rcp_f32_e32 v19, v19
	v_add_f32_e32 v21, 1.0, v23
	v_rcp_f32_e32 v21, v21
	v_mul_f32_e32 v8, v8, v14
	v_mul_f32_e32 v9, v9, v15
	v_mov_b32_e32 v14, v26
	v_mov_b32_e32 v15, v28
	v_mul_f32_e32 v14, v14, v22
	v_mul_f32_e32 v15, v15, v22
	v_mul_f32_e32 v8, v10, v8
	v_mul_f32_e32 v9, v11, v9
	v_mul_f32_e32 v10, v18, v16
	v_mul_f32_e32 v11, v19, v17
	v_mul_f32_e32 v6, v6, v14
	v_mul_f32_e32 v7, v7, v15
	v_mov_b32_e32 v28, v27
	v_mul_f32_e32 v6, v10, v6
	v_mul_f32_e32 v7, v11, v7
	v_mul_f32_e32 v10, v28, v22
	v_mul_f32_e32 v11, v29, v22
	v_mul_f32_e32 v12, v20, v12
	v_mul_f32_e32 v13, v21, v13
	v_mul_f32_e32 v4, v4, v10
	v_mul_f32_e32 v5, v5, v11
	s_nop 0
	v_mul_f32_e32 v4, v12, v4
	v_mul_f32_e32 v5, v13, v5
	v_bfe_u32 v12, v9, 16, 1
	v_bfe_u32 v13, v8, 16, 1
	v_add3_u32 v9, v9, v12, s81
	v_bfe_u32 v12, v6, 16, 1
	v_bfe_u32 v11, v4, 16, 1
	v_add3_u32 v8, v8, v13, s81
	v_bfe_u32 v13, v7, 16, 1
	v_add3_u32 v6, v6, v12, s81
	v_bfe_u32 v10, v5, 16, 1
	v_add3_u32 v4, v4, v11, s81
	v_add3_u32 v7, v7, v13, s81
	v_lshrrev_b32_e32 v6, 16, v6
	v_add3_u32 v5, v5, v10, s81
	v_bfe_u32 v10, v2, 16, 1
	v_bfe_u32 v11, v3, 16, 1
	v_lshrrev_b32_e32 v7, 16, v7
	v_and_or_b32 v4, v4, s82, v6
	v_or_b32_e32 v6, v56, v119
	v_add3_u32 v3, v3, v11, s81
	v_add3_u32 v2, v2, v10, s81
	v_and_or_b32 v5, v5, s82, v7
	v_ashrrev_i32_e32 v7, 31, v6
	v_lshrrev_b32_e32 v2, 16, v2
	v_lshrrev_b32_e32 v3, 16, v3
	v_lshlrev_b64 v[6:7], 11, v[6:7]
	v_and_or_b32 v3, v9, s82, v3
	v_and_or_b32 v2, v8, s82, v2
	v_lshl_add_u64 v[6:7], v[38:39], 0, v[6:7]
	global_store_dwordx4 v[6:7], v[2:5], off
	s_barrier
	s_cbranch_scc0 .LBB0_601

; __device__ __forceinline__ unsigned pk2(float lo, float hi) { return f2bf(lo) | (f2bf(hi) << 16); }
; __global__ void __launch_bounds__(NTHR, 2) mega(Args args) {
;     ...
;             for (int t0 = gw; t0 < M2; t0 += 4 * NGW) {
;                 v4u p0[4], p1[4];
; #pragma unroll
;                 for (int u = 0; u < 4; ++u) { const int t = t0 + u * NGW < M2 ? t0 + u * NGW : t0; const int b = t >> 11, l = t & 2047;
;                     p0[u] = *(const v4u*)(ODb + ((size_t)(b * 8 + 2 * h) * L + l) * 128 + e0); p1[u] = *(const v4u*)(ODb + ((size_t)(b * 8 + 2 * h + 1) * L + l) * 128 + e0); }
; #pragma unroll
;                 for (int u = 0; u < 4; ++u) {
;                     const int t = t0 + u * NGW;
;                     float y[8]; float ss = 0.f;
; #pragma unroll
;                     for (int j = 0; j < 4; ++j) {
;                         y[2 * j] = __builtin_bit_cast(float, p0[u][j] << 16) - lam * __builtin_bit_cast(float, p1[u][j] << 16);
;                         y[2 * j + 1] = __builtin_bit_cast(float, p0[u][j] & 0xffff0000u) - lam * __builtin_bit_cast(float, p1[u][j] & 0xffff0000u);
;                         ss += y[2 * j] * y[2 * j] + y[2 * j + 1] * y[2 * j + 1]; }
;                     ss += __shfl_xor(ss, 1); ss += __shfl_xor(ss, 2); ss += __shfl_xor(ss, 4); ss += __shfl_xor(ss, 8);
;                     const float rstd = rsqrtf(ss * (1.f / 128.f) + EPS) * (1.f - lam_init);
;                     v4u o; o.x = pk2(y[0] * rstd * g0.x, y[1] * rstd * g0.y); o.y = pk2(y[2] * rstd * g0.z, y[3] * rstd * g0.w);
;                     o.z = pk2(y[4] * rstd * g1v.x, y[5] * rstd * g1v.y); o.w = pk2(y[6] * rstd * g1v.z, y[7] * rstd * g1v.w);
;                     if (t < M2) *(v4u*)(MIX + (size_t)t * D + 512 + h * 128 + e0) = o;
.LBB0_637:
	s_ashr_i32 s4, s78, 8
	v_and_or_b32 v12, s4, -8, v44
	v_ashrrev_i32_e32 v13, 31, v12
	v_lshlrev_b64 v[8:9], 19, v[12:13]
	v_or_b32_e32 v12, 1, v12
	v_ashrrev_i32_e32 v13, 31, v12
	v_lshlrev_b64 v[12:13], 19, v[12:13]
	v_lshl_add_u64 v[8:9], s[44:45], 0, v[8:9]
	s_and_b32 s4, s19, 0x7ff00
	v_lshl_add_u64 v[12:13], s[44:45], 0, v[12:13]
	v_lshl_add_u64 v[8:9], v[8:9], 0, s[4:5]
	v_lshl_add_u64 v[12:13], v[12:13], 0, s[4:5]
	v_lshl_add_u64 v[8:9], v[8:9], 0, v[24:25]
	v_lshl_add_u64 v[12:13], v[12:13], 0, v[24:25]
	global_load_dwordx4 v[8:11], v[8:9], off
	s_add_i32 s10, s33, s78
	s_waitcnt lgkmcnt(0)
	global_load_dwordx4 v[12:15], v[12:13], off
	s_cmpk_lt_i32 s10, 0x4000
	s_cselect_b32 s4, s10, s78
	s_ashr_i32 s6, s4, 8
	v_and_or_b32 v16, s6, -8, v44
	v_ashrrev_i32_e32 v17, 31, v16
	v_or_b32_e32 v18, 1, v16
	s_lshl_b32 s4, s4, 8
	v_lshlrev_b64 v[16:17], 19, v[16:17]
	v_ashrrev_i32_e32 v19, 31, v18
	s_and_b32 s4, s4, 0x7ff00
	v_lshl_add_u64 v[16:17], s[44:45], 0, v[16:17]
	v_lshlrev_b64 v[18:19], 19, v[18:19]
	v_lshl_add_u64 v[16:17], v[16:17], 0, s[4:5]
	v_lshl_add_u64 v[18:19], s[44:45], 0, v[18:19]
	v_lshl_add_u64 v[16:17], v[16:17], 0, v[24:25]
	v_lshl_add_u64 v[18:19], v[18:19], 0, s[4:5]
	v_lshl_add_u64 v[18:19], v[18:19], 0, v[24:25]
	global_load_dwordx4 v[36:39], v[16:17], off
	global_load_dwordx4 v[46:49], v[18:19], off
	s_add_i32 s11, s33, s10
	s_cmpk_lt_i32 s11, 0x4000
	s_cselect_b64 s[8:9], -1, 0
	s_and_b64 s[6:7], s[8:9], exec
	s_cselect_b32 s6, s11, s78
	s_ashr_i32 s7, s6, 8
	s_lshl_b32 s6, s6, 8
	s_add_i32 s4, s33, s11
	s_and_b32 s24, s6, 0x7ff00
	s_cmpk_lt_i32 s4, 0x4000
	v_and_or_b32 v16, s7, -8, v44
	s_cselect_b64 s[6:7], -1, 0
	s_and_b64 s[34:35], s[6:7], exec
	s_cselect_b32 s11, s4, s78
	s_ashr_i32 s23, s11, 8
	v_or_b32_e32 v18, 1, v16
	v_ashrrev_i32_e32 v17, 31, v16
	v_ashrrev_i32_e32 v19, 31, v18
	v_lshlrev_b64 v[16:17], 19, v[16:17]
	v_lshlrev_b64 v[18:19], 19, v[18:19]
	s_lshl_b32 s11, s11, 8
	s_mov_b32 s25, s5
	s_mov_b32 s13, s5
	v_lshl_add_u64 v[16:17], s[44:45], 0, v[16:17]
	v_lshl_add_u64 v[18:19], s[44:45], 0, v[18:19]
	s_and_b32 s12, s11, 0x7ff00
	v_lshl_add_u64 v[16:17], v[16:17], 0, s[24:25]
	v_lshl_add_u64 v[18:19], v[18:19], 0, s[24:25]
	v_lshl_add_u64 v[16:17], v[16:17], 0, v[24:25]
	v_lshl_add_u64 v[18:19], v[18:19], 0, v[24:25]
	s_ashr_i32 s79, s78, 31
	s_waitcnt vmcnt(3)
	v_lshlrev_b32_e32 v21, 16, v9
	v_lshlrev_b32_e32 v20, 16, v8
	s_waitcnt vmcnt(2)
	v_lshlrev_b32_e32 v33, 16, v13
	v_lshlrev_b32_e32 v32, 16, v12
	v_and_b32_e32 v9, 0xffff0000, v9
	v_and_b32_e32 v8, 0xffff0000, v8
	v_lshlrev_b32_e32 v23, 16, v11
	v_lshlrev_b32_e32 v22, 16, v10
	v_and_b32_e32 v13, 0xffff0000, v13
	v_and_b32_e32 v12, 0xffff0000, v12
	v_lshlrev_b32_e32 v35, 16, v15
	v_lshlrev_b32_e32 v34, 16, v14
	v_fma_f32 v32, -v28, v32, v20
	v_fma_f32 v33, -v29, v33, v21
	v_and_b32_e32 v11, 0xffff0000, v11
	v_and_b32_e32 v10, 0xffff0000, v10
	v_and_b32_e32 v15, 0xffff0000, v15
	v_and_b32_e32 v14, 0xffff0000, v14
	v_fma_f32 v50, -v28, v12, v8
	v_fma_f32 v51, -v29, v13, v9
	v_fma_f32 v34, -v28, v34, v22
	v_fma_f32 v35, -v29, v35, v23
	v_mul_f32_e32 v8, v32, v32
	v_mul_f32_e32 v9, v33, v33
	v_fma_f32 v52, -v28, v14, v10
	v_fma_f32 v53, -v29, v15, v11
	v_mul_f32_e32 v10, v34, v34
	v_mul_f32_e32 v11, v35, v35
	v_fma_f32 v8, v50, v50, v8
	v_fma_f32 v9, v51, v51, v9
	v_fma_f32 v10, v52, v52, v10
	v_fma_f32 v11, v53, v53, v11
	v_add_f32_e32 v8, v8, v9
	v_add_f32_e32 v8, v8, v10
	v_add_f32_e32 v10, v8, v11
	ds_bpermute_b32 v11, v1, v10
	v_and_or_b32 v8, s23, -8, v44
	v_ashrrev_i32_e32 v9, 31, v8
	global_load_dwordx4 v[20:23], v[16:17], off
	s_nop 0
	global_load_dwordx4 v[16:19], v[18:19], off
	s_waitcnt lgkmcnt(0)
	v_add_f32_e32 v12, v10, v11
	ds_bpermute_b32 v13, v40, v12
	v_or_b32_e32 v10, 1, v8
	v_ashrrev_i32_e32 v11, 31, v10
	v_lshlrev_b64 v[8:9], 19, v[8:9]
	v_lshlrev_b64 v[10:11], 19, v[10:11]
	s_waitcnt lgkmcnt(0)
	v_add_f32_e32 v12, v12, v13
	ds_bpermute_b32 v13, v41, v12
	v_lshl_add_u64 v[8:9], s[44:45], 0, v[8:9]
	v_lshl_add_u64 v[10:11], s[44:45], 0, v[10:11]
	v_lshl_add_u64 v[8:9], v[8:9], 0, s[12:13]
	v_lshl_add_u64 v[10:11], v[10:11], 0, s[12:13]
	v_lshl_add_u64 v[8:9], v[8:9], 0, v[24:25]
	v_lshl_add_u64 v[10:11], v[10:11], 0, v[24:25]
	s_waitcnt lgkmcnt(0)
	v_add_f32_e32 v45, v12, v13
	global_load_dwordx4 v[12:15], v[8:9], off
	s_nop 0
	global_load_dwordx4 v[8:11], v[10:11], off
	ds_bpermute_b32 v54, v42, v45
	s_lshl_b64 s[12:13], s[78:79], 11
	s_cmpk_gt_i32 s10, 0x3fff
	s_waitcnt lgkmcnt(0)
	v_add_f32_e32 v45, v45, v54
	v_fmamk_f32 v45, v45, 0x3c000000, v43
	v_mul_f32_e32 v54, 0x4b800000, v45
	v_cmp_gt_f32_e32 vcc, s17, v45
	s_nop 1
	v_cndmask_b32_e32 v45, v45, v54, vcc
	v_rsq_f32_e32 v45, v45
	v_lshl_add_u64 v[54:55], v[26:27], 0, s[12:13]
	v_mul_f32_e32 v56, 0x45800000, v45
	v_cndmask_b32_e32 v45, v45, v56, vcc
	v_mul_f32_e32 v56, 0x3f4ccccd, v45
	v_mul_f32_e32 v32, v32, v56
	v_mul_f32_e32 v33, v33, v56
	v_mul_f32_e32 v50, v50, v56
	v_mul_f32_e32 v51, v51, v56
	v_mul_f32_e32 v58, v2, v32
	v_mul_f32_e32 v59, v3, v33
	v_mul_f32_e32 v32, v52, v56
	v_mul_f32_e32 v33, v53, v56
	v_mul_f32_e32 v50, v30, v50
	v_mul_f32_e32 v51, v31, v51
	v_mul_f32_e32 v32, v4, v32
	v_mul_f32_e32 v33, v5, v33
	v_mul_f32_e32 v34, v34, v56
	v_mul_f32_e32 v35, v35, v56
	v_bfe_u32 v45, v51, 16, 1
	v_mul_f32_e32 v52, v6, v34
	v_mul_f32_e32 v53, v7, v35
	v_bfe_u32 v34, v33, 16, 1
	v_bfe_u32 v35, v32, 16, 1
	v_add3_u32 v57, v51, v45, s22
	v_add3_u32 v60, v32, v35, s22
	v_add3_u32 v45, v33, v34, s22
	s_waitcnt vmcnt(5)
	v_lshlrev_b32_e32 v33, 16, v37
	v_lshlrev_b32_e32 v32, 16, v36
	s_waitcnt vmcnt(4)
; __device__ __forceinline__ unsigned pk2(float lo, float hi) { return f2bf(lo) | (f2bf(hi) << 16); }
; __global__ void __launch_bounds__(NTHR, 2) mega(Args args) {
;     ...
;                 for (int u = 0; u < 4; ++u) {
;                     const int t = t0 + u * NGW;
;                     float y[8]; float ss = 0.f;
; #pragma unroll
;                     for (int j = 0; j < 4; ++j) {
;                         y[2 * j] = __builtin_bit_cast(float, p0[u][j] << 16) - lam * __builtin_bit_cast(float, p1[u][j] << 16);
;                         y[2 * j + 1] = __builtin_bit_cast(float, p0[u][j] & 0xffff0000u) - lam * __builtin_bit_cast(float, p1[u][j] & 0xffff0000u);
;                         ss += y[2 * j] * y[2 * j] + y[2 * j + 1] * y[2 * j + 1]; }
;                     ss += __shfl_xor(ss, 1); ss += __shfl_xor(ss, 2); ss += __shfl_xor(ss, 4); ss += __shfl_xor(ss, 8);
;                     const float rstd = rsqrtf(ss * (1.f / 128.f) + EPS) * (1.f - lam_init);
;                     v4u o; o.x = pk2(y[0] * rstd * g0.x, y[1] * rstd * g0.y); o.y = pk2(y[2] * rstd * g0.z, y[3] * rstd * g0.w);
;                     o.z = pk2(y[4] * rstd * g1v.x, y[5] * rstd * g1v.y); o.w = pk2(y[6] * rstd * g1v.z, y[7] * rstd * g1v.w);
;                     if (t < M2) *(v4u*)(MIX + (size_t)t * D + 512 + h * 128 + e0) = o;
	v_lshlrev_b32_e32 v35, 16, v47
	v_lshlrev_b32_e32 v34, 16, v46
	v_bfe_u32 v56, v50, 16, 1
	v_fma_f32 v32, -v28, v34, v32
	v_fma_f32 v33, -v29, v35, v33
	v_and_b32_e32 v35, 0xffff0000, v37
	v_and_b32_e32 v34, 0xffff0000, v36
	v_and_b32_e32 v37, 0xffff0000, v47
	v_and_b32_e32 v36, 0xffff0000, v46
	v_add3_u32 v56, v50, v56, s22
	v_mul_f32_e32 v50, v32, v32
	v_mul_f32_e32 v51, v33, v33
	v_fma_f32 v34, -v28, v36, v34
	v_fma_f32 v35, -v29, v37, v35
	v_lshlrev_b32_e32 v37, 16, v39
	v_fma_f32 v46, v34, v34, v50
	v_fma_f32 v47, v35, v35, v51
	v_lshlrev_b32_e32 v36, 16, v38
	v_lshlrev_b32_e32 v51, 16, v49
	v_lshlrev_b32_e32 v50, 16, v48
	v_fma_f32 v36, -v28, v50, v36
	v_fma_f32 v37, -v29, v51, v37
	v_and_b32_e32 v39, 0xffff0000, v39
	v_and_b32_e32 v38, 0xffff0000, v38
	v_and_b32_e32 v49, 0xffff0000, v49
	v_and_b32_e32 v48, 0xffff0000, v48
	v_mul_f32_e32 v50, v36, v36
	v_mul_f32_e32 v51, v37, v37
	v_fma_f32 v38, -v28, v48, v38
	v_fma_f32 v39, -v29, v49, v39
	v_add_f32_e32 v46, v46, v47
	v_fma_f32 v48, v38, v38, v50
	v_fma_f32 v49, v39, v39, v51
	v_bfe_u32 v50, v53, 16, 1
	v_add_f32_e32 v46, v46, v48
	v_add_f32_e32 v46, v46, v49
	ds_bpermute_b32 v47, v1, v46
	v_bfe_u32 v61, v58, 16, 1
	v_add3_u32 v50, v53, v50, s22
	v_bfe_u32 v49, v52, 16, 1
	v_add3_u32 v51, v58, v61, s22
	s_waitcnt lgkmcnt(0)
	v_add_f32_e32 v46, v46, v47
	ds_bpermute_b32 v47, v40, v46
	v_lshrrev_b32_e32 v50, 16, v50
	v_add3_u32 v49, v52, v49, s22
	v_lshrrev_b32_e32 v52, 16, v51
	v_and_or_b32 v51, v45, s16, v50
	s_waitcnt lgkmcnt(0)
	v_add_f32_e32 v46, v46, v47
	ds_bpermute_b32 v47, v41, v46
	v_bfe_u32 v48, v59, 16, 1
	v_add3_u32 v48, v59, v48, s22
	v_lshrrev_b32_e32 v48, 16, v48
	v_lshrrev_b32_e32 v49, 16, v49
	s_waitcnt lgkmcnt(0)
	v_add_f32_e32 v45, v46, v47
	ds_bpermute_b32 v46, v42, v45
	v_and_or_b32 v50, v60, s16, v49
	v_and_or_b32 v49, v57, s16, v48
	v_and_or_b32 v48, v56, s16, v52
	global_store_dwordx4 v[54:55], v[48:51], off offset:1024
	s_cbranch_scc1 .LBB0_639
	s_waitcnt lgkmcnt(0)
	v_add_f32_e32 v45, v45, v46
	v_fmamk_f32 v45, v45, 0x3c000000, v43
	v_mul_f32_e32 v46, 0x4b800000, v45
	v_cmp_gt_f32_e32 vcc, s17, v45
	s_ashr_i32 s11, s10, 31
	s_lshl_b64 s[10:11], s[10:11], 11
	v_cndmask_b32_e32 v45, v45, v46, vcc
	v_rsq_f32_e32 v45, v45
	v_lshl_add_u64 v[46:47], v[26:27], 0, s[10:11]
	v_mul_f32_e32 v48, 0x45800000, v45
	v_cndmask_b32_e32 v45, v45, v48, vcc
	v_mul_f32_e32 v48, 0x3f4ccccd, v45
	v_mul_f32_e32 v34, v34, v48
	v_mul_f32_e32 v35, v35, v48
	v_mul_f32_e32 v38, v38, v48
	v_mul_f32_e32 v39, v39, v48
	v_mul_f32_e32 v34, v30, v34
	v_mul_f32_e32 v35, v31, v35
	v_mul_f32_e32 v32, v32, v48
	v_mul_f32_e32 v33, v33, v48
	v_mul_f32_e32 v38, v4, v38
	v_mul_f32_e32 v39, v5, v39
	v_mul_f32_e32 v36, v36, v48
	v_mul_f32_e32 v37, v37, v48
	v_mul_f32_e32 v32, v2, v32
	v_mul_f32_e32 v33, v3, v33
	v_mul_f32_e32 v36, v6, v36
	v_mul_f32_e32 v37, v7, v37
	v_bfe_u32 v45, v39, 16, 1
	v_bfe_u32 v48, v38, 16, 1
	v_bfe_u32 v49, v35, 16, 1
	v_bfe_u32 v50, v34, 16, 1
	v_add3_u32 v50, v34, v50, s22
	v_add3_u32 v49, v35, v49, s22
	v_add3_u32 v34, v38, v48, s22
	v_add3_u32 v35, v39, v45, s22
	v_bfe_u32 v38, v32, 16, 1
	v_bfe_u32 v39, v33, 16, 1
	v_bfe_u32 v45, v36, 16, 1
	v_bfe_u32 v48, v37, 16, 1
	v_add3_u32 v37, v37, v48, s22
	v_add3_u32 v36, v36, v45, s22
	v_add3_u32 v33, v33, v39, s22
	v_add3_u32 v32, v32, v38, s22
	v_lshrrev_b32_e32 v32, 16, v32
	v_lshrrev_b32_e32 v33, 16, v33
	v_lshrrev_b32_e32 v36, 16, v36
	v_lshrrev_b32_e32 v37, 16, v37
	v_and_or_b32 v35, v35, s16, v37
	v_and_or_b32 v34, v34, s16, v36
	v_and_or_b32 v33, v49, s16, v33
	v_and_or_b32 v32, v50, s16, v32
	global_store_dwordx4 v[46:47], v[32:35], off offset:1024
; __device__ __forceinline__ unsigned pk2(float lo, float hi) { return f2bf(lo) | (f2bf(hi) << 16); }
; __global__ void __launch_bounds__(NTHR, 2) mega(Args args) {
;     ...
;                 for (int u = 0; u < 4; ++u) {
;                     const int t = t0 + u * NGW;
;                     float y[8]; float ss = 0.f;
; #pragma unroll
;                     for (int j = 0; j < 4; ++j) {
;                         y[2 * j] = __builtin_bit_cast(float, p0[u][j] << 16) - lam * __builtin_bit_cast(float, p1[u][j] << 16);
;                         y[2 * j + 1] = __builtin_bit_cast(float, p0[u][j] & 0xffff0000u) - lam * __builtin_bit_cast(float, p1[u][j] & 0xffff0000u);
;                         ss += y[2 * j] * y[2 * j] + y[2 * j + 1] * y[2 * j + 1]; }
;                     ss += __shfl_xor(ss, 1); ss += __shfl_xor(ss, 2); ss += __shfl_xor(ss, 4); ss += __shfl_xor(ss, 8);
;                     const float rstd = rsqrtf(ss * (1.f / 128.f) + EPS) * (1.f - lam_init);
;                     v4u o; o.x = pk2(y[0] * rstd * g0.x, y[1] * rstd * g0.y); o.y = pk2(y[2] * rstd * g0.z, y[3] * rstd * g0.w);
;                     o.z = pk2(y[4] * rstd * g1v.x, y[5] * rstd * g1v.y); o.w = pk2(y[6] * rstd * g1v.z, y[7] * rstd * g1v.w);
;                     if (t < M2) *(v4u*)(MIX + (size_t)t * D + 512 + h * 128 + e0) = o;
.LBB0_639:
	s_waitcnt vmcnt(4)
	s_nop 0
	v_lshlrev_b32_e32 v33, 16, v21
	v_lshlrev_b32_e32 v32, 16, v20
	s_waitcnt vmcnt(3)
	v_lshlrev_b32_e32 v35, 16, v17
	v_lshlrev_b32_e32 v34, 16, v16
	v_and_b32_e32 v21, 0xffff0000, v21
	v_and_b32_e32 v20, 0xffff0000, v20
	v_and_b32_e32 v17, 0xffff0000, v17
	v_and_b32_e32 v16, 0xffff0000, v16
	v_fma_f32 v32, -v28, v34, v32
	v_fma_f32 v33, -v29, v35, v33
	v_fma_f32 v16, -v28, v16, v20
	v_fma_f32 v17, -v29, v17, v21
	v_lshlrev_b32_e32 v21, 16, v23
	v_lshlrev_b32_e32 v20, 16, v22
	v_lshlrev_b32_e32 v37, 16, v19
	v_lshlrev_b32_e32 v36, 16, v18
	v_mul_f32_e32 v34, v32, v32
	v_mul_f32_e32 v35, v33, v33
	v_fma_f32 v20, -v28, v36, v20
	v_fma_f32 v21, -v29, v37, v21
	v_and_b32_e32 v23, 0xffff0000, v23
	v_and_b32_e32 v22, 0xffff0000, v22
	v_and_b32_e32 v19, 0xffff0000, v19
	v_and_b32_e32 v18, 0xffff0000, v18
	v_fma_f32 v34, v16, v16, v34
	v_fma_f32 v35, v17, v17, v35
	v_mul_f32_e32 v36, v20, v20
	v_mul_f32_e32 v37, v21, v21
	v_fma_f32 v18, -v28, v18, v22
	v_fma_f32 v19, -v29, v19, v23
	v_add_f32_e32 v34, v34, v35
	v_fma_f32 v22, v18, v18, v36
	v_fma_f32 v23, v19, v19, v37
	s_andn2_b64 vcc, exec, s[8:9]
	v_add_f32_e32 v22, v34, v22
	v_add_f32_e32 v22, v22, v23
	ds_bpermute_b32 v23, v1, v22
	s_waitcnt lgkmcnt(0)
	v_add_f32_e32 v22, v22, v23
	ds_bpermute_b32 v23, v40, v22
	s_waitcnt lgkmcnt(0)
	v_add_f32_e32 v22, v22, v23
	ds_bpermute_b32 v23, v41, v22
	s_waitcnt lgkmcnt(0)
	v_add_f32_e32 v22, v22, v23
	ds_bpermute_b32 v23, v42, v22
	s_cbranch_vccnz .LBB0_641
	s_waitcnt lgkmcnt(0)
	v_add_f32_e32 v22, v22, v23
	v_fmamk_f32 v22, v22, 0x3c000000, v43
	v_mul_f32_e32 v23, 0x4b800000, v22
	v_cmp_gt_f32_e32 vcc, s17, v22
	s_add_i32 s8, s14, s78
	s_ashr_i32 s9, s8, 31
	v_cndmask_b32_e32 v22, v22, v23, vcc
	v_rsq_f32_e32 v34, v22
	s_lshl_b64 s[8:9], s[8:9], 11
	v_lshl_add_u64 v[22:23], v[26:27], 0, s[8:9]
	v_mul_f32_e32 v35, 0x45800000, v34
	v_cndmask_b32_e32 v34, v34, v35, vcc
	v_mul_f32_e32 v34, 0x3f4ccccd, v34
	v_mul_f32_e32 v16, v16, v34
	v_mul_f32_e32 v17, v17, v34
	v_mul_f32_e32 v18, v18, v34
	v_mul_f32_e32 v19, v19, v34
	v_mul_f32_e32 v16, v30, v16
	v_mul_f32_e32 v17, v31, v17
	v_mul_f32_e32 v32, v32, v34
	v_mul_f32_e32 v33, v33, v34
	v_mul_f32_e32 v18, v4, v18
	v_mul_f32_e32 v19, v5, v19
	v_mul_f32_e32 v20, v20, v34
	v_mul_f32_e32 v21, v21, v34
	v_mul_f32_e32 v32, v2, v32
	v_mul_f32_e32 v33, v3, v33
	v_mul_f32_e32 v20, v6, v20
	v_mul_f32_e32 v21, v7, v21
	v_bfe_u32 v34, v19, 16, 1
	v_bfe_u32 v35, v18, 16, 1
	v_bfe_u32 v36, v17, 16, 1
	v_bfe_u32 v37, v16, 16, 1
	v_add3_u32 v16, v16, v37, s22
	v_add3_u32 v17, v17, v36, s22
	v_add3_u32 v18, v18, v35, s22
	v_add3_u32 v19, v19, v34, s22
	v_bfe_u32 v34, v32, 16, 1
	v_bfe_u32 v35, v33, 16, 1
	v_bfe_u32 v36, v20, 16, 1
	v_bfe_u32 v37, v21, 16, 1
	v_add3_u32 v21, v21, v37, s22
	v_add3_u32 v20, v20, v36, s22
	v_add3_u32 v33, v33, v35, s22
	v_add3_u32 v32, v32, v34, s22
	v_lshrrev_b32_e32 v32, 16, v32
	v_lshrrev_b32_e32 v33, 16, v33
	v_lshrrev_b32_e32 v20, 16, v20
	v_lshrrev_b32_e32 v21, 16, v21
	v_and_or_b32 v19, v19, s16, v21
	v_and_or_b32 v18, v18, s16, v20
	v_and_or_b32 v17, v17, s16, v33
	v_and_or_b32 v16, v16, s16, v32
	global_store_dwordx4 v[22:23], v[16:19], off offset:1024
.LBB0_641:
	s_waitcnt vmcnt(2)
	s_nop 0
	v_lshlrev_b32_e32 v17, 16, v13
	v_lshlrev_b32_e32 v16, 16, v12
	s_waitcnt vmcnt(1)
	v_lshlrev_b32_e32 v19, 16, v9
	v_lshlrev_b32_e32 v18, 16, v8
	v_and_b32_e32 v13, 0xffff0000, v13
	v_and_b32_e32 v12, 0xffff0000, v12
	v_and_b32_e32 v9, 0xffff0000, v9
	v_and_b32_e32 v8, 0xffff0000, v8
	v_fma_f32 v16, -v28, v18, v16
	v_fma_f32 v17, -v29, v19, v17
	v_fma_f32 v8, -v28, v8, v12
	v_fma_f32 v9, -v29, v9, v13
	v_lshlrev_b32_e32 v13, 16, v15
	v_lshlrev_b32_e32 v12, 16, v14
	v_lshlrev_b32_e32 v21, 16, v11
	v_lshlrev_b32_e32 v20, 16, v10
	v_mul_f32_e32 v18, v16, v16
	v_mul_f32_e32 v19, v17, v17
	v_fma_f32 v12, -v28, v20, v12
	v_fma_f32 v13, -v29, v21, v13
	v_and_b32_e32 v15, 0xffff0000, v15
	v_and_b32_e32 v14, 0xffff0000, v14
	v_and_b32_e32 v11, 0xffff0000, v11
	v_and_b32_e32 v10, 0xffff0000, v10
	v_fma_f32 v18, v8, v8, v18
	v_fma_f32 v19, v9, v9, v19
	v_mul_f32_e32 v20, v12, v12
	v_mul_f32_e32 v21, v13, v13
	v_fma_f32 v10, -v28, v10, v14
	v_fma_f32 v11, -v29, v11, v15
	v_add_f32_e32 v18, v18, v19
	v_fma_f32 v14, v10, v10, v20
	v_fma_f32 v15, v11, v11, v21
	s_andn2_b64 vcc, exec, s[6:7]
	v_add_f32_e32 v14, v18, v14
	v_add_f32_e32 v14, v14, v15
	ds_bpermute_b32 v15, v1, v14
	s_waitcnt lgkmcnt(0)
	v_add_f32_e32 v14, v14, v15
	ds_bpermute_b32 v15, v40, v14
	s_waitcnt lgkmcnt(0)
	v_add_f32_e32 v14, v14, v15
	ds_bpermute_b32 v15, v41, v14
	s_waitcnt lgkmcnt(0)
	v_add_f32_e32 v14, v14, v15
	ds_bpermute_b32 v15, v42, v14
	s_cbranch_vccnz .LBB0_636
	s_waitcnt lgkmcnt(0)
	v_add_f32_e32 v14, v14, v15
	v_fmamk_f32 v14, v14, 0x3c000000, v43
	v_mul_f32_e32 v15, 0x4b800000, v14
	v_cmp_gt_f32_e32 vcc, s17, v14
	s_add_i32 s6, s15, s78
	s_ashr_i32 s7, s6, 31
	v_cndmask_b32_e32 v14, v14, v15, vcc
	v_rsq_f32_e32 v18, v14
	s_lshl_b64 s[6:7], s[6:7], 11
	v_lshl_add_u64 v[14:15], v[26:27], 0, s[6:7]
	v_mul_f32_e32 v19, 0x45800000, v18
	v_cndmask_b32_e32 v18, v18, v19, vcc
	v_mul_f32_e32 v18, 0x3f4ccccd, v18
	v_mul_f32_e32 v8, v8, v18
	v_mul_f32_e32 v9, v9, v18
	v_mul_f32_e32 v10, v10, v18
	v_mul_f32_e32 v11, v11, v18
	v_mul_f32_e32 v8, v30, v8
	v_mul_f32_e32 v9, v31, v9
	v_mul_f32_e32 v16, v16, v18
	v_mul_f32_e32 v17, v17, v18
	v_mul_f32_e32 v10, v4, v10
	v_mul_f32_e32 v11, v5, v11
	v_mul_f32_e32 v12, v12, v18
	v_mul_f32_e32 v13, v13, v18
	v_mul_f32_e32 v16, v2, v16
	v_mul_f32_e32 v17, v3, v17
	v_mul_f32_e32 v12, v6, v12
	v_mul_f32_e32 v13, v7, v13
	v_bfe_u32 v18, v11, 16, 1
	v_bfe_u32 v19, v10, 16, 1
	v_bfe_u32 v20, v9, 16, 1
	v_bfe_u32 v21, v8, 16, 1
	v_add3_u32 v8, v8, v21, s22
	v_add3_u32 v9, v9, v20, s22
	v_add3_u32 v10, v10, v19, s22
	v_add3_u32 v11, v11, v18, s22
	v_bfe_u32 v18, v16, 16, 1
	v_bfe_u32 v19, v17, 16, 1
	v_bfe_u32 v20, v12, 16, 1
	v_bfe_u32 v21, v13, 16, 1
	v_add3_u32 v13, v13, v21, s22
	v_add3_u32 v12, v12, v20, s22
	v_add3_u32 v17, v17, v19, s22
	v_add3_u32 v16, v16, v18, s22
	v_lshrrev_b32_e32 v16, 16, v16
	v_lshrrev_b32_e32 v17, 16, v17
	v_lshrrev_b32_e32 v12, 16, v12
	v_lshrrev_b32_e32 v13, 16, v13
	v_and_or_b32 v11, v11, s16, v13
	v_and_or_b32 v10, v10, s16, v12
	v_and_or_b32 v9, v9, s16, v17
	v_and_or_b32 v8, v8, s16, v16
	global_store_dwordx4 v[14:15], v[8:11], off offset:1024
	s_branch .LBB0_636

; __device__ __forceinline__ unsigned pk2(float lo, float hi) { return f2bf(lo) | (f2bf(hi) << 16); }
;     __device__ __forceinline__ void operator()(const pg8::f32x4 (&acc)[2][2][4][2], const pg8::Unit& u, int wr, int wc, int fr, int fq) const {
;     ...
;         f32x4 gt[2][2], al[2][2];
; #pragma unroll
;         for (int bj = 0; bj < 2; ++bj)
; #pragma unroll
;             for (int n = 0; n < 2; ++n) { gt[bj][n] = *(const f32x4*)(mod + (size_t)b * NMODC + 2 * D + col0 + bj * 128 + n * 16); al[bj][n] = *(const f32x4*)(alpha2 + (size_t)b * D + col0 + bj * 128 + n * 16); }
; #pragma unroll
;         for (int ai = 0; ai < 2; ++ai)
; #pragma unroll
;             for (int mh = 0; mh < 4; mh += MB) {
;                 f32x4 xv[MB][2][2];
; #pragma unroll
;                 for (int mm = 0; mm < MB; ++mm) { const size_t row = (size_t)u.pm * 256 + ai * 128 + wr * 64 + (mh + mm) * 16 + fr;
; #pragma unroll
;                     for (int bj = 0; bj < 2; ++bj)
; #pragma unroll
;                         for (int n = 0; n < 2; ++n) xv[mm][bj][n] = *(const f32x4*)(x + row * D + col0 + bj * 128 + n * 16); }
; #pragma unroll
;                 for (int mm = 0; mm < MB; ++mm) { const int m = mh + mm;
;                     const size_t row = (size_t)u.pm * 256 + ai * 128 + wr * 64 + m * 16 + fr;
;                     float ss = 0.f;
; #pragma unroll
;                     for (int bj = 0; bj < 2; ++bj)
; #pragma unroll
;                         for (int n = 0; n < 2; ++n) { const size_t off = row * D + col0 + bj * 128 + n * 16;
;                             const f32x4 x1 = xv[mm][bj][n] + gt[bj][n] * acc[ai][bj][m][n];
;                             { v2u pb; pb.x = pk2(x1.x, x1.y); pb.y = pk2(x1.z, x1.w); *(v2u*)(x1b + off) = pb; } ss += (x1.x * x1.x + x1.y * x1.y) + (x1.z * x1.z + x1.w * x1.w);
;                             const f32x4 xa = x1 * al[bj][n]; v2u pk; pk.x = pk2(xa.x, xa.y); pk.y = pk2(xa.z, xa.w); *(v2u*)(x1a + off) = pk; }
;                     ss += __shfl_xor(ss, 16); ss += __shfl_xor(ss, 32);
;                     if (fq == 0) ssq[row * 16 + u.pn * 4 + wc] = ss;
;                 }
.LBB0_716:
	s_ashr_i32 s62, s60, 3
	s_mul_i32 s53, s62, 0x6000
	s_add_u32 s64, s28, s53
	s_addc_u32 s65, s29, 0
	s_lshl_b32 s62, s62, 12
	s_add_u32 s62, s70, s62
	s_addc_u32 s63, s71, 0
	v_lshl_or_b32 v246, s8, 8, v208
	v_lshlrev_b32_e32 v246, 2, v246
	v_add_u32_e32 v247, 0x2000, v246
	global_load_dwordx4 v[58:61], v247, s[64:65]
	global_load_dwordx4 v[62:65], v247, s[64:65] offset:64
	global_load_dwordx4 v[66:69], v247, s[64:65] offset:512
	global_load_dwordx4 v[70:73], v247, s[64:65] offset:576
	global_load_dwordx4 v[74:77], v246, s[62:63]
	global_load_dwordx4 v[78:81], v246, s[62:63] offset:64
	global_load_dwordx4 v[82:85], v246, s[62:63] offset:512
	global_load_dwordx4 v[86:89], v246, s[62:63] offset:576
	s_lshl_b32 s10, s60, 8
	v_add_u32_e32 v203, s10, v184
	v_lshl_add_u32 v200, v203, 12, v246
	v_and_b32_e32 v246, 4, v208
	v_and_b32_e32 v247, 0x68, v208
	v_lshl_or_b32 v246, v246, 2, v247
	s_lshl_b32 s10, s8, 8
	v_or_b32_e32 v246, s10, v246
	v_lshl_add_u32 v246, v203, 10, v246
	v_lshlrev_b32_e32 v201, 1, v246
	s_lshl_b32 s10, s8, 2
	s_add_i32 s10, s10, s69
	s_lshl_b32 s10, s10, 2
	v_lshlrev_b32_e32 v203, 6, v203
	v_add_u32_e32 v202, s10, v203
	v_xor_b32_e32 v238, 16, v212
	v_xor_b32_e32 v239, 32, v212
	v_lshlrev_b32_e32 v238, 2, v238
	v_lshlrev_b32_e32 v239, 2, v239
	global_load_dwordx4 v[162:165], v200, s[36:37]
	global_load_dwordx4 v[166:169], v200, s[36:37] offset:64
	global_load_dwordx4 v[170:173], v200, s[36:37] offset:512
	global_load_dwordx4 v[174:177], v200, s[36:37] offset:576
	v_add_u32_e32 v203, 0x10000, v200
	global_load_dwordx4 v[214:217], v203, s[36:37]
	global_load_dwordx4 v[218:221], v203, s[36:37] offset:64
	global_load_dwordx4 v[222:225], v203, s[36:37] offset:512
	global_load_dwordx4 v[226:229], v203, s[36:37] offset:576
	v_add_u32_e32 v203, 0x20000, v200
	global_load_dwordx4 v[230:233], v203, s[36:37]
	global_load_dwordx4 v[234:237], v203, s[36:37] offset:64
	global_load_dwordx4 v[242:245], v203, s[36:37] offset:512
	global_load_dwordx4 v[204:207], v203, s[36:37] offset:576
	s_waitcnt vmcnt(8)
	v_fma_f32 v158, v158, v58, v162
	v_fma_f32 v159, v159, v59, v163
	v_fma_f32 v160, v160, v60, v164
	v_fma_f32 v161, v161, v61, v165
	v_fma_f32 v154, v154, v62, v166
	v_fma_f32 v155, v155, v63, v167
	v_fma_f32 v156, v156, v64, v168
	v_fma_f32 v157, v157, v65, v169
	v_fma_f32 v150, v150, v66, v170
	v_fma_f32 v151, v151, v67, v171
	v_fma_f32 v152, v152, v68, v172
	v_fma_f32 v153, v153, v69, v173
	v_fma_f32 v146, v146, v70, v174
	v_fma_f32 v147, v147, v71, v175
	v_fma_f32 v148, v148, v72, v176
	v_fma_f32 v149, v149, v73, v177
	v_mul_f32_e32 v241, v158, v158
	v_mul_f32_e32 v213, v159, v159
	v_fmac_f32_e32 v241, v160, v160
	v_fmac_f32_e32 v213, v161, v161
	v_fmac_f32_e32 v241, v154, v154
	v_fmac_f32_e32 v213, v155, v155
	v_fmac_f32_e32 v241, v156, v156
	v_fmac_f32_e32 v213, v157, v157
	v_fmac_f32_e32 v241, v150, v150
	v_fmac_f32_e32 v213, v151, v151
	v_fmac_f32_e32 v241, v152, v152
	v_fmac_f32_e32 v213, v153, v153
	v_fmac_f32_e32 v241, v146, v146
	v_fmac_f32_e32 v213, v147, v147
	v_fmac_f32_e32 v241, v148, v148
	v_fmac_f32_e32 v213, v149, v149
	v_add_f32_e32 v241, v241, v213
	ds_bpermute_b32 v213, v238, v241
	v_mul_f32_e32 v162, v158, v74
	v_mul_f32_e32 v163, v159, v75
	v_mul_f32_e32 v164, v160, v76
	v_mul_f32_e32 v165, v161, v77
	v_mul_f32_e32 v166, v154, v78
	v_mul_f32_e32 v167, v155, v79
	v_mul_f32_e32 v168, v156, v80
	v_mul_f32_e32 v169, v157, v81
	v_mul_f32_e32 v170, v150, v82
	v_mul_f32_e32 v171, v151, v83
	v_mul_f32_e32 v172, v152, v84
	v_mul_f32_e32 v173, v153, v85
	v_mul_f32_e32 v174, v146, v86
	v_mul_f32_e32 v175, v147, v87
	v_mul_f32_e32 v176, v148, v88
	v_mul_f32_e32 v177, v149, v89
	v_cvt_pk_bf16_f32 v158, v158, v159
	v_cvt_pk_bf16_f32 v159, v160, v161
	v_cvt_pk_bf16_f32 v160, v154, v155
	v_cvt_pk_bf16_f32 v161, v156, v157
	v_cvt_pk_bf16_f32 v150, v150, v151
	v_cvt_pk_bf16_f32 v151, v152, v153
	v_cvt_pk_bf16_f32 v152, v146, v147
	v_cvt_pk_bf16_f32 v153, v148, v149
	v_cvt_pk_bf16_f32 v162, v162, v163
	v_cvt_pk_bf16_f32 v163, v164, v165
	v_cvt_pk_bf16_f32 v164, v166, v167
	v_cvt_pk_bf16_f32 v165, v168, v169
	v_cvt_pk_bf16_f32 v170, v170, v171
	v_cvt_pk_bf16_f32 v171, v172, v173
	v_cvt_pk_bf16_f32 v172, v174, v175
	v_cvt_pk_bf16_f32 v173, v176, v177
	s_waitcnt lgkmcnt(0)
	v_add_f32_e32 v241, v241, v213
	ds_bpermute_b32 v213, v239, v241
	v_permlane16_swap_b32_e32 v158, v160
	v_permlane16_swap_b32_e32 v159, v161
	v_permlane16_swap_b32_e32 v150, v152
	v_permlane16_swap_b32_e32 v151, v153
	v_permlane16_swap_b32_e32 v162, v164
	v_permlane16_swap_b32_e32 v163, v165
	v_permlane16_swap_b32_e32 v170, v172
	v_permlane16_swap_b32_e32 v171, v173
	global_store_dwordx4 v201, v[158:161], s[14:15]
	global_store_dwordx4 v201, v[150:153], s[14:15] offset:256
	global_store_dwordx4 v201, v[162:165], s[44:45]
	global_store_dwordx4 v201, v[170:173], s[44:45] offset:256
	s_waitcnt lgkmcnt(0)
	v_add_f32_e32 v241, v241, v213
	v_mov_b32_e32 v203, v202
	s_and_saveexec_b64 s[60:61], s[4:5]
	global_store_dword v203, v241, s[16:17]
	s_or_b64 exec, exec, s[60:61]
	v_add_u32_e32 v203, 0x30000, v200
	global_load_dwordx4 v[162:165], v203, s[36:37]
	global_load_dwordx4 v[166:169], v203, s[36:37] offset:64
	global_load_dwordx4 v[170:173], v203, s[36:37] offset:512
	global_load_dwordx4 v[174:177], v203, s[36:37] offset:576
	s_waitcnt vmcnt(13)
; __device__ __forceinline__ unsigned pk2(float lo, float hi) { return f2bf(lo) | (f2bf(hi) << 16); }
;     __device__ __forceinline__ void operator()(const pg8::f32x4 (&acc)[2][2][4][2], const pg8::Unit& u, int wr, int wc, int fr, int fq) const {
;     ...
; #pragma unroll
;         for (int ai = 0; ai < 2; ++ai)
; #pragma unroll
;             for (int mh = 0; mh < 4; mh += MB) {
;                 f32x4 xv[MB][2][2];
; #pragma unroll
;                 for (int mm = 0; mm < MB; ++mm) { const size_t row = (size_t)u.pm * 256 + ai * 128 + wr * 64 + (mh + mm) * 16 + fr;
; #pragma unroll
;                     for (int bj = 0; bj < 2; ++bj)
; #pragma unroll
;                         for (int n = 0; n < 2; ++n) xv[mm][bj][n] = *(const f32x4*)(x + row * D + col0 + bj * 128 + n * 16); }
; #pragma unroll
;                 for (int mm = 0; mm < MB; ++mm) { const int m = mh + mm;
;                     const size_t row = (size_t)u.pm * 256 + ai * 128 + wr * 64 + m * 16 + fr;
;                     float ss = 0.f;
; #pragma unroll
;                     for (int bj = 0; bj < 2; ++bj)
; #pragma unroll
;                         for (int n = 0; n < 2; ++n) { const size_t off = row * D + col0 + bj * 128 + n * 16;
;                             const f32x4 x1 = xv[mm][bj][n] + gt[bj][n] * acc[ai][bj][m][n];
;                             { v2u pb; pb.x = pk2(x1.x, x1.y); pb.y = pk2(x1.z, x1.w); *(v2u*)(x1b + off) = pb; } ss += (x1.x * x1.x + x1.y * x1.y) + (x1.z * x1.z + x1.w * x1.w);
;                             const f32x4 xa = x1 * al[bj][n]; v2u pk; pk.x = pk2(xa.x, xa.y); pk.y = pk2(xa.z, xa.w); *(v2u*)(x1a + off) = pk; }
;                     ss += __shfl_xor(ss, 16); ss += __shfl_xor(ss, 32);
;                     if (fq == 0) ssq[row * 16 + u.pn * 4 + wc] = ss;
;                 }
;             }
	v_fma_f32 v142, v142, v58, v214
	v_fma_f32 v143, v143, v59, v215
	v_fma_f32 v144, v144, v60, v216
	v_fma_f32 v145, v145, v61, v217
	v_fma_f32 v138, v138, v62, v218
	v_fma_f32 v139, v139, v63, v219
	v_fma_f32 v140, v140, v64, v220
	v_fma_f32 v141, v141, v65, v221
	v_fma_f32 v134, v134, v66, v222
	v_fma_f32 v135, v135, v67, v223
	v_fma_f32 v136, v136, v68, v224
	v_fma_f32 v137, v137, v69, v225
	v_fma_f32 v130, v130, v70, v226
	v_fma_f32 v131, v131, v71, v227
	v_fma_f32 v132, v132, v72, v228
	v_fma_f32 v133, v133, v73, v229
	v_mul_f32_e32 v241, v142, v142
	v_mul_f32_e32 v213, v143, v143
	v_fmac_f32_e32 v241, v144, v144
	v_fmac_f32_e32 v213, v145, v145
	v_fmac_f32_e32 v241, v138, v138
	v_fmac_f32_e32 v213, v139, v139
	v_fmac_f32_e32 v241, v140, v140
	v_fmac_f32_e32 v213, v141, v141
	v_fmac_f32_e32 v241, v134, v134
	v_fmac_f32_e32 v213, v135, v135
	v_fmac_f32_e32 v241, v136, v136
	v_fmac_f32_e32 v213, v137, v137
	v_fmac_f32_e32 v241, v130, v130
	v_fmac_f32_e32 v213, v131, v131
	v_fmac_f32_e32 v241, v132, v132
	v_fmac_f32_e32 v213, v133, v133
	v_add_f32_e32 v241, v241, v213
	ds_bpermute_b32 v213, v238, v241
	v_mul_f32_e32 v214, v142, v74
	v_mul_f32_e32 v215, v143, v75
	v_mul_f32_e32 v216, v144, v76
	v_mul_f32_e32 v217, v145, v77
	v_mul_f32_e32 v218, v138, v78
	v_mul_f32_e32 v219, v139, v79
	v_mul_f32_e32 v220, v140, v80
	v_mul_f32_e32 v221, v141, v81
	v_mul_f32_e32 v222, v134, v82
	v_mul_f32_e32 v223, v135, v83
	v_mul_f32_e32 v224, v136, v84
	v_mul_f32_e32 v225, v137, v85
	v_mul_f32_e32 v226, v130, v86
	v_mul_f32_e32 v227, v131, v87
	v_mul_f32_e32 v228, v132, v88
	v_mul_f32_e32 v229, v133, v89
	v_cvt_pk_bf16_f32 v142, v142, v143
	v_cvt_pk_bf16_f32 v143, v144, v145
	v_cvt_pk_bf16_f32 v144, v138, v139
	v_cvt_pk_bf16_f32 v145, v140, v141
	v_cvt_pk_bf16_f32 v134, v134, v135
	v_cvt_pk_bf16_f32 v135, v136, v137
	v_cvt_pk_bf16_f32 v136, v130, v131
	v_cvt_pk_bf16_f32 v137, v132, v133
	v_cvt_pk_bf16_f32 v214, v214, v215
	v_cvt_pk_bf16_f32 v215, v216, v217
	v_cvt_pk_bf16_f32 v216, v218, v219
	v_cvt_pk_bf16_f32 v217, v220, v221
	v_cvt_pk_bf16_f32 v222, v222, v223
	v_cvt_pk_bf16_f32 v223, v224, v225
	v_cvt_pk_bf16_f32 v224, v226, v227
	v_cvt_pk_bf16_f32 v225, v228, v229
	s_waitcnt lgkmcnt(0)
	v_add_f32_e32 v241, v241, v213
	ds_bpermute_b32 v213, v239, v241
	v_permlane16_swap_b32_e32 v142, v144
	v_permlane16_swap_b32_e32 v143, v145
	v_permlane16_swap_b32_e32 v134, v136
	v_permlane16_swap_b32_e32 v135, v137
	v_permlane16_swap_b32_e32 v214, v216
	v_permlane16_swap_b32_e32 v215, v217
	v_permlane16_swap_b32_e32 v222, v224
	v_permlane16_swap_b32_e32 v223, v225
	v_add_u32_e32 v203, 0x8000, v201
	global_store_dwordx4 v203, v[142:145], s[14:15]
	global_store_dwordx4 v203, v[134:137], s[14:15] offset:256
	global_store_dwordx4 v203, v[214:217], s[44:45]
	global_store_dwordx4 v203, v[222:225], s[44:45] offset:256
	s_waitcnt lgkmcnt(0)
	v_add_f32_e32 v241, v241, v213
	v_add_u32_e32 v203, 0x400, v202
	s_and_saveexec_b64 s[60:61], s[4:5]
	global_store_dword v203, v241, s[16:17]
	s_or_b64 exec, exec, s[60:61]
	v_add_u32_e32 v203, 0x80000, v200
	global_load_dwordx4 v[214:217], v203, s[36:37]
	global_load_dwordx4 v[218:221], v203, s[36:37] offset:64
	global_load_dwordx4 v[222:225], v203, s[36:37] offset:512
	global_load_dwordx4 v[226:229], v203, s[36:37] offset:576
	s_waitcnt vmcnt(18)
	v_fma_f32 v126, v126, v58, v230
	v_fma_f32 v127, v127, v59, v231
	v_fma_f32 v128, v128, v60, v232
	v_fma_f32 v129, v129, v61, v233
	v_fma_f32 v122, v122, v62, v234
	v_fma_f32 v123, v123, v63, v235
	v_fma_f32 v124, v124, v64, v236
	v_fma_f32 v125, v125, v65, v237
	v_fma_f32 v118, v118, v66, v242
	v_fma_f32 v119, v119, v67, v243
	v_fma_f32 v120, v120, v68, v244
	v_fma_f32 v121, v121, v69, v245
	v_fma_f32 v114, v114, v70, v204
	v_fma_f32 v115, v115, v71, v205
	v_fma_f32 v116, v116, v72, v206
	v_fma_f32 v117, v117, v73, v207
	v_mul_f32_e32 v241, v126, v126
	v_mul_f32_e32 v213, v127, v127
	v_fmac_f32_e32 v241, v128, v128
	v_fmac_f32_e32 v213, v129, v129
	v_fmac_f32_e32 v241, v122, v122
	v_fmac_f32_e32 v213, v123, v123
	v_fmac_f32_e32 v241, v124, v124
	v_fmac_f32_e32 v213, v125, v125
	v_fmac_f32_e32 v241, v118, v118
	v_fmac_f32_e32 v213, v119, v119
	v_fmac_f32_e32 v241, v120, v120
	v_fmac_f32_e32 v213, v121, v121
	v_fmac_f32_e32 v241, v114, v114
	v_fmac_f32_e32 v213, v115, v115
	v_fmac_f32_e32 v241, v116, v116
	v_fmac_f32_e32 v213, v117, v117
	v_add_f32_e32 v241, v241, v213
	ds_bpermute_b32 v213, v238, v241
	v_mul_f32_e32 v230, v126, v74
	v_mul_f32_e32 v231, v127, v75
	v_mul_f32_e32 v232, v128, v76
	v_mul_f32_e32 v233, v129, v77
	v_mul_f32_e32 v234, v122, v78
	v_mul_f32_e32 v235, v123, v79
	v_mul_f32_e32 v236, v124, v80
	v_mul_f32_e32 v237, v125, v81
	v_mul_f32_e32 v242, v118, v82
	v_mul_f32_e32 v243, v119, v83
	v_mul_f32_e32 v244, v120, v84
	v_mul_f32_e32 v245, v121, v85
	v_mul_f32_e32 v204, v114, v86
	v_mul_f32_e32 v205, v115, v87
	v_mul_f32_e32 v206, v116, v88
	v_mul_f32_e32 v207, v117, v89
	v_cvt_pk_bf16_f32 v126, v126, v127
	v_cvt_pk_bf16_f32 v127, v128, v129
	v_cvt_pk_bf16_f32 v128, v122, v123
	v_cvt_pk_bf16_f32 v129, v124, v125
	v_cvt_pk_bf16_f32 v118, v118, v119
	v_cvt_pk_bf16_f32 v119, v120, v121
	v_cvt_pk_bf16_f32 v120, v114, v115
	v_cvt_pk_bf16_f32 v121, v116, v117
	v_cvt_pk_bf16_f32 v230, v230, v231
	v_cvt_pk_bf16_f32 v231, v232, v233
	v_cvt_pk_bf16_f32 v232, v234, v235
	v_cvt_pk_bf16_f32 v233, v236, v237
	v_cvt_pk_bf16_f32 v242, v242, v243
	v_cvt_pk_bf16_f32 v243, v244, v245
	v_cvt_pk_bf16_f32 v244, v204, v205
	v_cvt_pk_bf16_f32 v245, v206, v207
	s_waitcnt lgkmcnt(0)
; __device__ __forceinline__ unsigned pk2(float lo, float hi) { return f2bf(lo) | (f2bf(hi) << 16); }
;     __device__ __forceinline__ void operator()(const pg8::f32x4 (&acc)[2][2][4][2], const pg8::Unit& u, int wr, int wc, int fr, int fq) const {
;     ...
; #pragma unroll
;         for (int ai = 0; ai < 2; ++ai)
; #pragma unroll
;             for (int mh = 0; mh < 4; mh += MB) {
;                 f32x4 xv[MB][2][2];
; #pragma unroll
;                 for (int mm = 0; mm < MB; ++mm) { const size_t row = (size_t)u.pm * 256 + ai * 128 + wr * 64 + (mh + mm) * 16 + fr;
; #pragma unroll
;                     for (int bj = 0; bj < 2; ++bj)
; #pragma unroll
;                         for (int n = 0; n < 2; ++n) xv[mm][bj][n] = *(const f32x4*)(x + row * D + col0 + bj * 128 + n * 16); }
; #pragma unroll
;                 for (int mm = 0; mm < MB; ++mm) { const int m = mh + mm;
;                     const size_t row = (size_t)u.pm * 256 + ai * 128 + wr * 64 + m * 16 + fr;
;                     float ss = 0.f;
; #pragma unroll
;                     for (int bj = 0; bj < 2; ++bj)
; #pragma unroll
;                         for (int n = 0; n < 2; ++n) { const size_t off = row * D + col0 + bj * 128 + n * 16;
;                             const f32x4 x1 = xv[mm][bj][n] + gt[bj][n] * acc[ai][bj][m][n];
;                             { v2u pb; pb.x = pk2(x1.x, x1.y); pb.y = pk2(x1.z, x1.w); *(v2u*)(x1b + off) = pb; } ss += (x1.x * x1.x + x1.y * x1.y) + (x1.z * x1.z + x1.w * x1.w);
;                             const f32x4 xa = x1 * al[bj][n]; v2u pk; pk.x = pk2(xa.x, xa.y); pk.y = pk2(xa.z, xa.w); *(v2u*)(x1a + off) = pk; }
;                     ss += __shfl_xor(ss, 16); ss += __shfl_xor(ss, 32);
;                     if (fq == 0) ssq[row * 16 + u.pn * 4 + wc] = ss;
;                 }
;             }
	v_add_f32_e32 v241, v241, v213
	ds_bpermute_b32 v213, v239, v241
	v_permlane16_swap_b32_e32 v126, v128
	v_permlane16_swap_b32_e32 v127, v129
	v_permlane16_swap_b32_e32 v118, v120
	v_permlane16_swap_b32_e32 v119, v121
	v_permlane16_swap_b32_e32 v230, v232
	v_permlane16_swap_b32_e32 v231, v233
	v_permlane16_swap_b32_e32 v242, v244
	v_permlane16_swap_b32_e32 v243, v245
	v_add_u32_e32 v203, 0x10000, v201
	global_store_dwordx4 v203, v[126:129], s[14:15]
	global_store_dwordx4 v203, v[118:121], s[14:15] offset:256
	global_store_dwordx4 v203, v[230:233], s[44:45]
	global_store_dwordx4 v203, v[242:245], s[44:45] offset:256
	s_waitcnt lgkmcnt(0)
	v_add_f32_e32 v241, v241, v213
	v_add_u32_e32 v203, 0x800, v202
	s_and_saveexec_b64 s[60:61], s[4:5]
	global_store_dword v203, v241, s[16:17]
	s_or_b64 exec, exec, s[60:61]
	v_add_u32_e32 v203, 0x90000, v200
	global_load_dwordx4 v[230:233], v203, s[36:37]
	global_load_dwordx4 v[234:237], v203, s[36:37] offset:64
	global_load_dwordx4 v[242:245], v203, s[36:37] offset:512
	global_load_dwordx4 v[204:207], v203, s[36:37] offset:576
	s_waitcnt vmcnt(18)
	v_fma_f32 v110, v110, v58, v162
	v_fma_f32 v111, v111, v59, v163
	v_fma_f32 v112, v112, v60, v164
	v_fma_f32 v113, v113, v61, v165
	v_fma_f32 v106, v106, v62, v166
	v_fma_f32 v107, v107, v63, v167
	v_fma_f32 v108, v108, v64, v168
	v_fma_f32 v109, v109, v65, v169
	v_fma_f32 v102, v102, v66, v170
	v_fma_f32 v103, v103, v67, v171
	v_fma_f32 v104, v104, v68, v172
	v_fma_f32 v105, v105, v69, v173
	v_fma_f32 v98, v98, v70, v174
	v_fma_f32 v99, v99, v71, v175
	v_fma_f32 v100, v100, v72, v176
	v_fma_f32 v101, v101, v73, v177
	v_mul_f32_e32 v241, v110, v110
	v_mul_f32_e32 v213, v111, v111
	v_fmac_f32_e32 v241, v112, v112
	v_fmac_f32_e32 v213, v113, v113
	v_fmac_f32_e32 v241, v106, v106
	v_fmac_f32_e32 v213, v107, v107
	v_fmac_f32_e32 v241, v108, v108
	v_fmac_f32_e32 v213, v109, v109
	v_fmac_f32_e32 v241, v102, v102
	v_fmac_f32_e32 v213, v103, v103
	v_fmac_f32_e32 v241, v104, v104
	v_fmac_f32_e32 v213, v105, v105
	v_fmac_f32_e32 v241, v98, v98
	v_fmac_f32_e32 v213, v99, v99
	v_fmac_f32_e32 v241, v100, v100
	v_fmac_f32_e32 v213, v101, v101
	v_add_f32_e32 v241, v241, v213
	ds_bpermute_b32 v213, v238, v241
	v_mul_f32_e32 v162, v110, v74
	v_mul_f32_e32 v163, v111, v75
	v_mul_f32_e32 v164, v112, v76
	v_mul_f32_e32 v165, v113, v77
	v_mul_f32_e32 v166, v106, v78
	v_mul_f32_e32 v167, v107, v79
	v_mul_f32_e32 v168, v108, v80
	v_mul_f32_e32 v169, v109, v81
	v_mul_f32_e32 v170, v102, v82
	v_mul_f32_e32 v171, v103, v83
	v_mul_f32_e32 v172, v104, v84
	v_mul_f32_e32 v173, v105, v85
	v_mul_f32_e32 v174, v98, v86
	v_mul_f32_e32 v175, v99, v87
	v_mul_f32_e32 v176, v100, v88
	v_mul_f32_e32 v177, v101, v89
	v_cvt_pk_bf16_f32 v110, v110, v111
	v_cvt_pk_bf16_f32 v111, v112, v113
	v_cvt_pk_bf16_f32 v112, v106, v107
	v_cvt_pk_bf16_f32 v113, v108, v109
	v_cvt_pk_bf16_f32 v102, v102, v103
	v_cvt_pk_bf16_f32 v103, v104, v105
	v_cvt_pk_bf16_f32 v104, v98, v99
	v_cvt_pk_bf16_f32 v105, v100, v101
	v_cvt_pk_bf16_f32 v162, v162, v163
	v_cvt_pk_bf16_f32 v163, v164, v165
	v_cvt_pk_bf16_f32 v164, v166, v167
	v_cvt_pk_bf16_f32 v165, v168, v169
	v_cvt_pk_bf16_f32 v170, v170, v171
	v_cvt_pk_bf16_f32 v171, v172, v173
	v_cvt_pk_bf16_f32 v172, v174, v175
	v_cvt_pk_bf16_f32 v173, v176, v177
	s_waitcnt lgkmcnt(0)
	v_add_f32_e32 v241, v241, v213
	ds_bpermute_b32 v213, v239, v241
	v_permlane16_swap_b32_e32 v110, v112
	v_permlane16_swap_b32_e32 v111, v113
	v_permlane16_swap_b32_e32 v102, v104
	v_permlane16_swap_b32_e32 v103, v105
	v_permlane16_swap_b32_e32 v162, v164
	v_permlane16_swap_b32_e32 v163, v165
	v_permlane16_swap_b32_e32 v170, v172
	v_permlane16_swap_b32_e32 v171, v173
	v_add_u32_e32 v203, 0x18000, v201
	global_store_dwordx4 v203, v[110:113], s[14:15]
	global_store_dwordx4 v203, v[102:105], s[14:15] offset:256
	global_store_dwordx4 v203, v[162:165], s[44:45]
	global_store_dwordx4 v203, v[170:173], s[44:45] offset:256
	s_waitcnt lgkmcnt(0)
	v_add_f32_e32 v241, v241, v213
	v_add_u32_e32 v203, 0xc00, v202
	s_and_saveexec_b64 s[60:61], s[4:5]
	global_store_dword v203, v241, s[16:17]
	s_or_b64 exec, exec, s[60:61]
	v_add_u32_e32 v203, 0xa0000, v200
	global_load_dwordx4 v[162:165], v203, s[36:37]
	global_load_dwordx4 v[166:169], v203, s[36:37] offset:64
	global_load_dwordx4 v[170:173], v203, s[36:37] offset:512
	global_load_dwordx4 v[174:177], v203, s[36:37] offset:576
	s_waitcnt vmcnt(18)
	v_fma_f32 v94, v94, v58, v214
	v_fma_f32 v95, v95, v59, v215
	v_fma_f32 v96, v96, v60, v216
	v_fma_f32 v97, v97, v61, v217
	v_fma_f32 v90, v90, v62, v218
	v_fma_f32 v91, v91, v63, v219
	v_fma_f32 v92, v92, v64, v220
	v_fma_f32 v93, v93, v65, v221
	v_fma_f32 v54, v54, v66, v222
	v_fma_f32 v55, v55, v67, v223
	v_fma_f32 v56, v56, v68, v224
	v_fma_f32 v57, v57, v69, v225
	v_fma_f32 v50, v50, v70, v226
	v_fma_f32 v51, v51, v71, v227
	v_fma_f32 v52, v52, v72, v228
	v_fma_f32 v53, v53, v73, v229
	v_mul_f32_e32 v241, v94, v94
	v_mul_f32_e32 v213, v95, v95
	v_fmac_f32_e32 v241, v96, v96
	v_fmac_f32_e32 v213, v97, v97
	v_fmac_f32_e32 v241, v90, v90
	v_fmac_f32_e32 v213, v91, v91
	v_fmac_f32_e32 v241, v92, v92
	v_fmac_f32_e32 v213, v93, v93
	v_fmac_f32_e32 v241, v54, v54
	v_fmac_f32_e32 v213, v55, v55
	v_fmac_f32_e32 v241, v56, v56
	v_fmac_f32_e32 v213, v57, v57
	v_fmac_f32_e32 v241, v50, v50
	v_fmac_f32_e32 v213, v51, v51
	v_fmac_f32_e32 v241, v52, v52
	v_fmac_f32_e32 v213, v53, v53
	v_add_f32_e32 v241, v241, v213
	ds_bpermute_b32 v213, v238, v241
	v_mul_f32_e32 v214, v94, v74
	v_mul_f32_e32 v215, v95, v75
	v_mul_f32_e32 v216, v96, v76
	v_mul_f32_e32 v217, v97, v77
	v_mul_f32_e32 v218, v90, v78
	v_mul_f32_e32 v219, v91, v79
	v_mul_f32_e32 v220, v92, v80
	v_mul_f32_e32 v221, v93, v81
	v_mul_f32_e32 v222, v54, v82
	v_mul_f32_e32 v223, v55, v83
	v_mul_f32_e32 v224, v56, v84
	v_mul_f32_e32 v225, v57, v85
	v_mul_f32_e32 v226, v50, v86
	v_mul_f32_e32 v227, v51, v87
	v_mul_f32_e32 v228, v52, v88
	v_mul_f32_e32 v229, v53, v89
	v_cvt_pk_bf16_f32 v94, v94, v95
	v_cvt_pk_bf16_f32 v95, v96, v97
	v_cvt_pk_bf16_f32 v96, v90, v91
	v_cvt_pk_bf16_f32 v97, v92, v93
	v_cvt_pk_bf16_f32 v54, v54, v55
	v_cvt_pk_bf16_f32 v55, v56, v57
	v_cvt_pk_bf16_f32 v56, v50, v51
	v_cvt_pk_bf16_f32 v57, v52, v53
	v_cvt_pk_bf16_f32 v214, v214, v215
	v_cvt_pk_bf16_f32 v215, v216, v217
	v_cvt_pk_bf16_f32 v216, v218, v219
	v_cvt_pk_bf16_f32 v217, v220, v221
	v_cvt_pk_bf16_f32 v222, v222, v223
	v_cvt_pk_bf16_f32 v223, v224, v225
	v_cvt_pk_bf16_f32 v224, v226, v227
	v_cvt_pk_bf16_f32 v225, v228, v229
	s_waitcnt lgkmcnt(0)
; __device__ __forceinline__ unsigned pk2(float lo, float hi) { return f2bf(lo) | (f2bf(hi) << 16); }
;     __device__ __forceinline__ void operator()(const pg8::f32x4 (&acc)[2][2][4][2], const pg8::Unit& u, int wr, int wc, int fr, int fq) const {
;     ...
; #pragma unroll
;         for (int ai = 0; ai < 2; ++ai)
; #pragma unroll
;             for (int mh = 0; mh < 4; mh += MB) {
;                 f32x4 xv[MB][2][2];
; #pragma unroll
;                 for (int mm = 0; mm < MB; ++mm) { const size_t row = (size_t)u.pm * 256 + ai * 128 + wr * 64 + (mh + mm) * 16 + fr;
; #pragma unroll
;                     for (int bj = 0; bj < 2; ++bj)
; #pragma unroll
;                         for (int n = 0; n < 2; ++n) xv[mm][bj][n] = *(const f32x4*)(x + row * D + col0 + bj * 128 + n * 16); }
; #pragma unroll
;                 for (int mm = 0; mm < MB; ++mm) { const int m = mh + mm;
;                     const size_t row = (size_t)u.pm * 256 + ai * 128 + wr * 64 + m * 16 + fr;
;                     float ss = 0.f;
; #pragma unroll
;                     for (int bj = 0; bj < 2; ++bj)
; #pragma unroll
;                         for (int n = 0; n < 2; ++n) { const size_t off = row * D + col0 + bj * 128 + n * 16;
;                             const f32x4 x1 = xv[mm][bj][n] + gt[bj][n] * acc[ai][bj][m][n];
;                             { v2u pb; pb.x = pk2(x1.x, x1.y); pb.y = pk2(x1.z, x1.w); *(v2u*)(x1b + off) = pb; } ss += (x1.x * x1.x + x1.y * x1.y) + (x1.z * x1.z + x1.w * x1.w);
;                             const f32x4 xa = x1 * al[bj][n]; v2u pk; pk.x = pk2(xa.x, xa.y); pk.y = pk2(xa.z, xa.w); *(v2u*)(x1a + off) = pk; }
;                     ss += __shfl_xor(ss, 16); ss += __shfl_xor(ss, 32);
;                     if (fq == 0) ssq[row * 16 + u.pn * 4 + wc] = ss;
;                 }
;             }
	v_add_f32_e32 v241, v241, v213
	ds_bpermute_b32 v213, v239, v241
	v_permlane16_swap_b32_e32 v94, v96
	v_permlane16_swap_b32_e32 v95, v97
	v_permlane16_swap_b32_e32 v54, v56
	v_permlane16_swap_b32_e32 v55, v57
	v_permlane16_swap_b32_e32 v214, v216
	v_permlane16_swap_b32_e32 v215, v217
	v_permlane16_swap_b32_e32 v222, v224
	v_permlane16_swap_b32_e32 v223, v225
	v_add_u32_e32 v203, 0x40000, v201
	global_store_dwordx4 v203, v[94:97], s[14:15]
	global_store_dwordx4 v203, v[54:57], s[14:15] offset:256
	global_store_dwordx4 v203, v[214:217], s[44:45]
	global_store_dwordx4 v203, v[222:225], s[44:45] offset:256
	s_waitcnt lgkmcnt(0)
	v_add_f32_e32 v241, v241, v213
	v_add_u32_e32 v203, 0x2000, v202
	s_and_saveexec_b64 s[60:61], s[4:5]
	global_store_dword v203, v241, s[16:17]
	s_or_b64 exec, exec, s[60:61]
	v_add_u32_e32 v203, 0xb0000, v200
	global_load_dwordx4 v[214:217], v203, s[36:37]
	global_load_dwordx4 v[218:221], v203, s[36:37] offset:64
	global_load_dwordx4 v[222:225], v203, s[36:37] offset:512
	global_load_dwordx4 v[226:229], v203, s[36:37] offset:576
	s_waitcnt vmcnt(18)
	v_fma_f32 v46, v46, v58, v230
	v_fma_f32 v47, v47, v59, v231
	v_fma_f32 v48, v48, v60, v232
	v_fma_f32 v49, v49, v61, v233
	v_fma_f32 v42, v42, v62, v234
	v_fma_f32 v43, v43, v63, v235
	v_fma_f32 v44, v44, v64, v236
	v_fma_f32 v45, v45, v65, v237
	v_fma_f32 v38, v38, v66, v242
	v_fma_f32 v39, v39, v67, v243
	v_fma_f32 v40, v40, v68, v244
	v_fma_f32 v41, v41, v69, v245
	v_fma_f32 v34, v34, v70, v204
	v_fma_f32 v35, v35, v71, v205
	v_fma_f32 v36, v36, v72, v206
	v_fma_f32 v37, v37, v73, v207
	v_mul_f32_e32 v241, v46, v46
	v_mul_f32_e32 v213, v47, v47
	v_fmac_f32_e32 v241, v48, v48
	v_fmac_f32_e32 v213, v49, v49
	v_fmac_f32_e32 v241, v42, v42
	v_fmac_f32_e32 v213, v43, v43
	v_fmac_f32_e32 v241, v44, v44
	v_fmac_f32_e32 v213, v45, v45
	v_fmac_f32_e32 v241, v38, v38
	v_fmac_f32_e32 v213, v39, v39
	v_fmac_f32_e32 v241, v40, v40
	v_fmac_f32_e32 v213, v41, v41
	v_fmac_f32_e32 v241, v34, v34
	v_fmac_f32_e32 v213, v35, v35
	v_fmac_f32_e32 v241, v36, v36
	v_fmac_f32_e32 v213, v37, v37
	v_add_f32_e32 v241, v241, v213
	ds_bpermute_b32 v213, v238, v241
	v_mul_f32_e32 v230, v46, v74
	v_mul_f32_e32 v231, v47, v75
	v_mul_f32_e32 v232, v48, v76
	v_mul_f32_e32 v233, v49, v77
	v_mul_f32_e32 v234, v42, v78
	v_mul_f32_e32 v235, v43, v79
	v_mul_f32_e32 v236, v44, v80
	v_mul_f32_e32 v237, v45, v81
	v_mul_f32_e32 v242, v38, v82
	v_mul_f32_e32 v243, v39, v83
	v_mul_f32_e32 v244, v40, v84
	v_mul_f32_e32 v245, v41, v85
	v_mul_f32_e32 v204, v34, v86
	v_mul_f32_e32 v205, v35, v87
	v_mul_f32_e32 v206, v36, v88
	v_mul_f32_e32 v207, v37, v89
	v_cvt_pk_bf16_f32 v46, v46, v47
	v_cvt_pk_bf16_f32 v47, v48, v49
	v_cvt_pk_bf16_f32 v48, v42, v43
	v_cvt_pk_bf16_f32 v49, v44, v45
	v_cvt_pk_bf16_f32 v38, v38, v39
	v_cvt_pk_bf16_f32 v39, v40, v41
	v_cvt_pk_bf16_f32 v40, v34, v35
	v_cvt_pk_bf16_f32 v41, v36, v37
	v_cvt_pk_bf16_f32 v230, v230, v231
	v_cvt_pk_bf16_f32 v231, v232, v233
	v_cvt_pk_bf16_f32 v232, v234, v235
	v_cvt_pk_bf16_f32 v233, v236, v237
	v_cvt_pk_bf16_f32 v242, v242, v243
	v_cvt_pk_bf16_f32 v243, v244, v245
	v_cvt_pk_bf16_f32 v244, v204, v205
	v_cvt_pk_bf16_f32 v245, v206, v207
	s_waitcnt lgkmcnt(0)
	v_add_f32_e32 v241, v241, v213
	ds_bpermute_b32 v213, v239, v241
	v_permlane16_swap_b32_e32 v46, v48
	v_permlane16_swap_b32_e32 v47, v49
	v_permlane16_swap_b32_e32 v38, v40
	v_permlane16_swap_b32_e32 v39, v41
	v_permlane16_swap_b32_e32 v230, v232
	v_permlane16_swap_b32_e32 v231, v233
	v_permlane16_swap_b32_e32 v242, v244
	v_permlane16_swap_b32_e32 v243, v245
	v_add_u32_e32 v203, 0x48000, v201
	global_store_dwordx4 v203, v[46:49], s[14:15]
	global_store_dwordx4 v203, v[38:41], s[14:15] offset:256
	global_store_dwordx4 v203, v[230:233], s[44:45]
	global_store_dwordx4 v203, v[242:245], s[44:45] offset:256
	s_waitcnt lgkmcnt(0)
	v_add_f32_e32 v241, v241, v213
	v_add_u32_e32 v203, 0x2400, v202
	s_and_saveexec_b64 s[60:61], s[4:5]
	global_store_dword v203, v241, s[16:17]
	s_or_b64 exec, exec, s[60:61]
	s_waitcnt vmcnt(14)
; __device__ __forceinline__ unsigned pk2(float lo, float hi) { return f2bf(lo) | (f2bf(hi) << 16); }
;     __device__ __forceinline__ void operator()(const pg8::f32x4 (&acc)[2][2][4][2], const pg8::Unit& u, int wr, int wc, int fr, int fq) const {
;     ...
; #pragma unroll
;         for (int ai = 0; ai < 2; ++ai)
; #pragma unroll
;             for (int mh = 0; mh < 4; mh += MB) {
;                 f32x4 xv[MB][2][2];
; #pragma unroll
;                 for (int mm = 0; mm < MB; ++mm) { const size_t row = (size_t)u.pm * 256 + ai * 128 + wr * 64 + (mh + mm) * 16 + fr;
; #pragma unroll
;                     for (int bj = 0; bj < 2; ++bj)
; #pragma unroll
;                         for (int n = 0; n < 2; ++n) xv[mm][bj][n] = *(const f32x4*)(x + row * D + col0 + bj * 128 + n * 16); }
; #pragma unroll
;                 for (int mm = 0; mm < MB; ++mm) { const int m = mh + mm;
;                     const size_t row = (size_t)u.pm * 256 + ai * 128 + wr * 64 + m * 16 + fr;
;                     float ss = 0.f;
; #pragma unroll
;                     for (int bj = 0; bj < 2; ++bj)
; #pragma unroll
;                         for (int n = 0; n < 2; ++n) { const size_t off = row * D + col0 + bj * 128 + n * 16;
;                             const f32x4 x1 = xv[mm][bj][n] + gt[bj][n] * acc[ai][bj][m][n];
;                             { v2u pb; pb.x = pk2(x1.x, x1.y); pb.y = pk2(x1.z, x1.w); *(v2u*)(x1b + off) = pb; } ss += (x1.x * x1.x + x1.y * x1.y) + (x1.z * x1.z + x1.w * x1.w);
;                             const f32x4 xa = x1 * al[bj][n]; v2u pk; pk.x = pk2(xa.x, xa.y); pk.y = pk2(xa.z, xa.w); *(v2u*)(x1a + off) = pk; }
;                     ss += __shfl_xor(ss, 16); ss += __shfl_xor(ss, 32);
;                     if (fq == 0) ssq[row * 16 + u.pn * 4 + wc] = ss;
;                 }
;             }
	v_fma_f32 v30, v30, v58, v162
	v_fma_f32 v31, v31, v59, v163
	v_fma_f32 v32, v32, v60, v164
	v_fma_f32 v33, v33, v61, v165
	v_fma_f32 v26, v26, v62, v166
	v_fma_f32 v27, v27, v63, v167
	v_fma_f32 v28, v28, v64, v168
	v_fma_f32 v29, v29, v65, v169
	v_fma_f32 v22, v22, v66, v170
	v_fma_f32 v23, v23, v67, v171
	v_fma_f32 v24, v24, v68, v172
	v_fma_f32 v25, v25, v69, v173
	v_fma_f32 v18, v18, v70, v174
	v_fma_f32 v19, v19, v71, v175
	v_fma_f32 v20, v20, v72, v176
	v_fma_f32 v21, v21, v73, v177
	v_mul_f32_e32 v241, v30, v30
	v_mul_f32_e32 v213, v31, v31
	v_fmac_f32_e32 v241, v32, v32
	v_fmac_f32_e32 v213, v33, v33
	v_fmac_f32_e32 v241, v26, v26
	v_fmac_f32_e32 v213, v27, v27
	v_fmac_f32_e32 v241, v28, v28
	v_fmac_f32_e32 v213, v29, v29
	v_fmac_f32_e32 v241, v22, v22
	v_fmac_f32_e32 v213, v23, v23
	v_fmac_f32_e32 v241, v24, v24
	v_fmac_f32_e32 v213, v25, v25
	v_fmac_f32_e32 v241, v18, v18
	v_fmac_f32_e32 v213, v19, v19
	v_fmac_f32_e32 v241, v20, v20
	v_fmac_f32_e32 v213, v21, v21
	v_add_f32_e32 v241, v241, v213
	ds_bpermute_b32 v213, v238, v241
	v_mul_f32_e32 v162, v30, v74
	v_mul_f32_e32 v163, v31, v75
	v_mul_f32_e32 v164, v32, v76
	v_mul_f32_e32 v165, v33, v77
	v_mul_f32_e32 v166, v26, v78
	v_mul_f32_e32 v167, v27, v79
	v_mul_f32_e32 v168, v28, v80
	v_mul_f32_e32 v169, v29, v81
	v_mul_f32_e32 v170, v22, v82
	v_mul_f32_e32 v171, v23, v83
	v_mul_f32_e32 v172, v24, v84
	v_mul_f32_e32 v173, v25, v85
	v_mul_f32_e32 v174, v18, v86
	v_mul_f32_e32 v175, v19, v87
	v_mul_f32_e32 v176, v20, v88
	v_mul_f32_e32 v177, v21, v89
	v_cvt_pk_bf16_f32 v30, v30, v31
	v_cvt_pk_bf16_f32 v31, v32, v33
	v_cvt_pk_bf16_f32 v32, v26, v27
	v_cvt_pk_bf16_f32 v33, v28, v29
	v_cvt_pk_bf16_f32 v22, v22, v23
	v_cvt_pk_bf16_f32 v23, v24, v25
	v_cvt_pk_bf16_f32 v24, v18, v19
	v_cvt_pk_bf16_f32 v25, v20, v21
	v_cvt_pk_bf16_f32 v162, v162, v163
	v_cvt_pk_bf16_f32 v163, v164, v165
	v_cvt_pk_bf16_f32 v164, v166, v167
	v_cvt_pk_bf16_f32 v165, v168, v169
	v_cvt_pk_bf16_f32 v170, v170, v171
	v_cvt_pk_bf16_f32 v171, v172, v173
	v_cvt_pk_bf16_f32 v172, v174, v175
	v_cvt_pk_bf16_f32 v173, v176, v177
	s_waitcnt lgkmcnt(0)
	v_add_f32_e32 v241, v241, v213
	ds_bpermute_b32 v213, v239, v241
	v_permlane16_swap_b32_e32 v30, v32
	v_permlane16_swap_b32_e32 v31, v33
	v_permlane16_swap_b32_e32 v22, v24
	v_permlane16_swap_b32_e32 v23, v25
	v_permlane16_swap_b32_e32 v162, v164
	v_permlane16_swap_b32_e32 v163, v165
	v_permlane16_swap_b32_e32 v170, v172
	v_permlane16_swap_b32_e32 v171, v173
	v_add_u32_e32 v203, 0x50000, v201
	global_store_dwordx4 v203, v[30:33], s[14:15]
	global_store_dwordx4 v203, v[22:25], s[14:15] offset:256
	global_store_dwordx4 v203, v[162:165], s[44:45]
	global_store_dwordx4 v203, v[170:173], s[44:45] offset:256
	s_waitcnt lgkmcnt(0)
	v_add_f32_e32 v241, v241, v213
	v_add_u32_e32 v203, 0x2800, v202
	s_and_saveexec_b64 s[60:61], s[4:5]
	global_store_dword v203, v241, s[16:17]
	s_or_b64 exec, exec, s[60:61]
	s_waitcnt vmcnt(10)
	v_fma_f32 v14, v14, v58, v214
	v_fma_f32 v15, v15, v59, v215
	v_fma_f32 v16, v16, v60, v216
	v_fma_f32 v17, v17, v61, v217
	v_fma_f32 v10, v10, v62, v218
	v_fma_f32 v11, v11, v63, v219
	v_fma_f32 v12, v12, v64, v220
	v_fma_f32 v13, v13, v65, v221
	v_fma_f32 v6, v6, v66, v222
	v_fma_f32 v7, v7, v67, v223
	v_fma_f32 v8, v8, v68, v224
	v_fma_f32 v9, v9, v69, v225
	v_fma_f32 v2, v2, v70, v226
	v_fma_f32 v3, v3, v71, v227
	v_fma_f32 v4, v4, v72, v228
	v_fma_f32 v5, v5, v73, v229
	v_mul_f32_e32 v241, v14, v14
	v_mul_f32_e32 v213, v15, v15
	v_fmac_f32_e32 v241, v16, v16
	v_fmac_f32_e32 v213, v17, v17
	v_fmac_f32_e32 v241, v10, v10
	v_fmac_f32_e32 v213, v11, v11
	v_fmac_f32_e32 v241, v12, v12
	v_fmac_f32_e32 v213, v13, v13
	v_fmac_f32_e32 v241, v6, v6
	v_fmac_f32_e32 v213, v7, v7
	v_fmac_f32_e32 v241, v8, v8
	v_fmac_f32_e32 v213, v9, v9
	v_fmac_f32_e32 v241, v2, v2
	v_fmac_f32_e32 v213, v3, v3
	v_fmac_f32_e32 v241, v4, v4
	v_fmac_f32_e32 v213, v5, v5
	v_add_f32_e32 v241, v241, v213
	ds_bpermute_b32 v213, v238, v241
	v_mul_f32_e32 v214, v14, v74
	v_mul_f32_e32 v215, v15, v75
	v_mul_f32_e32 v216, v16, v76
	v_mul_f32_e32 v217, v17, v77
	v_mul_f32_e32 v218, v10, v78
	v_mul_f32_e32 v219, v11, v79
	v_mul_f32_e32 v220, v12, v80
	v_mul_f32_e32 v221, v13, v81
	v_mul_f32_e32 v222, v6, v82
	v_mul_f32_e32 v223, v7, v83
	v_mul_f32_e32 v224, v8, v84
	v_mul_f32_e32 v225, v9, v85
	v_mul_f32_e32 v226, v2, v86
	v_mul_f32_e32 v227, v3, v87
	v_mul_f32_e32 v228, v4, v88
	v_mul_f32_e32 v229, v5, v89
	v_cvt_pk_bf16_f32 v14, v14, v15
	v_cvt_pk_bf16_f32 v15, v16, v17
	v_cvt_pk_bf16_f32 v16, v10, v11
	v_cvt_pk_bf16_f32 v17, v12, v13
	v_cvt_pk_bf16_f32 v6, v6, v7
	v_cvt_pk_bf16_f32 v7, v8, v9
	v_cvt_pk_bf16_f32 v8, v2, v3
	v_cvt_pk_bf16_f32 v9, v4, v5
	v_cvt_pk_bf16_f32 v214, v214, v215
	v_cvt_pk_bf16_f32 v215, v216, v217
	v_cvt_pk_bf16_f32 v216, v218, v219
	v_cvt_pk_bf16_f32 v217, v220, v221
	v_cvt_pk_bf16_f32 v222, v222, v223
	v_cvt_pk_bf16_f32 v223, v224, v225
	v_cvt_pk_bf16_f32 v224, v226, v227
	v_cvt_pk_bf16_f32 v225, v228, v229
	s_waitcnt lgkmcnt(0)
	v_add_f32_e32 v241, v241, v213
	ds_bpermute_b32 v213, v239, v241
	v_permlane16_swap_b32_e32 v14, v16
	v_permlane16_swap_b32_e32 v15, v17
	v_permlane16_swap_b32_e32 v6, v8
	v_permlane16_swap_b32_e32 v7, v9
	v_permlane16_swap_b32_e32 v214, v216
	v_permlane16_swap_b32_e32 v215, v217
	v_permlane16_swap_b32_e32 v222, v224
	v_permlane16_swap_b32_e32 v223, v225
	v_add_u32_e32 v203, 0x58000, v201
	global_store_dwordx4 v203, v[14:17], s[14:15]
	global_store_dwordx4 v203, v[6:9], s[14:15] offset:256
	global_store_dwordx4 v203, v[214:217], s[44:45]
	global_store_dwordx4 v203, v[222:225], s[44:45] offset:256
	s_waitcnt lgkmcnt(0)
	v_add_f32_e32 v241, v241, v213
	v_add_u32_e32 v203, 0x2c00, v202
	s_and_saveexec_b64 s[60:61], s[4:5]
	global_store_dword v203, v241, s[16:17]
	s_or_b64 exec, exec, s[60:61]
	s_mov_b64 s[60:61], exec
